# v19
# speedup vs baseline: 1.0495x; 1.0034x over previous
; template <class Epi, class Sched>
; __device__ __forceinline__ void gemm_simple(PG8_LAS unsigned char* lds, const Gemm g, const Sched& S, const Epi& E, int wave_s) {
;     ...
; #pragma unroll
;         for (int a = 0; a < 2; ++a)
; #pragma unroll
;             for (int b = 0; b < 2; ++b)
; #pragma unroll
;                 for (int m = 0; m < 4; ++m)
; #pragma unroll
;                     for (int n = 0; n < 2; ++n) acc[a][b][m][n] = (f32x4){zero_o, zero_o, zero_o, zero_o};
.LBB0_60:
	s_waitcnt lgkmcnt(0)
	s_cmp_lg_u32 s53, 0
	s_cbranch_scc1 .Lacc0_skip_63
	v_mov_b64_e32 v[6:7], v[2:3]
	v_mov_b64_e32 v[10:11], v[2:3]
	v_mov_b64_e32 v[22:23], v[2:3]
	v_mov_b64_e32 v[26:27], v[2:3]
	v_mov_b64_e32 v[38:39], v[2:3]
	v_mov_b64_e32 v[42:43], v[2:3]
	v_mov_b64_e32 v[54:55], v[2:3]
	v_mov_b64_e32 v[58:59], v[2:3]
	v_mov_b64_e32 v[14:15], v[2:3]
	v_mov_b64_e32 v[18:19], v[2:3]
	v_mov_b64_e32 v[30:31], v[2:3]
	v_mov_b64_e32 v[34:35], v[2:3]
	v_mov_b64_e32 v[46:47], v[2:3]
	v_mov_b64_e32 v[50:51], v[2:3]
	v_mov_b64_e32 v[62:63], v[2:3]
	v_mov_b64_e32 v[66:67], v[2:3]
	v_mov_b64_e32 v[70:71], v[2:3]
	v_mov_b64_e32 v[74:75], v[2:3]
	v_mov_b64_e32 v[86:87], v[2:3]
	v_mov_b64_e32 v[90:91], v[2:3]
	v_mov_b64_e32 v[102:103], v[2:3]
	v_mov_b64_e32 v[106:107], v[2:3]
	v_mov_b64_e32 v[118:119], v[2:3]
	v_mov_b64_e32 v[122:123], v[2:3]
	v_mov_b64_e32 v[78:79], v[2:3]
	v_mov_b64_e32 v[82:83], v[2:3]
	v_mov_b64_e32 v[94:95], v[2:3]
	v_mov_b64_e32 v[98:99], v[2:3]
	v_mov_b64_e32 v[110:111], v[2:3]
	v_mov_b64_e32 v[114:115], v[2:3]
	v_mov_b64_e32 v[126:127], v[2:3]
	v_mov_b64_e32 v[130:131], v[2:3]
	v_mov_b64_e32 v[4:5], v[0:1]
	v_mov_b64_e32 v[8:9], v[0:1]
	v_mov_b64_e32 v[20:21], v[0:1]
	v_mov_b64_e32 v[24:25], v[0:1]
	v_mov_b64_e32 v[36:37], v[0:1]
	v_mov_b64_e32 v[40:41], v[0:1]
	v_mov_b64_e32 v[52:53], v[0:1]
	v_mov_b64_e32 v[56:57], v[0:1]
	v_mov_b64_e32 v[12:13], v[0:1]
	v_mov_b64_e32 v[16:17], v[0:1]
	v_mov_b64_e32 v[28:29], v[0:1]
	v_mov_b64_e32 v[32:33], v[0:1]
	v_mov_b64_e32 v[44:45], v[0:1]
	v_mov_b64_e32 v[48:49], v[0:1]
	v_mov_b64_e32 v[60:61], v[0:1]
	v_mov_b64_e32 v[64:65], v[0:1]
	v_mov_b64_e32 v[68:69], v[0:1]
	v_mov_b64_e32 v[72:73], v[0:1]
	v_mov_b64_e32 v[84:85], v[0:1]
	v_mov_b64_e32 v[88:89], v[0:1]
	v_mov_b64_e32 v[100:101], v[0:1]
	v_mov_b64_e32 v[104:105], v[0:1]
	v_mov_b64_e32 v[116:117], v[0:1]
	v_mov_b64_e32 v[120:121], v[0:1]
	v_mov_b64_e32 v[76:77], v[0:1]
	v_mov_b64_e32 v[80:81], v[0:1]
	v_mov_b64_e32 v[92:93], v[0:1]
	v_mov_b64_e32 v[96:97], v[0:1]
	v_mov_b64_e32 v[108:109], v[0:1]
	v_mov_b64_e32 v[112:113], v[0:1]
	v_mov_b64_e32 v[124:125], v[0:1]
	v_mov_b64_e32 v[128:129], v[0:1]
.Lacc0_skip_63:
	s_mov_b32 s10, 0
	s_cmp_eq_u32 s53, 0
	v_add_u32_e32 v132, 0x10000, v153
	v_add_u32_e32 v133, 0x14000, v153
	v_add_u32_e32 v134, 0x18000, v153
	v_add_u32_e32 v135, 0x1c000, v153
	s_cbranch_scc1 .LBB0_62
	s_waitcnt vmcnt(18) lgkmcnt(0)
	s_barrier
	ds_read_b128 v[4:7], v132
	ds_read_b128 v[44:47], v154 offset:6144
	ds_read_b128 v[20:23], v154
	ds_read_b128 v[12:15], v132 offset:2048
	ds_read_b128 v[28:31], v154 offset:2048
	s_add_u32 s10, s16, 0x80
	s_addc_u32 s11, s17, 0
	s_mov_b32 m0, s39
	s_nop 0
	global_load_lds_dwordx4 v139, s[10:11]
	s_mov_b32 m0, s43
	s_nop 0
	global_load_lds_dwordx4 v152, s[10:11]
	s_waitcnt lgkmcnt(3)
	v_mfma_f32_16x16x32_bf16 v[92:95], v[4:7], v[44:47], v[0:3]
	ds_read_b128 v[36:39], v154 offset:4096
	s_waitcnt lgkmcnt(3)
	v_mfma_f32_16x16x32_bf16 v[68:71], v[4:7], v[20:23], v[0:3]
	s_waitcnt lgkmcnt(2)
	v_mfma_f32_16x16x32_bf16 v[72:75], v[12:15], v[20:23], v[0:3]
	ds_read_b128 v[8:11], v132 offset:1024
	ds_read_b128 v[48:51], v154 offset:7168
	s_waitcnt lgkmcnt(3)
	v_mfma_f32_16x16x32_bf16 v[76:79], v[4:7], v[28:31], v[0:3]
	v_mfma_f32_16x16x32_bf16 v[80:83], v[12:15], v[28:31], v[0:3]
	ds_read_b128 v[24:27], v154 offset:1024
	s_waitcnt lgkmcnt(3)
	v_mfma_f32_16x16x32_bf16 v[84:87], v[4:7], v[36:39], v[0:3]
	ds_read_b128 v[16:19], v132 offset:3072
	v_mfma_f32_16x16x32_bf16 v[88:91], v[12:15], v[36:39], v[0:3]
	ds_read_b128 v[32:35], v154 offset:3072
	s_waitcnt lgkmcnt(3)
	v_mfma_f32_16x16x32_bf16 v[100:103], v[8:11], v[48:51], v[92:95]
	v_mfma_f32_16x16x32_bf16 v[92:95], v[12:15], v[44:47], v[0:3]
	ds_read_b128 v[40:43], v154 offset:5120
	s_waitcnt lgkmcnt(3)
	v_mfma_f32_16x16x32_bf16 v[68:71], v[8:11], v[24:27], v[68:71]
	s_waitcnt lgkmcnt(2)
	v_mfma_f32_16x16x32_bf16 v[72:75], v[16:19], v[24:27], v[72:75]
	s_waitcnt lgkmcnt(1)
	v_mfma_f32_16x16x32_bf16 v[76:79], v[8:11], v[32:35], v[76:79]
	ds_read_b128 v[52:55], v133
	v_mfma_f32_16x16x32_bf16 v[80:83], v[16:19], v[32:35], v[80:83]
	ds_read_b128 v[60:63], v133 offset:2048
	s_waitcnt lgkmcnt(2)
	v_mfma_f32_16x16x32_bf16 v[84:87], v[8:11], v[40:43], v[84:87]
	ds_read_b128 v[56:59], v133 offset:1024
	v_mfma_f32_16x16x32_bf16 v[88:91], v[16:19], v[40:43], v[88:91]
	ds_read_b128 v[64:67], v133 offset:3072
	v_mfma_f32_16x16x32_bf16 v[104:107], v[16:19], v[48:51], v[92:95]
	s_add_u32 s10, s18, 0x80
	s_addc_u32 s11, s19, 0
	s_mov_b32 m0, s40
	s_nop 0
	global_load_lds_dwordx4 v138, s[10:11]
	s_mov_b32 m0, s44
	s_nop 0
	global_load_lds_dwordx4 v140, s[10:11]
	s_waitcnt lgkmcnt(3)
	v_mfma_f32_16x16x32_bf16 v[92:95], v[52:55], v[20:23], v[0:3]
	s_waitcnt lgkmcnt(2)
	v_mfma_f32_16x16x32_bf16 v[20:23], v[60:63], v[20:23], v[0:3]
	s_waitcnt lgkmcnt(1)
	v_mfma_f32_16x16x32_bf16 v[116:119], v[56:59], v[24:27], v[92:95]
	s_waitcnt lgkmcnt(0)
	v_mfma_f32_16x16x32_bf16 v[20:23], v[64:67], v[24:27], v[20:23]
	v_mfma_f32_16x16x32_bf16 v[24:27], v[52:55], v[28:31], v[0:3]
	v_mfma_f32_16x16x32_bf16 v[28:31], v[60:63], v[28:31], v[0:3]
	v_mfma_f32_16x16x32_bf16 v[24:27], v[56:59], v[32:35], v[24:27]
	v_mfma_f32_16x16x32_bf16 v[28:31], v[64:67], v[32:35], v[28:31]
	v_mfma_f32_16x16x32_bf16 v[32:35], v[52:55], v[36:39], v[0:3]
	v_mfma_f32_16x16x32_bf16 v[36:39], v[60:63], v[36:39], v[0:3]
	v_mfma_f32_16x16x32_bf16 v[32:35], v[56:59], v[40:43], v[32:35]
	v_mfma_f32_16x16x32_bf16 v[36:39], v[64:67], v[40:43], v[36:39]
	v_mfma_f32_16x16x32_bf16 v[40:43], v[52:55], v[44:47], v[0:3]
	v_mfma_f32_16x16x32_bf16 v[44:47], v[60:63], v[44:47], v[0:3]
	v_mfma_f32_16x16x32_bf16 v[40:43], v[56:59], v[48:51], v[40:43]
	v_mfma_f32_16x16x32_bf16 v[44:47], v[64:67], v[48:51], v[44:47]
	s_waitcnt vmcnt(20) lgkmcnt(0)
	s_barrier
; template <class Epi, class Sched>
; __device__ __forceinline__ void gemm_simple(PG8_LAS unsigned char* lds, const Gemm g, const Sched& S, const Epi& E, int wave_s) {
;     ...
;             PG8_TILE_W(1, cA + 2 * kstep, cB + 2 * kstep, "2", "4");
	ds_read_b128 v[48:51], v154 offset:16384
	ds_read_b128 v[96:99], v154 offset:18432
	ds_read_b128 v[112:115], v154 offset:20480
	ds_read_b128 v[124:127], v154 offset:22528
	ds_read_b128 v[92:95], v154 offset:17408
	s_add_u32 s10, s16, 0x160080
	s_addc_u32 s11, s17, 0
	s_mov_b32 m0, s41
	s_nop 0
	global_load_lds_dwordx4 v139, s[10:11]
	s_mov_b32 m0, s45
	s_nop 0
	global_load_lds_dwordx4 v152, s[10:11]
	s_waitcnt lgkmcnt(4)
	v_mfma_f32_16x16x32_bf16 v[142:145], v[4:7], v[48:51], v[0:3]
	ds_read_b128 v[108:111], v154 offset:19456
	s_waitcnt lgkmcnt(4)
	v_mfma_f32_16x16x32_bf16 v[156:159], v[4:7], v[96:99], v[0:3]
	ds_read_b128 v[120:123], v154 offset:21504
	s_waitcnt lgkmcnt(4)
	v_mfma_f32_16x16x32_bf16 v[170:173], v[4:7], v[112:115], v[0:3]
	ds_read_b128 v[128:131], v154 offset:23552
	s_waitcnt lgkmcnt(4)
	v_mfma_f32_16x16x32_bf16 v[4:7], v[4:7], v[124:127], v[0:3]
	s_waitcnt lgkmcnt(3)
	v_mfma_f32_16x16x32_bf16 v[142:145], v[8:11], v[92:95], v[142:145]
	s_waitcnt lgkmcnt(2)
	v_mfma_f32_16x16x32_bf16 v[156:159], v[8:11], v[108:111], v[156:159]
	s_waitcnt lgkmcnt(1)
	v_mfma_f32_16x16x32_bf16 v[170:173], v[8:11], v[120:123], v[170:173]
	s_waitcnt lgkmcnt(0)
	v_mfma_f32_16x16x32_bf16 v[4:7], v[8:11], v[128:131], v[4:7]
	v_mfma_f32_16x16x32_bf16 v[8:11], v[12:15], v[124:127], v[0:3]
	v_mfma_f32_16x16x32_bf16 v[146:149], v[12:15], v[48:51], v[0:3]
	v_mfma_f32_16x16x32_bf16 v[160:163], v[12:15], v[96:99], v[0:3]
	v_mfma_f32_16x16x32_bf16 v[174:177], v[12:15], v[112:115], v[0:3]
	v_mfma_f32_16x16x32_bf16 v[8:11], v[16:19], v[128:131], v[8:11]
	v_mfma_f32_16x16x32_bf16 v[146:149], v[16:19], v[92:95], v[146:149]
	v_mfma_f32_16x16x32_bf16 v[160:163], v[16:19], v[108:111], v[160:163]
	v_mfma_f32_16x16x32_bf16 v[174:177], v[16:19], v[120:123], v[174:177]
	s_add_u32 s10, s18, 0x160080
	s_addc_u32 s11, s19, 0
	s_mov_b32 m0, s42
	s_nop 0
	global_load_lds_dwordx4 v138, s[10:11]
	s_mov_b32 m0, s46
	s_nop 0
	global_load_lds_dwordx4 v140, s[10:11]
	v_mfma_f32_16x16x32_bf16 v[12:15], v[52:55], v[48:51], v[0:3]
	v_mfma_f32_16x16x32_bf16 v[178:181], v[56:59], v[92:95], v[12:15]
	v_mfma_f32_16x16x32_bf16 v[12:15], v[60:63], v[48:51], v[0:3]
	v_mfma_f32_16x16x32_bf16 v[182:185], v[64:67], v[92:95], v[12:15]
	v_mfma_f32_16x16x32_bf16 v[12:15], v[52:55], v[96:99], v[0:3]
	v_mfma_f32_16x16x32_bf16 v[186:189], v[56:59], v[108:111], v[12:15]
	v_mfma_f32_16x16x32_bf16 v[12:15], v[60:63], v[96:99], v[0:3]
	v_mfma_f32_16x16x32_bf16 v[190:193], v[64:67], v[108:111], v[12:15]
	v_mfma_f32_16x16x32_bf16 v[12:15], v[52:55], v[112:115], v[0:3]
	v_mfma_f32_16x16x32_bf16 v[194:197], v[56:59], v[120:123], v[12:15]
	v_mfma_f32_16x16x32_bf16 v[12:15], v[60:63], v[112:115], v[0:3]
	v_mfma_f32_16x16x32_bf16 v[198:201], v[64:67], v[120:123], v[12:15]
	v_mfma_f32_16x16x32_bf16 v[12:15], v[52:55], v[124:127], v[0:3]
	v_mfma_f32_16x16x32_bf16 v[202:205], v[56:59], v[128:131], v[12:15]
	v_mfma_f32_16x16x32_bf16 v[12:15], v[60:63], v[124:127], v[0:3]
	v_mfma_f32_16x16x32_bf16 v[206:209], v[64:67], v[128:131], v[12:15]
	s_waitcnt vmcnt(2) lgkmcnt(0)
	s_barrier
; template <class Epi, class Sched>
; __device__ __forceinline__ void gemm_simple(PG8_LAS unsigned char* lds, const Gemm g, const Sched& S, const Epi& E, int wave_s) {
;     ...
;             PG8_TILE_W(1, cA + 2 * kstep, cB + 2 * kstep, "2", "4");
	s_nop 5
	ds_read_b128 v[12:15], v134
	ds_read_b128 v[48:51], v154 offset:32768
	ds_read_b128 v[16:19], v134 offset:1024
	ds_read_b128 v[60:63], v154 offset:33792
	ds_read_b128 v[52:55], v134 offset:2048
	ds_read_b128 v[56:59], v134 offset:3072
	ds_read_b128 v[64:67], v154 offset:34816
	s_add_u32 s10, s16, 0x100
	s_addc_u32 s11, s17, 0
	s_mov_b32 m0, s26
	s_nop 0
	global_load_lds_dwordx4 v139, s[10:11]
	s_mov_b32 m0, s27
	s_nop 0
	global_load_lds_dwordx4 v152, s[10:11]
	s_waitcnt lgkmcnt(5)
	v_mfma_f32_16x16x32_bf16 v[68:71], v[12:15], v[48:51], v[68:71]
	ds_read_b128 v[210:213], v154 offset:35840
	s_waitcnt lgkmcnt(4)
	v_mfma_f32_16x16x32_bf16 v[128:131], v[16:19], v[60:63], v[68:71]
	s_waitcnt lgkmcnt(3)
	v_mfma_f32_16x16x32_bf16 v[68:71], v[52:55], v[48:51], v[72:75]
	s_waitcnt lgkmcnt(2)
	v_mfma_f32_16x16x32_bf16 v[124:127], v[56:59], v[60:63], v[68:71]
	ds_read_b128 v[214:217], v154 offset:36864
	s_waitcnt lgkmcnt(2)
	v_mfma_f32_16x16x32_bf16 v[68:71], v[12:15], v[64:67], v[76:79]
	ds_read_b128 v[218:221], v154 offset:37888
	s_waitcnt lgkmcnt(2)
	v_mfma_f32_16x16x32_bf16 v[112:115], v[16:19], v[210:213], v[68:71]
	v_mfma_f32_16x16x32_bf16 v[68:71], v[52:55], v[64:67], v[80:83]
	v_mfma_f32_16x16x32_bf16 v[108:111], v[56:59], v[210:213], v[68:71]
	ds_read_b128 v[222:225], v154 offset:38912
	s_waitcnt lgkmcnt(2)
	v_mfma_f32_16x16x32_bf16 v[68:71], v[12:15], v[214:217], v[84:87]
	ds_read_b128 v[226:229], v154 offset:39936
	s_waitcnt lgkmcnt(2)
	v_mfma_f32_16x16x32_bf16 v[96:99], v[16:19], v[218:221], v[68:71]
	v_mfma_f32_16x16x32_bf16 v[68:71], v[52:55], v[214:217], v[88:91]
	v_mfma_f32_16x16x32_bf16 v[92:95], v[56:59], v[218:221], v[68:71]
	ds_read_b128 v[238:241], v135 offset:2048
	s_waitcnt lgkmcnt(2)
	v_mfma_f32_16x16x32_bf16 v[68:71], v[12:15], v[222:225], v[100:103]
	ds_read_b128 v[230:233], v135
	s_waitcnt lgkmcnt(2)
	v_mfma_f32_16x16x32_bf16 v[80:83], v[16:19], v[226:229], v[68:71]
	ds_read_b128 v[242:245], v135 offset:3072
	v_mfma_f32_16x16x32_bf16 v[68:71], v[52:55], v[222:225], v[104:107]
	v_mfma_f32_16x16x32_bf16 v[76:79], v[56:59], v[226:229], v[68:71]
	s_add_u32 s10, s18, 0x100
	s_addc_u32 s11, s19, 0
	s_mov_b32 m0, s25
	s_nop 0
	global_load_lds_dwordx4 v138, s[10:11]
	s_mov_b32 m0, s28
	s_nop 0
	global_load_lds_dwordx4 v140, s[10:11]
	ds_read_b128 v[234:237], v135 offset:1024
	s_waitcnt lgkmcnt(3)
	v_mfma_f32_16x16x32_bf16 v[20:23], v[238:241], v[48:51], v[20:23]
	s_waitcnt lgkmcnt(2)
	v_mfma_f32_16x16x32_bf16 v[68:71], v[230:233], v[48:51], v[116:119]
	s_waitcnt lgkmcnt(1)
	v_mfma_f32_16x16x32_bf16 v[116:119], v[242:245], v[60:63], v[20:23]
	v_mfma_f32_16x16x32_bf16 v[20:23], v[230:233], v[64:67], v[24:27]
	s_waitcnt lgkmcnt(0)
	v_mfma_f32_16x16x32_bf16 v[104:107], v[234:237], v[210:213], v[20:23]
	v_mfma_f32_16x16x32_bf16 v[20:23], v[238:241], v[64:67], v[28:31]
	v_mfma_f32_16x16x32_bf16 v[100:103], v[242:245], v[210:213], v[20:23]
	v_mfma_f32_16x16x32_bf16 v[20:23], v[230:233], v[214:217], v[32:35]
	v_mfma_f32_16x16x32_bf16 v[88:91], v[234:237], v[218:221], v[20:23]
	v_mfma_f32_16x16x32_bf16 v[20:23], v[238:241], v[214:217], v[36:39]
	v_mfma_f32_16x16x32_bf16 v[84:87], v[242:245], v[218:221], v[20:23]
	v_mfma_f32_16x16x32_bf16 v[20:23], v[230:233], v[222:225], v[40:43]
	v_mfma_f32_16x16x32_bf16 v[72:75], v[234:237], v[226:229], v[20:23]
	v_mfma_f32_16x16x32_bf16 v[20:23], v[238:241], v[222:225], v[44:47]
	v_mfma_f32_16x16x32_bf16 v[120:123], v[234:237], v[60:63], v[68:71]
	v_mfma_f32_16x16x32_bf16 v[68:71], v[242:245], v[226:229], v[20:23]
	s_waitcnt vmcnt(4) lgkmcnt(0)
	s_barrier
	s_nop 4
	ds_read_b128 v[20:23], v154 offset:49152
	ds_read_b128 v[24:27], v154 offset:50176
	ds_read_b128 v[36:39], v154 offset:51200
	s_add_u32 s10, s16, 0x160100
	s_addc_u32 s11, s17, 0
	s_mov_b32 m0, s29
	s_nop 0
	global_load_lds_dwordx4 v139, s[10:11]
	s_mov_b32 m0, s36
	s_nop 0
	global_load_lds_dwordx4 v152, s[10:11]
	s_waitcnt lgkmcnt(2)
	v_mfma_f32_16x16x32_bf16 v[28:31], v[12:15], v[20:23], v[142:145]
	ds_read_b128 v[210:213], v154 offset:52224
	s_waitcnt lgkmcnt(2)
	v_mfma_f32_16x16x32_bf16 v[64:67], v[16:19], v[24:27], v[28:31]
	v_mfma_f32_16x16x32_bf16 v[28:31], v[52:55], v[20:23], v[146:149]
	v_mfma_f32_16x16x32_bf16 v[60:63], v[56:59], v[24:27], v[28:31]
	ds_read_b128 v[214:217], v154 offset:53248
	s_waitcnt lgkmcnt(2)
	v_mfma_f32_16x16x32_bf16 v[28:31], v[12:15], v[36:39], v[156:159]
	ds_read_b128 v[222:225], v154 offset:55296
	s_waitcnt lgkmcnt(2)
	v_mfma_f32_16x16x32_bf16 v[48:51], v[16:19], v[210:213], v[28:31]
	ds_read_b128 v[218:221], v154 offset:54272
	v_mfma_f32_16x16x32_bf16 v[28:31], v[52:55], v[36:39], v[160:163]
	v_mfma_f32_16x16x32_bf16 v[44:47], v[56:59], v[210:213], v[28:31]
	ds_read_b128 v[226:229], v154 offset:56320
	s_waitcnt lgkmcnt(3)
	v_mfma_f32_16x16x32_bf16 v[28:31], v[12:15], v[214:217], v[170:173]
	s_waitcnt lgkmcnt(2)
	v_mfma_f32_16x16x32_bf16 v[4:7], v[12:15], v[222:225], v[4:7]
	s_waitcnt lgkmcnt(1)
	v_mfma_f32_16x16x32_bf16 v[32:35], v[16:19], v[218:221], v[28:31]
	v_mfma_f32_16x16x32_bf16 v[28:31], v[52:55], v[214:217], v[174:177]
	s_waitcnt lgkmcnt(0)
	v_mfma_f32_16x16x32_bf16 v[16:19], v[16:19], v[226:229], v[4:7]
	v_mfma_f32_16x16x32_bf16 v[4:7], v[52:55], v[222:225], v[8:11]
	v_mfma_f32_16x16x32_bf16 v[28:31], v[56:59], v[218:221], v[28:31]
	v_mfma_f32_16x16x32_bf16 v[12:15], v[56:59], v[226:229], v[4:7]
	s_add_u32 s10, s18, 0x160100
	s_addc_u32 s11, s19, 0
	s_mov_b32 m0, s37
	s_nop 0
	global_load_lds_dwordx4 v138, s[10:11]
	s_mov_b32 m0, s38
	s_nop 0
	global_load_lds_dwordx4 v140, s[10:11]
	v_mfma_f32_16x16x32_bf16 v[4:7], v[230:233], v[20:23], v[178:181]
	s_mov_b32 s10, 2
	v_mfma_f32_16x16x32_bf16 v[56:59], v[234:237], v[24:27], v[4:7]
	v_mfma_f32_16x16x32_bf16 v[4:7], v[238:241], v[20:23], v[182:185]
	v_mfma_f32_16x16x32_bf16 v[52:55], v[242:245], v[24:27], v[4:7]
	v_mfma_f32_16x16x32_bf16 v[4:7], v[230:233], v[36:39], v[186:189]
	v_mfma_f32_16x16x32_bf16 v[40:43], v[234:237], v[210:213], v[4:7]
	v_mfma_f32_16x16x32_bf16 v[4:7], v[238:241], v[36:39], v[190:193]
	v_mfma_f32_16x16x32_bf16 v[36:39], v[242:245], v[210:213], v[4:7]
	v_mfma_f32_16x16x32_bf16 v[4:7], v[230:233], v[214:217], v[194:197]
	v_mfma_f32_16x16x32_bf16 v[24:27], v[234:237], v[218:221], v[4:7]
	v_mfma_f32_16x16x32_bf16 v[4:7], v[238:241], v[214:217], v[198:201]
	v_mfma_f32_16x16x32_bf16 v[20:23], v[242:245], v[218:221], v[4:7]
	v_mfma_f32_16x16x32_bf16 v[4:7], v[230:233], v[222:225], v[202:205]
	v_mfma_f32_16x16x32_bf16 v[8:11], v[234:237], v[226:229], v[4:7]
	v_mfma_f32_16x16x32_bf16 v[4:7], v[238:241], v[222:225], v[206:209]
	v_mfma_f32_16x16x32_bf16 v[4:7], v[242:245], v[226:229], v[4:7]

; template <class Epi, class Sched>
; __device__ __forceinline__ void gemm_simple(PG8_LAS unsigned char* lds, const Gemm g, const Sched& S, const Epi& E, int wave_s) {
;     ...
; #pragma unroll
;         for (int a = 0; a < 2; ++a)
; #pragma unroll
;             for (int b = 0; b < 2; ++b)
; #pragma unroll
;                 for (int m = 0; m < 4; ++m)
; #pragma unroll
;                     for (int n = 0; n < 2; ++n) acc[a][b][m][n] = (f32x4){zero_o, zero_o, zero_o, zero_o};
.LBB0_92:
	s_cmp_lg_u32 s59, 0
	s_cbranch_scc1 .Lacc0_skip_95
	v_mov_b64_e32 v[14:15], v[2:3]
	v_mov_b64_e32 v[18:19], v[2:3]
	v_mov_b64_e32 v[26:27], v[2:3]
	v_mov_b64_e32 v[34:35], v[2:3]
	v_mov_b64_e32 v[42:43], v[2:3]
	v_mov_b64_e32 v[50:51], v[2:3]
	v_mov_b64_e32 v[58:59], v[2:3]
	v_mov_b64_e32 v[66:67], v[2:3]
	v_mov_b64_e32 v[6:7], v[2:3]
	v_mov_b64_e32 v[10:11], v[2:3]
	v_mov_b64_e32 v[22:23], v[2:3]
	v_mov_b64_e32 v[30:31], v[2:3]
	v_mov_b64_e32 v[38:39], v[2:3]
	v_mov_b64_e32 v[46:47], v[2:3]
	v_mov_b64_e32 v[54:55], v[2:3]
	v_mov_b64_e32 v[62:63], v[2:3]
	v_mov_b64_e32 v[74:75], v[2:3]
	v_mov_b64_e32 v[82:83], v[2:3]
	v_mov_b64_e32 v[90:91], v[2:3]
	v_mov_b64_e32 v[98:99], v[2:3]
	v_mov_b64_e32 v[106:107], v[2:3]
	v_mov_b64_e32 v[114:115], v[2:3]
	v_mov_b64_e32 v[122:123], v[2:3]
	v_mov_b64_e32 v[130:131], v[2:3]
	v_mov_b64_e32 v[70:71], v[2:3]
	v_mov_b64_e32 v[78:79], v[2:3]
	v_mov_b64_e32 v[86:87], v[2:3]
	v_mov_b64_e32 v[94:95], v[2:3]
	v_mov_b64_e32 v[102:103], v[2:3]
	v_mov_b64_e32 v[110:111], v[2:3]
	v_mov_b64_e32 v[118:119], v[2:3]
	v_mov_b64_e32 v[126:127], v[2:3]
	v_mov_b64_e32 v[12:13], v[0:1]
	v_mov_b64_e32 v[16:17], v[0:1]
	v_mov_b64_e32 v[24:25], v[0:1]
	v_mov_b64_e32 v[32:33], v[0:1]
	v_mov_b64_e32 v[40:41], v[0:1]
	v_mov_b64_e32 v[48:49], v[0:1]
	v_mov_b64_e32 v[56:57], v[0:1]
	v_mov_b64_e32 v[64:65], v[0:1]
	v_mov_b64_e32 v[4:5], v[0:1]
	v_mov_b64_e32 v[8:9], v[0:1]
	v_mov_b64_e32 v[20:21], v[0:1]
	v_mov_b64_e32 v[28:29], v[0:1]
	v_mov_b64_e32 v[36:37], v[0:1]
	v_mov_b64_e32 v[44:45], v[0:1]
	v_mov_b64_e32 v[52:53], v[0:1]
	v_mov_b64_e32 v[60:61], v[0:1]
	v_mov_b64_e32 v[72:73], v[0:1]
	v_mov_b64_e32 v[80:81], v[0:1]
	v_mov_b64_e32 v[88:89], v[0:1]
	v_mov_b64_e32 v[96:97], v[0:1]
	v_mov_b64_e32 v[104:105], v[0:1]
	v_mov_b64_e32 v[112:113], v[0:1]
	v_mov_b64_e32 v[120:121], v[0:1]
	v_mov_b64_e32 v[128:129], v[0:1]
	v_mov_b64_e32 v[68:69], v[0:1]
	v_mov_b64_e32 v[76:77], v[0:1]
	v_mov_b64_e32 v[84:85], v[0:1]
	v_mov_b64_e32 v[92:93], v[0:1]
	v_mov_b64_e32 v[100:101], v[0:1]
	v_mov_b64_e32 v[108:109], v[0:1]
	v_mov_b64_e32 v[116:117], v[0:1]
	v_mov_b64_e32 v[124:125], v[0:1]
.Lacc0_skip_95:
	s_mov_b32 s26, 0
	s_cmp_eq_u32 s59, 0
	v_add_u32_e32 v132, 0x10000, v155
	v_add_u32_e32 v133, 0x14000, v155
	v_add_u32_e32 v134, 0x18000, v155
	v_add_u32_e32 v135, 0x1c000, v155
	s_cbranch_scc1 .LBB0_94
	s_waitcnt vmcnt(10) lgkmcnt(0)
	s_barrier
	ds_read_b128 v[4:7], v132
	ds_read_b128 v[44:47], v156 offset:6144
	ds_read_b128 v[20:23], v156
	ds_read_b128 v[12:15], v132 offset:2048
	ds_read_b128 v[28:31], v156 offset:2048
	s_add_u32 s18, s10, 0x80
	s_addc_u32 s19, s11, 0
	s_mov_b32 m0, s48
	s_nop 0
	global_load_lds_dwordx4 v140, s[18:19]
	s_mov_b32 m0, s52
	s_nop 0
	global_load_lds_dwordx4 v153, s[18:19]
	s_waitcnt lgkmcnt(3)
	v_mfma_f32_16x16x32_bf16 v[92:95], v[4:7], v[44:47], v[0:3]
	ds_read_b128 v[36:39], v156 offset:4096
	s_waitcnt lgkmcnt(3)
	v_mfma_f32_16x16x32_bf16 v[68:71], v[4:7], v[20:23], v[0:3]
	s_waitcnt lgkmcnt(2)
	v_mfma_f32_16x16x32_bf16 v[72:75], v[12:15], v[20:23], v[0:3]
	ds_read_b128 v[8:11], v132 offset:1024
	ds_read_b128 v[48:51], v156 offset:7168
	s_waitcnt lgkmcnt(3)
	v_mfma_f32_16x16x32_bf16 v[76:79], v[4:7], v[28:31], v[0:3]
	v_mfma_f32_16x16x32_bf16 v[80:83], v[12:15], v[28:31], v[0:3]
	ds_read_b128 v[24:27], v156 offset:1024
	s_waitcnt lgkmcnt(3)
	v_mfma_f32_16x16x32_bf16 v[84:87], v[4:7], v[36:39], v[0:3]
	ds_read_b128 v[16:19], v132 offset:3072
	v_mfma_f32_16x16x32_bf16 v[88:91], v[12:15], v[36:39], v[0:3]
	ds_read_b128 v[32:35], v156 offset:3072
	s_waitcnt lgkmcnt(3)
	v_mfma_f32_16x16x32_bf16 v[96:99], v[8:11], v[48:51], v[92:95]
	v_mfma_f32_16x16x32_bf16 v[92:95], v[12:15], v[44:47], v[0:3]
	ds_read_b128 v[40:43], v156 offset:5120
	s_waitcnt lgkmcnt(3)
	v_mfma_f32_16x16x32_bf16 v[68:71], v[8:11], v[24:27], v[68:71]
	s_waitcnt lgkmcnt(2)
	v_mfma_f32_16x16x32_bf16 v[72:75], v[16:19], v[24:27], v[72:75]
	s_waitcnt lgkmcnt(1)
	v_mfma_f32_16x16x32_bf16 v[76:79], v[8:11], v[32:35], v[76:79]
	ds_read_b128 v[52:55], v133
	v_mfma_f32_16x16x32_bf16 v[80:83], v[16:19], v[32:35], v[80:83]
	ds_read_b128 v[60:63], v133 offset:2048
	s_waitcnt lgkmcnt(2)
	v_mfma_f32_16x16x32_bf16 v[84:87], v[8:11], v[40:43], v[84:87]
	ds_read_b128 v[56:59], v133 offset:1024
	v_mfma_f32_16x16x32_bf16 v[88:91], v[16:19], v[40:43], v[88:91]
	ds_read_b128 v[64:67], v133 offset:3072
	v_mfma_f32_16x16x32_bf16 v[104:107], v[16:19], v[48:51], v[92:95]
	s_add_u32 s18, s24, 0x80
	s_addc_u32 s19, s25, 0
	s_mov_b32 m0, s49
	s_nop 0
	global_load_lds_dwordx4 v139, s[18:19]
	s_mov_b32 m0, s53
	s_nop 0
	global_load_lds_dwordx4 v152, s[18:19]
	s_waitcnt lgkmcnt(3)
	v_mfma_f32_16x16x32_bf16 v[92:95], v[52:55], v[20:23], v[0:3]
	s_waitcnt lgkmcnt(2)
	v_mfma_f32_16x16x32_bf16 v[20:23], v[60:63], v[20:23], v[0:3]
	s_waitcnt lgkmcnt(1)
	v_mfma_f32_16x16x32_bf16 v[112:115], v[56:59], v[24:27], v[92:95]
	s_waitcnt lgkmcnt(0)
	v_mfma_f32_16x16x32_bf16 v[20:23], v[64:67], v[24:27], v[20:23]
	v_mfma_f32_16x16x32_bf16 v[24:27], v[52:55], v[28:31], v[0:3]
	v_mfma_f32_16x16x32_bf16 v[28:31], v[60:63], v[28:31], v[0:3]
	v_mfma_f32_16x16x32_bf16 v[24:27], v[56:59], v[32:35], v[24:27]
	v_mfma_f32_16x16x32_bf16 v[28:31], v[64:67], v[32:35], v[28:31]
	v_mfma_f32_16x16x32_bf16 v[32:35], v[52:55], v[36:39], v[0:3]
	v_mfma_f32_16x16x32_bf16 v[36:39], v[60:63], v[36:39], v[0:3]
	v_mfma_f32_16x16x32_bf16 v[32:35], v[56:59], v[40:43], v[32:35]
	v_mfma_f32_16x16x32_bf16 v[36:39], v[64:67], v[40:43], v[36:39]
	v_mfma_f32_16x16x32_bf16 v[40:43], v[52:55], v[44:47], v[0:3]
	v_mfma_f32_16x16x32_bf16 v[44:47], v[60:63], v[44:47], v[0:3]
	v_mfma_f32_16x16x32_bf16 v[40:43], v[56:59], v[48:51], v[40:43]
	v_mfma_f32_16x16x32_bf16 v[44:47], v[64:67], v[48:51], v[44:47]
	s_waitcnt vmcnt(12) lgkmcnt(0)
	s_barrier
	ds_read_b128 v[48:51], v156 offset:16384
	ds_read_b128 v[100:103], v156 offset:18432
	ds_read_b128 v[116:119], v156 offset:20480
	ds_read_b128 v[124:127], v156 offset:22528
	ds_read_b128 v[92:95], v156 offset:17408
	s_add_u32 s18, s10, 0x80080
	s_addc_u32 s19, s11, 0
	s_mov_b32 m0, s50
	s_nop 0
	global_load_lds_dwordx4 v140, s[18:19]
	s_mov_b32 m0, s54
	s_nop 0
	global_load_lds_dwordx4 v153, s[18:19]
	s_waitcnt lgkmcnt(4)
	v_mfma_f32_16x16x32_bf16 v[142:145], v[4:7], v[48:51], v[0:3]
	ds_read_b128 v[108:111], v156 offset:19456
	s_waitcnt lgkmcnt(4)
	v_mfma_f32_16x16x32_bf16 v[158:161], v[4:7], v[100:103], v[0:3]
	ds_read_b128 v[120:123], v156 offset:21504
	s_waitcnt lgkmcnt(4)
	v_mfma_f32_16x16x32_bf16 v[174:177], v[4:7], v[116:119], v[0:3]
	ds_read_b128 v[128:131], v156 offset:23552
	s_waitcnt lgkmcnt(4)
	v_mfma_f32_16x16x32_bf16 v[4:7], v[4:7], v[124:127], v[0:3]
	s_waitcnt lgkmcnt(3)
	v_mfma_f32_16x16x32_bf16 v[142:145], v[8:11], v[92:95], v[142:145]
	s_waitcnt lgkmcnt(2)
	v_mfma_f32_16x16x32_bf16 v[158:161], v[8:11], v[108:111], v[158:161]
	s_waitcnt lgkmcnt(1)
	v_mfma_f32_16x16x32_bf16 v[174:177], v[8:11], v[120:123], v[174:177]
	s_waitcnt lgkmcnt(0)
	v_mfma_f32_16x16x32_bf16 v[4:7], v[8:11], v[128:131], v[4:7]
	v_mfma_f32_16x16x32_bf16 v[8:11], v[12:15], v[124:127], v[0:3]
	v_mfma_f32_16x16x32_bf16 v[146:149], v[12:15], v[48:51], v[0:3]
	v_mfma_f32_16x16x32_bf16 v[170:173], v[12:15], v[100:103], v[0:3]
	v_mfma_f32_16x16x32_bf16 v[178:181], v[12:15], v[116:119], v[0:3]
	v_mfma_f32_16x16x32_bf16 v[12:15], v[16:19], v[128:131], v[8:11]
	v_mfma_f32_16x16x32_bf16 v[146:149], v[16:19], v[92:95], v[146:149]
	v_mfma_f32_16x16x32_bf16 v[170:173], v[16:19], v[108:111], v[170:173]
	v_mfma_f32_16x16x32_bf16 v[178:181], v[16:19], v[120:123], v[178:181]
	s_add_u32 s18, s24, 0x80080
	s_addc_u32 s19, s25, 0
	s_mov_b32 m0, s51
	s_nop 0
	global_load_lds_dwordx4 v139, s[18:19]
	s_mov_b32 m0, s55
	s_nop 0
	global_load_lds_dwordx4 v152, s[18:19]
	v_mfma_f32_16x16x32_bf16 v[8:11], v[52:55], v[48:51], v[0:3]
	v_mfma_f32_16x16x32_bf16 v[16:19], v[56:59], v[92:95], v[8:11]
	v_mfma_f32_16x16x32_bf16 v[8:11], v[60:63], v[48:51], v[0:3]
	v_mfma_f32_16x16x32_bf16 v[48:51], v[64:67], v[92:95], v[8:11]
	v_mfma_f32_16x16x32_bf16 v[8:11], v[52:55], v[100:103], v[0:3]
	v_mfma_f32_16x16x32_bf16 v[182:185], v[56:59], v[108:111], v[8:11]
	v_mfma_f32_16x16x32_bf16 v[8:11], v[60:63], v[100:103], v[0:3]
	v_mfma_f32_16x16x32_bf16 v[186:189], v[64:67], v[108:111], v[8:11]
	v_mfma_f32_16x16x32_bf16 v[8:11], v[52:55], v[116:119], v[0:3]
	v_mfma_f32_16x16x32_bf16 v[190:193], v[56:59], v[120:123], v[8:11]
	v_mfma_f32_16x16x32_bf16 v[8:11], v[60:63], v[116:119], v[0:3]
	v_mfma_f32_16x16x32_bf16 v[194:197], v[64:67], v[120:123], v[8:11]
	v_mfma_f32_16x16x32_bf16 v[8:11], v[52:55], v[124:127], v[0:3]
	v_mfma_f32_16x16x32_bf16 v[198:201], v[56:59], v[128:131], v[8:11]
	v_mfma_f32_16x16x32_bf16 v[8:11], v[60:63], v[124:127], v[0:3]
	v_mfma_f32_16x16x32_bf16 v[202:205], v[64:67], v[128:131], v[8:11]
	s_waitcnt vmcnt(2) lgkmcnt(0)
	s_barrier
	s_nop 5
	ds_read_b128 v[8:11], v134
	ds_read_b128 v[52:55], v156 offset:32768
	ds_read_b128 v[56:59], v134 offset:1024
	ds_read_b128 v[60:63], v156 offset:33792
	ds_read_b128 v[64:67], v134 offset:2048
	ds_read_b128 v[206:209], v134 offset:3072
	ds_read_b128 v[210:213], v156 offset:34816
	s_add_u32 s18, s10, 0x100
	s_addc_u32 s19, s11, 0
	s_mov_b32 m0, s35
	s_nop 0
	global_load_lds_dwordx4 v140, s[18:19]
	s_mov_b32 m0, s39
	s_nop 0
	global_load_lds_dwordx4 v153, s[18:19]
	s_waitcnt lgkmcnt(5)
	v_mfma_f32_16x16x32_bf16 v[68:71], v[8:11], v[52:55], v[68:71]
	ds_read_b128 v[214:217], v156 offset:35840
	s_waitcnt lgkmcnt(4)
	v_mfma_f32_16x16x32_bf16 v[124:127], v[56:59], v[60:63], v[68:71]
	s_waitcnt lgkmcnt(3)
	v_mfma_f32_16x16x32_bf16 v[68:71], v[64:67], v[52:55], v[72:75]
	s_waitcnt lgkmcnt(2)
	v_mfma_f32_16x16x32_bf16 v[116:119], v[206:209], v[60:63], v[68:71]
	ds_read_b128 v[218:221], v156 offset:36864
	s_waitcnt lgkmcnt(2)
	v_mfma_f32_16x16x32_bf16 v[68:71], v[8:11], v[210:213], v[76:79]
	ds_read_b128 v[222:225], v156 offset:37888
	s_waitcnt lgkmcnt(2)
	v_mfma_f32_16x16x32_bf16 v[108:111], v[56:59], v[214:217], v[68:71]
	v_mfma_f32_16x16x32_bf16 v[68:71], v[64:67], v[210:213], v[80:83]
	v_mfma_f32_16x16x32_bf16 v[100:103], v[206:209], v[214:217], v[68:71]
	ds_read_b128 v[226:229], v156 offset:38912
	s_waitcnt lgkmcnt(2)
	v_mfma_f32_16x16x32_bf16 v[68:71], v[8:11], v[218:221], v[84:87]
	ds_read_b128 v[230:233], v156 offset:39936
	s_waitcnt lgkmcnt(2)
	v_mfma_f32_16x16x32_bf16 v[92:95], v[56:59], v[222:225], v[68:71]
	v_mfma_f32_16x16x32_bf16 v[68:71], v[64:67], v[218:221], v[88:91]
	v_mfma_f32_16x16x32_bf16 v[84:87], v[206:209], v[222:225], v[68:71]
	ds_read_b128 v[242:245], v135 offset:2048
	s_waitcnt lgkmcnt(2)
	v_mfma_f32_16x16x32_bf16 v[68:71], v[8:11], v[226:229], v[96:99]
	ds_read_b128 v[246:249], v135 offset:3072
	s_waitcnt lgkmcnt(2)
	v_mfma_f32_16x16x32_bf16 v[76:79], v[56:59], v[230:233], v[68:71]
	ds_read_b128 v[234:237], v135
	v_mfma_f32_16x16x32_bf16 v[68:71], v[64:67], v[226:229], v[104:107]
	v_mfma_f32_16x16x32_bf16 v[68:71], v[206:209], v[230:233], v[68:71]
	s_add_u32 s18, s24, 0x100
	s_addc_u32 s19, s25, 0
	s_mov_b32 m0, s23
	s_nop 0
	global_load_lds_dwordx4 v139, s[18:19]
	s_mov_b32 m0, s40
	s_nop 0
	global_load_lds_dwordx4 v152, s[18:19]
	ds_read_b128 v[238:241], v135 offset:1024
	s_waitcnt lgkmcnt(3)
	v_mfma_f32_16x16x32_bf16 v[20:23], v[242:245], v[52:55], v[20:23]
	s_waitcnt lgkmcnt(2)
	v_mfma_f32_16x16x32_bf16 v[120:123], v[246:249], v[60:63], v[20:23]
	s_waitcnt lgkmcnt(1)
	v_mfma_f32_16x16x32_bf16 v[20:23], v[234:237], v[210:213], v[24:27]
	v_mfma_f32_16x16x32_bf16 v[72:75], v[234:237], v[52:55], v[112:115]
	s_waitcnt lgkmcnt(0)
	v_mfma_f32_16x16x32_bf16 v[112:115], v[238:241], v[214:217], v[20:23]
	v_mfma_f32_16x16x32_bf16 v[20:23], v[242:245], v[210:213], v[28:31]
	v_mfma_f32_16x16x32_bf16 v[104:107], v[246:249], v[214:217], v[20:23]
	v_mfma_f32_16x16x32_bf16 v[20:23], v[234:237], v[218:221], v[32:35]
	v_mfma_f32_16x16x32_bf16 v[96:99], v[238:241], v[222:225], v[20:23]
	v_mfma_f32_16x16x32_bf16 v[20:23], v[242:245], v[218:221], v[36:39]
	v_mfma_f32_16x16x32_bf16 v[88:91], v[246:249], v[222:225], v[20:23]
	v_mfma_f32_16x16x32_bf16 v[20:23], v[234:237], v[226:229], v[40:43]
	v_mfma_f32_16x16x32_bf16 v[80:83], v[238:241], v[230:233], v[20:23]
	v_mfma_f32_16x16x32_bf16 v[20:23], v[242:245], v[226:229], v[44:47]
	v_mfma_f32_16x16x32_bf16 v[128:131], v[238:241], v[60:63], v[72:75]
	v_mfma_f32_16x16x32_bf16 v[72:75], v[246:249], v[230:233], v[20:23]
	s_waitcnt vmcnt(4) lgkmcnt(0)
	s_barrier
; template <class Epi, class Sched>
; __device__ __forceinline__ void gemm_simple(PG8_LAS unsigned char* lds, const Gemm g, const Sched& S, const Epi& E, int wave_s) {
;     ...
;             PG8_TILE_W(1, cA + 2 * kstep, cB + 2 * kstep, "2", "4");
;             t = 2;
	ds_read_b128 v[24:27], v156 offset:49152
	ds_read_b128 v[32:35], v156 offset:50176
	ds_read_b128 v[40:43], v156 offset:51200
	s_add_u32 s18, s10, 0x80100
	s_addc_u32 s19, s11, 0
	s_mov_b32 m0, s41
	s_nop 0
	global_load_lds_dwordx4 v140, s[18:19]
	s_mov_b32 m0, s42
	s_nop 0
	global_load_lds_dwordx4 v153, s[18:19]
	s_waitcnt lgkmcnt(2)
	v_mfma_f32_16x16x32_bf16 v[20:23], v[8:11], v[24:27], v[142:145]
	ds_read_b128 v[210:213], v156 offset:52224
	s_waitcnt lgkmcnt(2)
	v_mfma_f32_16x16x32_bf16 v[60:63], v[56:59], v[32:35], v[20:23]
	v_mfma_f32_16x16x32_bf16 v[20:23], v[64:67], v[24:27], v[146:149]
	v_mfma_f32_16x16x32_bf16 v[52:55], v[206:209], v[32:35], v[20:23]
	ds_read_b128 v[214:217], v156 offset:53248
	s_waitcnt lgkmcnt(2)
	v_mfma_f32_16x16x32_bf16 v[20:23], v[8:11], v[40:43], v[158:161]
	ds_read_b128 v[222:225], v156 offset:55296
	s_waitcnt lgkmcnt(2)
	v_mfma_f32_16x16x32_bf16 v[44:47], v[56:59], v[210:213], v[20:23]
	ds_read_b128 v[218:221], v156 offset:54272
	v_mfma_f32_16x16x32_bf16 v[20:23], v[64:67], v[40:43], v[170:173]
	v_mfma_f32_16x16x32_bf16 v[36:39], v[206:209], v[210:213], v[20:23]
	ds_read_b128 v[226:229], v156 offset:56320
	s_waitcnt lgkmcnt(3)
	v_mfma_f32_16x16x32_bf16 v[20:23], v[8:11], v[214:217], v[174:177]
	s_waitcnt lgkmcnt(2)
	v_mfma_f32_16x16x32_bf16 v[4:7], v[8:11], v[222:225], v[4:7]
	s_waitcnt lgkmcnt(1)
	v_mfma_f32_16x16x32_bf16 v[28:31], v[56:59], v[218:221], v[20:23]
	v_mfma_f32_16x16x32_bf16 v[20:23], v[64:67], v[214:217], v[178:181]
	s_waitcnt lgkmcnt(0)
	v_mfma_f32_16x16x32_bf16 v[8:11], v[56:59], v[226:229], v[4:7]
	v_mfma_f32_16x16x32_bf16 v[4:7], v[64:67], v[222:225], v[12:15]
	v_mfma_f32_16x16x32_bf16 v[20:23], v[206:209], v[218:221], v[20:23]
	v_mfma_f32_16x16x32_bf16 v[4:7], v[206:209], v[226:229], v[4:7]
	s_add_u32 s18, s24, 0x80100
	s_addc_u32 s19, s25, 0
	s_mov_b32 m0, s43
	s_nop 0
	global_load_lds_dwordx4 v139, s[18:19]
	s_mov_b32 m0, s44
	s_nop 0
	global_load_lds_dwordx4 v152, s[18:19]
	v_mfma_f32_16x16x32_bf16 v[12:15], v[234:237], v[24:27], v[16:19]
	s_mov_b32 s26, 2
	v_mfma_f32_16x16x32_bf16 v[64:67], v[238:241], v[32:35], v[12:15]
	v_mfma_f32_16x16x32_bf16 v[12:15], v[242:245], v[24:27], v[48:51]
	v_mfma_f32_16x16x32_bf16 v[56:59], v[246:249], v[32:35], v[12:15]
	v_mfma_f32_16x16x32_bf16 v[12:15], v[234:237], v[40:43], v[182:185]
	v_mfma_f32_16x16x32_bf16 v[48:51], v[238:241], v[210:213], v[12:15]
	v_mfma_f32_16x16x32_bf16 v[12:15], v[242:245], v[40:43], v[186:189]
	v_mfma_f32_16x16x32_bf16 v[40:43], v[246:249], v[210:213], v[12:15]
	v_mfma_f32_16x16x32_bf16 v[12:15], v[234:237], v[214:217], v[190:193]
	v_mfma_f32_16x16x32_bf16 v[32:35], v[238:241], v[218:221], v[12:15]
	v_mfma_f32_16x16x32_bf16 v[12:15], v[242:245], v[214:217], v[194:197]
	v_mfma_f32_16x16x32_bf16 v[24:27], v[246:249], v[218:221], v[12:15]
	v_mfma_f32_16x16x32_bf16 v[12:15], v[234:237], v[222:225], v[198:201]
	v_mfma_f32_16x16x32_bf16 v[16:19], v[238:241], v[226:229], v[12:15]
	v_mfma_f32_16x16x32_bf16 v[12:15], v[242:245], v[222:225], v[202:205]
	v_mfma_f32_16x16x32_bf16 v[12:15], v[246:249], v[226:229], v[12:15]

; template <class Epi, class Sched>
; __device__ __forceinline__ void gemm_simple(PG8_LAS unsigned char* lds, const Gemm g, const Sched& S, const Epi& E, int wave_s) {
;     ...
; #pragma unroll
;         for (int a = 0; a < 2; ++a)
; #pragma unroll
;             for (int b = 0; b < 2; ++b)
; #pragma unroll
;                 for (int m = 0; m < 4; ++m)
; #pragma unroll
;                     for (int n = 0; n < 2; ++n) acc[a][b][m][n] = (f32x4){zero_o, zero_o, zero_o, zero_o};
.LBB0_116:
	s_waitcnt lgkmcnt(0)
	s_cmp_lg_u32 s11, 0
	s_cbranch_scc1 .Lacc0_skip_119
	v_mov_b64_e32 v[6:7], v[2:3]
	v_mov_b64_e32 v[10:11], v[2:3]
	v_mov_b64_e32 v[22:23], v[2:3]
	v_mov_b64_e32 v[26:27], v[2:3]
	v_mov_b64_e32 v[38:39], v[2:3]
	v_mov_b64_e32 v[42:43], v[2:3]
	v_mov_b64_e32 v[54:55], v[2:3]
	v_mov_b64_e32 v[58:59], v[2:3]
	v_mov_b64_e32 v[14:15], v[2:3]
	v_mov_b64_e32 v[18:19], v[2:3]
	v_mov_b64_e32 v[30:31], v[2:3]
	v_mov_b64_e32 v[34:35], v[2:3]
	v_mov_b64_e32 v[46:47], v[2:3]
	v_mov_b64_e32 v[50:51], v[2:3]
	v_mov_b64_e32 v[62:63], v[2:3]
	v_mov_b64_e32 v[66:67], v[2:3]
	v_mov_b64_e32 v[70:71], v[2:3]
	v_mov_b64_e32 v[74:75], v[2:3]
	v_mov_b64_e32 v[86:87], v[2:3]
	v_mov_b64_e32 v[90:91], v[2:3]
	v_mov_b64_e32 v[102:103], v[2:3]
	v_mov_b64_e32 v[106:107], v[2:3]
	v_mov_b64_e32 v[118:119], v[2:3]
	v_mov_b64_e32 v[122:123], v[2:3]
	v_mov_b64_e32 v[78:79], v[2:3]
	v_mov_b64_e32 v[82:83], v[2:3]
	v_mov_b64_e32 v[94:95], v[2:3]
	v_mov_b64_e32 v[98:99], v[2:3]
	v_mov_b64_e32 v[110:111], v[2:3]
	v_mov_b64_e32 v[114:115], v[2:3]
	v_mov_b64_e32 v[126:127], v[2:3]
	v_mov_b64_e32 v[130:131], v[2:3]
	v_mov_b64_e32 v[4:5], v[0:1]
	v_mov_b64_e32 v[8:9], v[0:1]
	v_mov_b64_e32 v[20:21], v[0:1]
	v_mov_b64_e32 v[24:25], v[0:1]
	v_mov_b64_e32 v[36:37], v[0:1]
	v_mov_b64_e32 v[40:41], v[0:1]
	v_mov_b64_e32 v[52:53], v[0:1]
	v_mov_b64_e32 v[56:57], v[0:1]
	v_mov_b64_e32 v[12:13], v[0:1]
	v_mov_b64_e32 v[16:17], v[0:1]
	v_mov_b64_e32 v[28:29], v[0:1]
	v_mov_b64_e32 v[32:33], v[0:1]
	v_mov_b64_e32 v[44:45], v[0:1]
	v_mov_b64_e32 v[48:49], v[0:1]
	v_mov_b64_e32 v[60:61], v[0:1]
	v_mov_b64_e32 v[64:65], v[0:1]
	v_mov_b64_e32 v[68:69], v[0:1]
	v_mov_b64_e32 v[72:73], v[0:1]
	v_mov_b64_e32 v[84:85], v[0:1]
	v_mov_b64_e32 v[88:89], v[0:1]
	v_mov_b64_e32 v[100:101], v[0:1]
	v_mov_b64_e32 v[104:105], v[0:1]
	v_mov_b64_e32 v[116:117], v[0:1]
	v_mov_b64_e32 v[120:121], v[0:1]
	v_mov_b64_e32 v[76:77], v[0:1]
	v_mov_b64_e32 v[80:81], v[0:1]
	v_mov_b64_e32 v[92:93], v[0:1]
	v_mov_b64_e32 v[96:97], v[0:1]
	v_mov_b64_e32 v[108:109], v[0:1]
	v_mov_b64_e32 v[112:113], v[0:1]
	v_mov_b64_e32 v[124:125], v[0:1]
	v_mov_b64_e32 v[128:129], v[0:1]
.Lacc0_skip_119:
	v_cmp_lt_i64_e32 vcc, s[16:17], v[168:169]
	s_mov_b32 s58, 0
	s_cmp_eq_u32 s11, 0
	v_add_u32_e32 v132, 0x10000, v153
	v_add_u32_e32 v133, 0x14000, v153
	v_add_u32_e32 v134, 0x18000, v153
	v_add_u32_e32 v135, 0x1c000, v153
	s_cbranch_scc1 .LBB0_118
	s_waitcnt vmcnt(18) lgkmcnt(0)
	s_barrier
	ds_read_b128 v[4:7], v132
	ds_read_b128 v[44:47], v154 offset:6144
	ds_read_b128 v[20:23], v154
	ds_read_b128 v[12:15], v132 offset:2048
	ds_read_b128 v[28:31], v154 offset:2048
	s_add_u32 s16, s24, 0x80
	s_addc_u32 s17, s25, 0
	s_mov_b32 m0, s47
	s_nop 0
	global_load_lds_dwordx4 v139, s[16:17]
	s_mov_b32 m0, s51
	s_nop 0
	global_load_lds_dwordx4 v152, s[16:17]
	s_waitcnt lgkmcnt(3)
	v_mfma_f32_16x16x32_bf16 v[92:95], v[4:7], v[44:47], v[0:3]
	ds_read_b128 v[36:39], v154 offset:4096
	s_waitcnt lgkmcnt(3)
	v_mfma_f32_16x16x32_bf16 v[68:71], v[4:7], v[20:23], v[0:3]
	s_waitcnt lgkmcnt(2)
	v_mfma_f32_16x16x32_bf16 v[72:75], v[12:15], v[20:23], v[0:3]
	ds_read_b128 v[8:11], v132 offset:1024
	ds_read_b128 v[48:51], v154 offset:7168
	s_waitcnt lgkmcnt(3)
	v_mfma_f32_16x16x32_bf16 v[76:79], v[4:7], v[28:31], v[0:3]
	v_mfma_f32_16x16x32_bf16 v[80:83], v[12:15], v[28:31], v[0:3]
	ds_read_b128 v[24:27], v154 offset:1024
	s_waitcnt lgkmcnt(3)
	v_mfma_f32_16x16x32_bf16 v[84:87], v[4:7], v[36:39], v[0:3]
	ds_read_b128 v[16:19], v132 offset:3072
	v_mfma_f32_16x16x32_bf16 v[88:91], v[12:15], v[36:39], v[0:3]
	ds_read_b128 v[32:35], v154 offset:3072
	s_waitcnt lgkmcnt(3)
	v_mfma_f32_16x16x32_bf16 v[100:103], v[8:11], v[48:51], v[92:95]
	v_mfma_f32_16x16x32_bf16 v[92:95], v[12:15], v[44:47], v[0:3]
	ds_read_b128 v[40:43], v154 offset:5120
	s_waitcnt lgkmcnt(3)
	v_mfma_f32_16x16x32_bf16 v[68:71], v[8:11], v[24:27], v[68:71]
	s_waitcnt lgkmcnt(2)
	v_mfma_f32_16x16x32_bf16 v[72:75], v[16:19], v[24:27], v[72:75]
	s_waitcnt lgkmcnt(1)
	v_mfma_f32_16x16x32_bf16 v[76:79], v[8:11], v[32:35], v[76:79]
	ds_read_b128 v[52:55], v133
	v_mfma_f32_16x16x32_bf16 v[80:83], v[16:19], v[32:35], v[80:83]
	ds_read_b128 v[60:63], v133 offset:2048
	s_waitcnt lgkmcnt(2)
	v_mfma_f32_16x16x32_bf16 v[84:87], v[8:11], v[40:43], v[84:87]
	ds_read_b128 v[56:59], v133 offset:1024
	v_mfma_f32_16x16x32_bf16 v[88:91], v[16:19], v[40:43], v[88:91]
	ds_read_b128 v[64:67], v133 offset:3072
	v_mfma_f32_16x16x32_bf16 v[104:107], v[16:19], v[48:51], v[92:95]
	s_add_u32 s16, s26, 0x80
	s_addc_u32 s17, s27, 0
	s_mov_b32 m0, s48
	s_nop 0
	global_load_lds_dwordx4 v138, s[16:17]
	s_mov_b32 m0, s52
	s_nop 0
	global_load_lds_dwordx4 v140, s[16:17]
	s_waitcnt lgkmcnt(3)
	v_mfma_f32_16x16x32_bf16 v[92:95], v[52:55], v[20:23], v[0:3]
	s_waitcnt lgkmcnt(2)
	v_mfma_f32_16x16x32_bf16 v[20:23], v[60:63], v[20:23], v[0:3]
	s_waitcnt lgkmcnt(1)
	v_mfma_f32_16x16x32_bf16 v[116:119], v[56:59], v[24:27], v[92:95]
	s_waitcnt lgkmcnt(0)
	v_mfma_f32_16x16x32_bf16 v[20:23], v[64:67], v[24:27], v[20:23]
	v_mfma_f32_16x16x32_bf16 v[24:27], v[52:55], v[28:31], v[0:3]
	v_mfma_f32_16x16x32_bf16 v[28:31], v[60:63], v[28:31], v[0:3]
	v_mfma_f32_16x16x32_bf16 v[24:27], v[56:59], v[32:35], v[24:27]
	v_mfma_f32_16x16x32_bf16 v[28:31], v[64:67], v[32:35], v[28:31]
	v_mfma_f32_16x16x32_bf16 v[32:35], v[52:55], v[36:39], v[0:3]
	v_mfma_f32_16x16x32_bf16 v[36:39], v[60:63], v[36:39], v[0:3]
	v_mfma_f32_16x16x32_bf16 v[32:35], v[56:59], v[40:43], v[32:35]
	v_mfma_f32_16x16x32_bf16 v[36:39], v[64:67], v[40:43], v[36:39]
	v_mfma_f32_16x16x32_bf16 v[40:43], v[52:55], v[44:47], v[0:3]
	v_mfma_f32_16x16x32_bf16 v[44:47], v[60:63], v[44:47], v[0:3]
	v_mfma_f32_16x16x32_bf16 v[40:43], v[56:59], v[48:51], v[40:43]
	v_mfma_f32_16x16x32_bf16 v[44:47], v[64:67], v[48:51], v[44:47]
	s_waitcnt vmcnt(20) lgkmcnt(0)
	s_barrier
	ds_read_b128 v[48:51], v154 offset:16384
	ds_read_b128 v[96:99], v154 offset:18432
	ds_read_b128 v[112:115], v154 offset:20480
	ds_read_b128 v[124:127], v154 offset:22528
	ds_read_b128 v[92:95], v154 offset:17408
	s_add_u32 s16, s24, 0x80080
	s_addc_u32 s17, s25, 0
	s_mov_b32 m0, s49
	s_nop 0
	global_load_lds_dwordx4 v139, s[16:17]
	s_mov_b32 m0, s53
	s_nop 0
	global_load_lds_dwordx4 v152, s[16:17]
	s_waitcnt lgkmcnt(4)
	v_mfma_f32_16x16x32_bf16 v[146:149], v[4:7], v[48:51], v[0:3]
	ds_read_b128 v[108:111], v154 offset:19456
	s_waitcnt lgkmcnt(4)
	v_mfma_f32_16x16x32_bf16 v[160:163], v[4:7], v[96:99], v[0:3]
	ds_read_b128 v[120:123], v154 offset:21504
	s_waitcnt lgkmcnt(4)
	v_mfma_f32_16x16x32_bf16 v[174:177], v[4:7], v[112:115], v[0:3]
	ds_read_b128 v[128:131], v154 offset:23552
	s_waitcnt lgkmcnt(4)
	v_mfma_f32_16x16x32_bf16 v[4:7], v[4:7], v[124:127], v[0:3]
	s_waitcnt lgkmcnt(3)
	v_mfma_f32_16x16x32_bf16 v[146:149], v[8:11], v[92:95], v[146:149]
	s_waitcnt lgkmcnt(2)
	v_mfma_f32_16x16x32_bf16 v[160:163], v[8:11], v[108:111], v[160:163]
	s_waitcnt lgkmcnt(1)
	v_mfma_f32_16x16x32_bf16 v[174:177], v[8:11], v[120:123], v[174:177]
	s_waitcnt lgkmcnt(0)
	v_mfma_f32_16x16x32_bf16 v[4:7], v[8:11], v[128:131], v[4:7]
	v_mfma_f32_16x16x32_bf16 v[8:11], v[12:15], v[124:127], v[0:3]
	v_mfma_f32_16x16x32_bf16 v[156:159], v[12:15], v[48:51], v[0:3]
	v_mfma_f32_16x16x32_bf16 v[170:173], v[12:15], v[96:99], v[0:3]
	v_mfma_f32_16x16x32_bf16 v[178:181], v[12:15], v[112:115], v[0:3]
	v_mfma_f32_16x16x32_bf16 v[8:11], v[16:19], v[128:131], v[8:11]
	v_mfma_f32_16x16x32_bf16 v[156:159], v[16:19], v[92:95], v[156:159]
	v_mfma_f32_16x16x32_bf16 v[170:173], v[16:19], v[108:111], v[170:173]
	v_mfma_f32_16x16x32_bf16 v[178:181], v[16:19], v[120:123], v[178:181]
	s_add_u32 s16, s26, 0x80080
	s_addc_u32 s17, s27, 0
	s_mov_b32 m0, s50
	s_nop 0
	global_load_lds_dwordx4 v138, s[16:17]
	s_mov_b32 m0, s54
	s_nop 0
	global_load_lds_dwordx4 v140, s[16:17]
	v_mfma_f32_16x16x32_bf16 v[12:15], v[52:55], v[48:51], v[0:3]
	v_mfma_f32_16x16x32_bf16 v[182:185], v[56:59], v[92:95], v[12:15]
	v_mfma_f32_16x16x32_bf16 v[12:15], v[60:63], v[48:51], v[0:3]
	v_mfma_f32_16x16x32_bf16 v[186:189], v[64:67], v[92:95], v[12:15]
	v_mfma_f32_16x16x32_bf16 v[12:15], v[52:55], v[96:99], v[0:3]
	v_mfma_f32_16x16x32_bf16 v[190:193], v[56:59], v[108:111], v[12:15]
	v_mfma_f32_16x16x32_bf16 v[12:15], v[60:63], v[96:99], v[0:3]
	v_mfma_f32_16x16x32_bf16 v[194:197], v[64:67], v[108:111], v[12:15]
	v_mfma_f32_16x16x32_bf16 v[12:15], v[52:55], v[112:115], v[0:3]
	v_mfma_f32_16x16x32_bf16 v[198:201], v[56:59], v[120:123], v[12:15]
	v_mfma_f32_16x16x32_bf16 v[12:15], v[60:63], v[112:115], v[0:3]
	v_mfma_f32_16x16x32_bf16 v[202:205], v[64:67], v[120:123], v[12:15]
	v_mfma_f32_16x16x32_bf16 v[12:15], v[52:55], v[124:127], v[0:3]
	v_mfma_f32_16x16x32_bf16 v[206:209], v[56:59], v[128:131], v[12:15]
	v_mfma_f32_16x16x32_bf16 v[12:15], v[60:63], v[124:127], v[0:3]
	v_mfma_f32_16x16x32_bf16 v[210:213], v[64:67], v[128:131], v[12:15]
	s_waitcnt vmcnt(2) lgkmcnt(0)
	s_barrier
; template <class Epi, class Sched>
; __device__ __forceinline__ void gemm_simple(PG8_LAS unsigned char* lds, const Gemm g, const Sched& S, const Epi& E, int wave_s) {
;     ...
;             PG8_TILE_W(1, cA + 2 * kstep, cB + 2 * kstep, "2", "4");
;             t = 2;
	s_nop 5
	ds_read_b128 v[12:15], v134
	ds_read_b128 v[48:51], v154 offset:32768
	ds_read_b128 v[16:19], v134 offset:1024
	ds_read_b128 v[60:63], v154 offset:33792
	ds_read_b128 v[52:55], v134 offset:2048
	ds_read_b128 v[56:59], v134 offset:3072
	ds_read_b128 v[64:67], v154 offset:34816
	s_add_u32 s16, s24, 0x100
	s_addc_u32 s17, s25, 0
	s_mov_b32 m0, s40
	s_nop 0
	global_load_lds_dwordx4 v139, s[16:17]
	s_mov_b32 m0, s41
	s_nop 0
	global_load_lds_dwordx4 v152, s[16:17]
	s_waitcnt lgkmcnt(5)
	v_mfma_f32_16x16x32_bf16 v[68:71], v[12:15], v[48:51], v[68:71]
	ds_read_b128 v[214:217], v154 offset:35840
	s_waitcnt lgkmcnt(4)
	v_mfma_f32_16x16x32_bf16 v[128:131], v[16:19], v[60:63], v[68:71]
	s_waitcnt lgkmcnt(3)
	v_mfma_f32_16x16x32_bf16 v[68:71], v[52:55], v[48:51], v[72:75]
	s_waitcnt lgkmcnt(2)
	v_mfma_f32_16x16x32_bf16 v[124:127], v[56:59], v[60:63], v[68:71]
	ds_read_b128 v[218:221], v154 offset:36864
	s_waitcnt lgkmcnt(2)
	v_mfma_f32_16x16x32_bf16 v[68:71], v[12:15], v[64:67], v[76:79]
	ds_read_b128 v[222:225], v154 offset:37888
	s_waitcnt lgkmcnt(2)
	v_mfma_f32_16x16x32_bf16 v[112:115], v[16:19], v[214:217], v[68:71]
	v_mfma_f32_16x16x32_bf16 v[68:71], v[52:55], v[64:67], v[80:83]
	v_mfma_f32_16x16x32_bf16 v[108:111], v[56:59], v[214:217], v[68:71]
	ds_read_b128 v[226:229], v154 offset:38912
	s_waitcnt lgkmcnt(2)
	v_mfma_f32_16x16x32_bf16 v[68:71], v[12:15], v[218:221], v[84:87]
	ds_read_b128 v[230:233], v154 offset:39936
	s_waitcnt lgkmcnt(2)
	v_mfma_f32_16x16x32_bf16 v[96:99], v[16:19], v[222:225], v[68:71]
	v_mfma_f32_16x16x32_bf16 v[68:71], v[52:55], v[218:221], v[88:91]
	v_mfma_f32_16x16x32_bf16 v[92:95], v[56:59], v[222:225], v[68:71]
	ds_read_b128 v[242:245], v135 offset:2048
	s_waitcnt lgkmcnt(2)
	v_mfma_f32_16x16x32_bf16 v[68:71], v[12:15], v[226:229], v[100:103]
	ds_read_b128 v[234:237], v135
	s_waitcnt lgkmcnt(2)
	v_mfma_f32_16x16x32_bf16 v[80:83], v[16:19], v[230:233], v[68:71]
	ds_read_b128 v[246:249], v135 offset:3072
	v_mfma_f32_16x16x32_bf16 v[68:71], v[52:55], v[226:229], v[104:107]
	v_mfma_f32_16x16x32_bf16 v[76:79], v[56:59], v[230:233], v[68:71]
	s_add_u32 s16, s26, 0x100
	s_addc_u32 s17, s27, 0
	s_mov_b32 m0, s39
	s_nop 0
	global_load_lds_dwordx4 v138, s[16:17]
	s_mov_b32 m0, s42
	s_nop 0
	global_load_lds_dwordx4 v140, s[16:17]
	ds_read_b128 v[238:241], v135 offset:1024
	s_waitcnt lgkmcnt(3)
	v_mfma_f32_16x16x32_bf16 v[20:23], v[242:245], v[48:51], v[20:23]
	s_waitcnt lgkmcnt(2)
	v_mfma_f32_16x16x32_bf16 v[68:71], v[234:237], v[48:51], v[116:119]
	s_waitcnt lgkmcnt(1)
	v_mfma_f32_16x16x32_bf16 v[116:119], v[246:249], v[60:63], v[20:23]
	v_mfma_f32_16x16x32_bf16 v[20:23], v[234:237], v[64:67], v[24:27]
	s_waitcnt lgkmcnt(0)
	v_mfma_f32_16x16x32_bf16 v[104:107], v[238:241], v[214:217], v[20:23]
	v_mfma_f32_16x16x32_bf16 v[20:23], v[242:245], v[64:67], v[28:31]
	v_mfma_f32_16x16x32_bf16 v[100:103], v[246:249], v[214:217], v[20:23]
	v_mfma_f32_16x16x32_bf16 v[20:23], v[234:237], v[218:221], v[32:35]
	v_mfma_f32_16x16x32_bf16 v[88:91], v[238:241], v[222:225], v[20:23]
	v_mfma_f32_16x16x32_bf16 v[20:23], v[242:245], v[218:221], v[36:39]
	v_mfma_f32_16x16x32_bf16 v[84:87], v[246:249], v[222:225], v[20:23]
	v_mfma_f32_16x16x32_bf16 v[20:23], v[234:237], v[226:229], v[40:43]
	v_mfma_f32_16x16x32_bf16 v[72:75], v[238:241], v[230:233], v[20:23]
	v_mfma_f32_16x16x32_bf16 v[20:23], v[242:245], v[226:229], v[44:47]
	v_mfma_f32_16x16x32_bf16 v[120:123], v[238:241], v[60:63], v[68:71]
	v_mfma_f32_16x16x32_bf16 v[68:71], v[246:249], v[230:233], v[20:23]
	s_waitcnt vmcnt(4) lgkmcnt(0)
	s_barrier
	s_nop 4
	ds_read_b128 v[20:23], v154 offset:49152
	ds_read_b128 v[24:27], v154 offset:50176
	ds_read_b128 v[36:39], v154 offset:51200
	s_add_u32 s16, s24, 0x80100
	s_addc_u32 s17, s25, 0
	s_mov_b32 m0, s43
	s_nop 0
	global_load_lds_dwordx4 v139, s[16:17]
	s_mov_b32 m0, s44
	s_nop 0
	global_load_lds_dwordx4 v152, s[16:17]
	s_waitcnt lgkmcnt(2)
	v_mfma_f32_16x16x32_bf16 v[28:31], v[12:15], v[20:23], v[146:149]
	ds_read_b128 v[214:217], v154 offset:52224
	s_waitcnt lgkmcnt(2)
	v_mfma_f32_16x16x32_bf16 v[64:67], v[16:19], v[24:27], v[28:31]
	v_mfma_f32_16x16x32_bf16 v[28:31], v[52:55], v[20:23], v[156:159]
	v_mfma_f32_16x16x32_bf16 v[60:63], v[56:59], v[24:27], v[28:31]
	ds_read_b128 v[218:221], v154 offset:53248
	s_waitcnt lgkmcnt(2)
	v_mfma_f32_16x16x32_bf16 v[28:31], v[12:15], v[36:39], v[160:163]
	ds_read_b128 v[226:229], v154 offset:55296
	s_waitcnt lgkmcnt(2)
	v_mfma_f32_16x16x32_bf16 v[48:51], v[16:19], v[214:217], v[28:31]
	ds_read_b128 v[222:225], v154 offset:54272
	v_mfma_f32_16x16x32_bf16 v[28:31], v[52:55], v[36:39], v[170:173]
	v_mfma_f32_16x16x32_bf16 v[44:47], v[56:59], v[214:217], v[28:31]
	ds_read_b128 v[230:233], v154 offset:56320
	s_waitcnt lgkmcnt(3)
	v_mfma_f32_16x16x32_bf16 v[28:31], v[12:15], v[218:221], v[174:177]
	s_waitcnt lgkmcnt(2)
	v_mfma_f32_16x16x32_bf16 v[4:7], v[12:15], v[226:229], v[4:7]
	s_waitcnt lgkmcnt(1)
	v_mfma_f32_16x16x32_bf16 v[32:35], v[16:19], v[222:225], v[28:31]
	v_mfma_f32_16x16x32_bf16 v[28:31], v[52:55], v[218:221], v[178:181]
	s_waitcnt lgkmcnt(0)
	v_mfma_f32_16x16x32_bf16 v[16:19], v[16:19], v[230:233], v[4:7]
	v_mfma_f32_16x16x32_bf16 v[4:7], v[52:55], v[226:229], v[8:11]
	v_mfma_f32_16x16x32_bf16 v[28:31], v[56:59], v[222:225], v[28:31]
	v_mfma_f32_16x16x32_bf16 v[12:15], v[56:59], v[230:233], v[4:7]
	s_add_u32 s16, s26, 0x80100
	s_addc_u32 s17, s27, 0
	s_mov_b32 m0, s45
	s_nop 0
	global_load_lds_dwordx4 v138, s[16:17]
	s_mov_b32 m0, s46
	s_nop 0
	global_load_lds_dwordx4 v140, s[16:17]
	v_mfma_f32_16x16x32_bf16 v[4:7], v[234:237], v[20:23], v[182:185]
	s_mov_b32 s58, 2
	v_mfma_f32_16x16x32_bf16 v[56:59], v[238:241], v[24:27], v[4:7]
	v_mfma_f32_16x16x32_bf16 v[4:7], v[242:245], v[20:23], v[186:189]
	v_mfma_f32_16x16x32_bf16 v[52:55], v[246:249], v[24:27], v[4:7]
	v_mfma_f32_16x16x32_bf16 v[4:7], v[234:237], v[36:39], v[190:193]
	v_mfma_f32_16x16x32_bf16 v[40:43], v[238:241], v[214:217], v[4:7]
	v_mfma_f32_16x16x32_bf16 v[4:7], v[242:245], v[36:39], v[194:197]
	v_mfma_f32_16x16x32_bf16 v[36:39], v[246:249], v[214:217], v[4:7]
	v_mfma_f32_16x16x32_bf16 v[4:7], v[234:237], v[218:221], v[198:201]
	v_mfma_f32_16x16x32_bf16 v[24:27], v[238:241], v[222:225], v[4:7]
	v_mfma_f32_16x16x32_bf16 v[4:7], v[242:245], v[218:221], v[202:205]
	v_mfma_f32_16x16x32_bf16 v[20:23], v[246:249], v[222:225], v[4:7]
	v_mfma_f32_16x16x32_bf16 v[4:7], v[234:237], v[226:229], v[206:209]
	v_mfma_f32_16x16x32_bf16 v[8:11], v[238:241], v[230:233], v[4:7]
	v_mfma_f32_16x16x32_bf16 v[4:7], v[242:245], v[226:229], v[210:213]
	v_mfma_f32_16x16x32_bf16 v[4:7], v[246:249], v[230:233], v[4:7]

; template <class Epi, class Sched>
; __device__ __forceinline__ void gemm_simple(PG8_LAS unsigned char* lds, const Gemm g, const Sched& S, const Epi& E, int wave_s) {
;     ...
; #pragma unroll
;         for (int a = 0; a < 2; ++a)
; #pragma unroll
;             for (int b = 0; b < 2; ++b)
; #pragma unroll
;                 for (int m = 0; m < 4; ++m)
; #pragma unroll
;                     for (int n = 0; n < 2; ++n) acc[a][b][m][n] = (f32x4){zero_o, zero_o, zero_o, zero_o};
.LBB0_170:
	s_cmp_lg_u32 s9, 0
	s_cbranch_scc1 .Lacc0_skip_173
	v_mov_b64_e32 v[10:11], v[2:3]
	v_mov_b64_e32 v[6:7], v[2:3]
	v_mov_b64_e32 v[22:23], v[2:3]
	v_mov_b64_e32 v[26:27], v[2:3]
	v_mov_b64_e32 v[38:39], v[2:3]
	v_mov_b64_e32 v[42:43], v[2:3]
	v_mov_b64_e32 v[54:55], v[2:3]
	v_mov_b64_e32 v[58:59], v[2:3]
	v_mov_b64_e32 v[14:15], v[2:3]
	v_mov_b64_e32 v[18:19], v[2:3]
	v_mov_b64_e32 v[30:31], v[2:3]
	v_mov_b64_e32 v[34:35], v[2:3]
	v_mov_b64_e32 v[46:47], v[2:3]
	v_mov_b64_e32 v[50:51], v[2:3]
	v_mov_b64_e32 v[62:63], v[2:3]
	v_mov_b64_e32 v[66:67], v[2:3]
	v_mov_b64_e32 v[70:71], v[2:3]
	v_mov_b64_e32 v[74:75], v[2:3]
	v_mov_b64_e32 v[86:87], v[2:3]
	v_mov_b64_e32 v[90:91], v[2:3]
	v_mov_b64_e32 v[102:103], v[2:3]
	v_mov_b64_e32 v[106:107], v[2:3]
	v_mov_b64_e32 v[118:119], v[2:3]
	v_mov_b64_e32 v[122:123], v[2:3]
	v_mov_b64_e32 v[78:79], v[2:3]
	v_mov_b64_e32 v[82:83], v[2:3]
	v_mov_b64_e32 v[94:95], v[2:3]
	v_mov_b64_e32 v[98:99], v[2:3]
	v_mov_b64_e32 v[110:111], v[2:3]
	v_mov_b64_e32 v[114:115], v[2:3]
	v_mov_b64_e32 v[126:127], v[2:3]
	v_mov_b64_e32 v[130:131], v[2:3]
	v_mov_b64_e32 v[8:9], v[0:1]
	v_mov_b64_e32 v[4:5], v[0:1]
	v_mov_b64_e32 v[20:21], v[0:1]
	v_mov_b64_e32 v[24:25], v[0:1]
	v_mov_b64_e32 v[36:37], v[0:1]
	v_mov_b64_e32 v[40:41], v[0:1]
	v_mov_b64_e32 v[52:53], v[0:1]
	v_mov_b64_e32 v[56:57], v[0:1]
	v_mov_b64_e32 v[12:13], v[0:1]
	v_mov_b64_e32 v[16:17], v[0:1]
	v_mov_b64_e32 v[28:29], v[0:1]
	v_mov_b64_e32 v[32:33], v[0:1]
	v_mov_b64_e32 v[44:45], v[0:1]
	v_mov_b64_e32 v[48:49], v[0:1]
	v_mov_b64_e32 v[60:61], v[0:1]
	v_mov_b64_e32 v[64:65], v[0:1]
	v_mov_b64_e32 v[68:69], v[0:1]
	v_mov_b64_e32 v[72:73], v[0:1]
	v_mov_b64_e32 v[84:85], v[0:1]
	v_mov_b64_e32 v[88:89], v[0:1]
	v_mov_b64_e32 v[100:101], v[0:1]
	v_mov_b64_e32 v[104:105], v[0:1]
	v_mov_b64_e32 v[116:117], v[0:1]
	v_mov_b64_e32 v[120:121], v[0:1]
	v_mov_b64_e32 v[76:77], v[0:1]
	v_mov_b64_e32 v[80:81], v[0:1]
	v_mov_b64_e32 v[92:93], v[0:1]
	v_mov_b64_e32 v[96:97], v[0:1]
	v_mov_b64_e32 v[108:109], v[0:1]
	v_mov_b64_e32 v[112:113], v[0:1]
	v_mov_b64_e32 v[124:125], v[0:1]
	v_mov_b64_e32 v[128:129], v[0:1]
.Lacc0_skip_173:
	v_cmp_lt_i64_e32 vcc, s[10:11], v[168:169]
	s_mov_b32 s24, 0
	s_cmp_eq_u32 s9, 0
	v_add_u32_e32 v132, 0x10000, v140
	v_add_u32_e32 v133, 0x14000, v140
	v_add_u32_e32 v134, 0x18000, v140
	v_add_u32_e32 v135, 0x1c000, v140
	s_cbranch_scc1 .LBB0_172
	s_waitcnt vmcnt(18) lgkmcnt(0)
	s_barrier
	ds_read_b128 v[4:7], v132
	ds_read_b128 v[44:47], v152 offset:6144
	ds_read_b128 v[20:23], v152
	ds_read_b128 v[12:15], v132 offset:2048
	ds_read_b128 v[28:31], v152 offset:2048
	s_add_u32 s10, s20, 0x80
	s_addc_u32 s11, s21, 0
	s_mov_b32 m0, s46
	s_nop 0
	global_load_lds_dwordx4 v137, s[10:11]
	s_mov_b32 m0, s50
	s_nop 0
	global_load_lds_dwordx4 v139, s[10:11]
	s_waitcnt lgkmcnt(3)
	v_mfma_f32_16x16x32_bf16 v[92:95], v[4:7], v[44:47], v[0:3]
	ds_read_b128 v[36:39], v152 offset:4096
	s_waitcnt lgkmcnt(3)
	v_mfma_f32_16x16x32_bf16 v[68:71], v[4:7], v[20:23], v[0:3]
	s_waitcnt lgkmcnt(2)
	v_mfma_f32_16x16x32_bf16 v[72:75], v[12:15], v[20:23], v[0:3]
	ds_read_b128 v[8:11], v132 offset:1024
	ds_read_b128 v[48:51], v152 offset:7168
	s_waitcnt lgkmcnt(3)
	v_mfma_f32_16x16x32_bf16 v[76:79], v[4:7], v[28:31], v[0:3]
	v_mfma_f32_16x16x32_bf16 v[80:83], v[12:15], v[28:31], v[0:3]
	ds_read_b128 v[24:27], v152 offset:1024
	s_waitcnt lgkmcnt(3)
	v_mfma_f32_16x16x32_bf16 v[84:87], v[4:7], v[36:39], v[0:3]
	ds_read_b128 v[16:19], v132 offset:3072
	v_mfma_f32_16x16x32_bf16 v[88:91], v[12:15], v[36:39], v[0:3]
	ds_read_b128 v[32:35], v152 offset:3072
	s_waitcnt lgkmcnt(3)
	v_mfma_f32_16x16x32_bf16 v[100:103], v[8:11], v[48:51], v[92:95]
	v_mfma_f32_16x16x32_bf16 v[92:95], v[12:15], v[44:47], v[0:3]
	ds_read_b128 v[40:43], v152 offset:5120
	s_waitcnt lgkmcnt(3)
	v_mfma_f32_16x16x32_bf16 v[68:71], v[8:11], v[24:27], v[68:71]
	s_waitcnt lgkmcnt(2)
	v_mfma_f32_16x16x32_bf16 v[72:75], v[16:19], v[24:27], v[72:75]
	s_waitcnt lgkmcnt(1)
	v_mfma_f32_16x16x32_bf16 v[76:79], v[8:11], v[32:35], v[76:79]
	ds_read_b128 v[52:55], v133
	v_mfma_f32_16x16x32_bf16 v[80:83], v[16:19], v[32:35], v[80:83]
	ds_read_b128 v[60:63], v133 offset:2048
	s_waitcnt lgkmcnt(2)
	v_mfma_f32_16x16x32_bf16 v[84:87], v[8:11], v[40:43], v[84:87]
	ds_read_b128 v[56:59], v133 offset:1024
	v_mfma_f32_16x16x32_bf16 v[88:91], v[16:19], v[40:43], v[88:91]
	ds_read_b128 v[64:67], v133 offset:3072
	v_mfma_f32_16x16x32_bf16 v[104:107], v[16:19], v[48:51], v[92:95]
	s_add_u32 s10, s22, 0x80
	s_addc_u32 s11, s23, 0
	s_mov_b32 m0, s47
	s_nop 0
	global_load_lds_dwordx4 v136, s[10:11]
	s_mov_b32 m0, s51
	s_nop 0
	global_load_lds_dwordx4 v138, s[10:11]
	s_waitcnt lgkmcnt(3)
	v_mfma_f32_16x16x32_bf16 v[92:95], v[52:55], v[20:23], v[0:3]
	s_waitcnt lgkmcnt(2)
	v_mfma_f32_16x16x32_bf16 v[20:23], v[60:63], v[20:23], v[0:3]
	s_waitcnt lgkmcnt(1)
	v_mfma_f32_16x16x32_bf16 v[116:119], v[56:59], v[24:27], v[92:95]
	s_waitcnt lgkmcnt(0)
	v_mfma_f32_16x16x32_bf16 v[20:23], v[64:67], v[24:27], v[20:23]
	v_mfma_f32_16x16x32_bf16 v[24:27], v[52:55], v[28:31], v[0:3]
	v_mfma_f32_16x16x32_bf16 v[28:31], v[60:63], v[28:31], v[0:3]
	v_mfma_f32_16x16x32_bf16 v[24:27], v[56:59], v[32:35], v[24:27]
	v_mfma_f32_16x16x32_bf16 v[28:31], v[64:67], v[32:35], v[28:31]
	v_mfma_f32_16x16x32_bf16 v[32:35], v[52:55], v[36:39], v[0:3]
	v_mfma_f32_16x16x32_bf16 v[36:39], v[60:63], v[36:39], v[0:3]
	v_mfma_f32_16x16x32_bf16 v[32:35], v[56:59], v[40:43], v[32:35]
	v_mfma_f32_16x16x32_bf16 v[36:39], v[64:67], v[40:43], v[36:39]
	v_mfma_f32_16x16x32_bf16 v[40:43], v[52:55], v[44:47], v[0:3]
	v_mfma_f32_16x16x32_bf16 v[44:47], v[60:63], v[44:47], v[0:3]
	v_mfma_f32_16x16x32_bf16 v[40:43], v[56:59], v[48:51], v[40:43]
	v_mfma_f32_16x16x32_bf16 v[44:47], v[64:67], v[48:51], v[44:47]
	s_waitcnt vmcnt(20) lgkmcnt(0)
	s_barrier
	ds_read_b128 v[48:51], v152 offset:16384
	ds_read_b128 v[96:99], v152 offset:18432
	ds_read_b128 v[112:115], v152 offset:20480
	ds_read_b128 v[124:127], v152 offset:22528
	ds_read_b128 v[92:95], v152 offset:17408
	s_add_u32 s10, s20, 0x40080
	s_addc_u32 s11, s21, 0
	s_mov_b32 m0, s48
	s_nop 0
	global_load_lds_dwordx4 v137, s[10:11]
	s_mov_b32 m0, s52
	s_nop 0
	global_load_lds_dwordx4 v139, s[10:11]
	s_waitcnt lgkmcnt(4)
	v_mfma_f32_16x16x32_bf16 v[146:149], v[4:7], v[48:51], v[0:3]
	ds_read_b128 v[108:111], v152 offset:19456
	s_waitcnt lgkmcnt(4)
	v_mfma_f32_16x16x32_bf16 v[158:161], v[4:7], v[96:99], v[0:3]
	ds_read_b128 v[120:123], v152 offset:21504
	s_waitcnt lgkmcnt(4)
	v_mfma_f32_16x16x32_bf16 v[174:177], v[4:7], v[112:115], v[0:3]
	ds_read_b128 v[128:131], v152 offset:23552
	s_waitcnt lgkmcnt(4)
	v_mfma_f32_16x16x32_bf16 v[4:7], v[4:7], v[124:127], v[0:3]
	s_waitcnt lgkmcnt(3)
	v_mfma_f32_16x16x32_bf16 v[146:149], v[8:11], v[92:95], v[146:149]
	s_waitcnt lgkmcnt(2)
	v_mfma_f32_16x16x32_bf16 v[158:161], v[8:11], v[108:111], v[158:161]
	s_waitcnt lgkmcnt(1)
	v_mfma_f32_16x16x32_bf16 v[174:177], v[8:11], v[120:123], v[174:177]
	s_waitcnt lgkmcnt(0)
	v_mfma_f32_16x16x32_bf16 v[4:7], v[8:11], v[128:131], v[4:7]
	v_mfma_f32_16x16x32_bf16 v[8:11], v[12:15], v[124:127], v[0:3]
	v_mfma_f32_16x16x32_bf16 v[154:157], v[12:15], v[48:51], v[0:3]
	v_mfma_f32_16x16x32_bf16 v[170:173], v[12:15], v[96:99], v[0:3]
	v_mfma_f32_16x16x32_bf16 v[178:181], v[12:15], v[112:115], v[0:3]
	v_mfma_f32_16x16x32_bf16 v[8:11], v[16:19], v[128:131], v[8:11]
	v_mfma_f32_16x16x32_bf16 v[154:157], v[16:19], v[92:95], v[154:157]
	v_mfma_f32_16x16x32_bf16 v[170:173], v[16:19], v[108:111], v[170:173]
	v_mfma_f32_16x16x32_bf16 v[178:181], v[16:19], v[120:123], v[178:181]
	s_add_u32 s10, s22, 0x40080
	s_addc_u32 s11, s23, 0
	s_mov_b32 m0, s49
	s_nop 0
	global_load_lds_dwordx4 v136, s[10:11]
	s_mov_b32 m0, s53
	s_nop 0
	global_load_lds_dwordx4 v138, s[10:11]
	v_mfma_f32_16x16x32_bf16 v[12:15], v[52:55], v[48:51], v[0:3]
	v_mfma_f32_16x16x32_bf16 v[182:185], v[56:59], v[92:95], v[12:15]
	v_mfma_f32_16x16x32_bf16 v[12:15], v[60:63], v[48:51], v[0:3]
	v_mfma_f32_16x16x32_bf16 v[186:189], v[64:67], v[92:95], v[12:15]
	v_mfma_f32_16x16x32_bf16 v[12:15], v[52:55], v[96:99], v[0:3]
	v_mfma_f32_16x16x32_bf16 v[190:193], v[56:59], v[108:111], v[12:15]
	v_mfma_f32_16x16x32_bf16 v[12:15], v[60:63], v[96:99], v[0:3]
	v_mfma_f32_16x16x32_bf16 v[194:197], v[64:67], v[108:111], v[12:15]
	v_mfma_f32_16x16x32_bf16 v[12:15], v[52:55], v[112:115], v[0:3]
	v_mfma_f32_16x16x32_bf16 v[198:201], v[56:59], v[120:123], v[12:15]
	v_mfma_f32_16x16x32_bf16 v[12:15], v[60:63], v[112:115], v[0:3]
	v_mfma_f32_16x16x32_bf16 v[202:205], v[64:67], v[120:123], v[12:15]
	v_mfma_f32_16x16x32_bf16 v[12:15], v[52:55], v[124:127], v[0:3]
	v_mfma_f32_16x16x32_bf16 v[206:209], v[56:59], v[128:131], v[12:15]
	v_mfma_f32_16x16x32_bf16 v[12:15], v[60:63], v[124:127], v[0:3]
	v_mfma_f32_16x16x32_bf16 v[210:213], v[64:67], v[128:131], v[12:15]
	s_waitcnt vmcnt(2) lgkmcnt(0)
	s_barrier
	s_nop 5
	ds_read_b128 v[12:15], v134
	ds_read_b128 v[48:51], v152 offset:32768
	ds_read_b128 v[16:19], v134 offset:1024
	ds_read_b128 v[60:63], v152 offset:33792
	ds_read_b128 v[52:55], v134 offset:2048
	ds_read_b128 v[56:59], v134 offset:3072
	ds_read_b128 v[64:67], v152 offset:34816
	s_add_u32 s10, s20, 0x100
	s_addc_u32 s11, s21, 0
	s_mov_b32 m0, s39
	s_nop 0
	global_load_lds_dwordx4 v137, s[10:11]
	s_mov_b32 m0, s40
	s_nop 0
	global_load_lds_dwordx4 v139, s[10:11]
	s_waitcnt lgkmcnt(5)
	v_mfma_f32_16x16x32_bf16 v[68:71], v[12:15], v[48:51], v[68:71]
	ds_read_b128 v[214:217], v152 offset:35840
	s_waitcnt lgkmcnt(4)
	v_mfma_f32_16x16x32_bf16 v[128:131], v[16:19], v[60:63], v[68:71]
	s_waitcnt lgkmcnt(3)
	v_mfma_f32_16x16x32_bf16 v[68:71], v[52:55], v[48:51], v[72:75]
	s_waitcnt lgkmcnt(2)
	v_mfma_f32_16x16x32_bf16 v[124:127], v[56:59], v[60:63], v[68:71]
	ds_read_b128 v[218:221], v152 offset:36864
	s_waitcnt lgkmcnt(2)
	v_mfma_f32_16x16x32_bf16 v[68:71], v[12:15], v[64:67], v[76:79]
	ds_read_b128 v[222:225], v152 offset:37888
	s_waitcnt lgkmcnt(2)
	v_mfma_f32_16x16x32_bf16 v[112:115], v[16:19], v[214:217], v[68:71]
	v_mfma_f32_16x16x32_bf16 v[68:71], v[52:55], v[64:67], v[80:83]
	v_mfma_f32_16x16x32_bf16 v[108:111], v[56:59], v[214:217], v[68:71]
	ds_read_b128 v[226:229], v152 offset:38912
	s_waitcnt lgkmcnt(2)
	v_mfma_f32_16x16x32_bf16 v[68:71], v[12:15], v[218:221], v[84:87]
	ds_read_b128 v[230:233], v152 offset:39936
	s_waitcnt lgkmcnt(2)
	v_mfma_f32_16x16x32_bf16 v[96:99], v[16:19], v[222:225], v[68:71]
	v_mfma_f32_16x16x32_bf16 v[68:71], v[52:55], v[218:221], v[88:91]
	v_mfma_f32_16x16x32_bf16 v[92:95], v[56:59], v[222:225], v[68:71]
	ds_read_b128 v[242:245], v135 offset:2048
	s_waitcnt lgkmcnt(2)
	v_mfma_f32_16x16x32_bf16 v[68:71], v[12:15], v[226:229], v[100:103]
	ds_read_b128 v[234:237], v135
	s_waitcnt lgkmcnt(2)
	v_mfma_f32_16x16x32_bf16 v[80:83], v[16:19], v[230:233], v[68:71]
	ds_read_b128 v[246:249], v135 offset:3072
	v_mfma_f32_16x16x32_bf16 v[68:71], v[52:55], v[226:229], v[104:107]
	v_mfma_f32_16x16x32_bf16 v[76:79], v[56:59], v[230:233], v[68:71]
	s_add_u32 s10, s22, 0x100
	s_addc_u32 s11, s23, 0
	s_mov_b32 m0, s19
	s_nop 0
	global_load_lds_dwordx4 v136, s[10:11]
	s_mov_b32 m0, s41
	s_nop 0
	global_load_lds_dwordx4 v138, s[10:11]
	ds_read_b128 v[238:241], v135 offset:1024
	s_waitcnt lgkmcnt(3)
	v_mfma_f32_16x16x32_bf16 v[20:23], v[242:245], v[48:51], v[20:23]
	s_waitcnt lgkmcnt(2)
	v_mfma_f32_16x16x32_bf16 v[68:71], v[234:237], v[48:51], v[116:119]
	s_waitcnt lgkmcnt(1)
	v_mfma_f32_16x16x32_bf16 v[116:119], v[246:249], v[60:63], v[20:23]
	v_mfma_f32_16x16x32_bf16 v[20:23], v[234:237], v[64:67], v[24:27]
	s_waitcnt lgkmcnt(0)
	v_mfma_f32_16x16x32_bf16 v[104:107], v[238:241], v[214:217], v[20:23]
	v_mfma_f32_16x16x32_bf16 v[20:23], v[242:245], v[64:67], v[28:31]
	v_mfma_f32_16x16x32_bf16 v[100:103], v[246:249], v[214:217], v[20:23]
	v_mfma_f32_16x16x32_bf16 v[20:23], v[234:237], v[218:221], v[32:35]
	v_mfma_f32_16x16x32_bf16 v[88:91], v[238:241], v[222:225], v[20:23]
	v_mfma_f32_16x16x32_bf16 v[20:23], v[242:245], v[218:221], v[36:39]
	v_mfma_f32_16x16x32_bf16 v[84:87], v[246:249], v[222:225], v[20:23]
	v_mfma_f32_16x16x32_bf16 v[20:23], v[234:237], v[226:229], v[40:43]
	v_mfma_f32_16x16x32_bf16 v[72:75], v[238:241], v[230:233], v[20:23]
	v_mfma_f32_16x16x32_bf16 v[20:23], v[242:245], v[226:229], v[44:47]
	v_mfma_f32_16x16x32_bf16 v[120:123], v[238:241], v[60:63], v[68:71]
	v_mfma_f32_16x16x32_bf16 v[68:71], v[246:249], v[230:233], v[20:23]
	s_waitcnt vmcnt(4) lgkmcnt(0)
	s_barrier
; template <class Epi, class Sched>
; __device__ __forceinline__ void gemm_simple(PG8_LAS unsigned char* lds, const Gemm g, const Sched& S, const Epi& E, int wave_s) {
;     ...
;             PG8_TILE_W(1, cA + 2 * kstep, cB + 2 * kstep, "2", "4");
;             t = 2;
	s_nop 4
	ds_read_b128 v[20:23], v152 offset:49152
	ds_read_b128 v[24:27], v152 offset:50176
	ds_read_b128 v[36:39], v152 offset:51200
	s_add_u32 s10, s20, 0x40100
	s_addc_u32 s11, s21, 0
	s_mov_b32 m0, s42
	s_nop 0
	global_load_lds_dwordx4 v137, s[10:11]
	s_mov_b32 m0, s43
	s_nop 0
	global_load_lds_dwordx4 v139, s[10:11]
	s_waitcnt lgkmcnt(2)
	v_mfma_f32_16x16x32_bf16 v[28:31], v[12:15], v[20:23], v[146:149]
	ds_read_b128 v[214:217], v152 offset:52224
	s_waitcnt lgkmcnt(2)
	v_mfma_f32_16x16x32_bf16 v[64:67], v[16:19], v[24:27], v[28:31]
	v_mfma_f32_16x16x32_bf16 v[28:31], v[52:55], v[20:23], v[154:157]
	v_mfma_f32_16x16x32_bf16 v[60:63], v[56:59], v[24:27], v[28:31]
	ds_read_b128 v[218:221], v152 offset:53248
	s_waitcnt lgkmcnt(2)
	v_mfma_f32_16x16x32_bf16 v[28:31], v[12:15], v[36:39], v[158:161]
	ds_read_b128 v[226:229], v152 offset:55296
	s_waitcnt lgkmcnt(2)
	v_mfma_f32_16x16x32_bf16 v[48:51], v[16:19], v[214:217], v[28:31]
	ds_read_b128 v[222:225], v152 offset:54272
	v_mfma_f32_16x16x32_bf16 v[28:31], v[52:55], v[36:39], v[170:173]
	v_mfma_f32_16x16x32_bf16 v[44:47], v[56:59], v[214:217], v[28:31]
	ds_read_b128 v[230:233], v152 offset:56320
	s_waitcnt lgkmcnt(3)
	v_mfma_f32_16x16x32_bf16 v[28:31], v[12:15], v[218:221], v[174:177]
	s_waitcnt lgkmcnt(2)
	v_mfma_f32_16x16x32_bf16 v[4:7], v[12:15], v[226:229], v[4:7]
	s_waitcnt lgkmcnt(1)
	v_mfma_f32_16x16x32_bf16 v[32:35], v[16:19], v[222:225], v[28:31]
	v_mfma_f32_16x16x32_bf16 v[28:31], v[52:55], v[218:221], v[178:181]
	s_waitcnt lgkmcnt(0)
	v_mfma_f32_16x16x32_bf16 v[16:19], v[16:19], v[230:233], v[4:7]
	v_mfma_f32_16x16x32_bf16 v[4:7], v[52:55], v[226:229], v[8:11]
	v_mfma_f32_16x16x32_bf16 v[28:31], v[56:59], v[222:225], v[28:31]
	v_mfma_f32_16x16x32_bf16 v[12:15], v[56:59], v[230:233], v[4:7]
	s_add_u32 s10, s22, 0x40100
	s_addc_u32 s11, s23, 0
	s_mov_b32 m0, s44
	s_nop 0
	global_load_lds_dwordx4 v136, s[10:11]
	s_mov_b32 m0, s45
	s_nop 0
	global_load_lds_dwordx4 v138, s[10:11]
	v_mfma_f32_16x16x32_bf16 v[4:7], v[234:237], v[20:23], v[182:185]
	s_mov_b32 s24, 2
	v_mfma_f32_16x16x32_bf16 v[56:59], v[238:241], v[24:27], v[4:7]
	v_mfma_f32_16x16x32_bf16 v[4:7], v[242:245], v[20:23], v[186:189]
	v_mfma_f32_16x16x32_bf16 v[52:55], v[246:249], v[24:27], v[4:7]
	v_mfma_f32_16x16x32_bf16 v[4:7], v[234:237], v[36:39], v[190:193]
	v_mfma_f32_16x16x32_bf16 v[40:43], v[238:241], v[214:217], v[4:7]
	v_mfma_f32_16x16x32_bf16 v[4:7], v[242:245], v[36:39], v[194:197]
	v_mfma_f32_16x16x32_bf16 v[36:39], v[246:249], v[214:217], v[4:7]
	v_mfma_f32_16x16x32_bf16 v[4:7], v[234:237], v[218:221], v[198:201]
	v_mfma_f32_16x16x32_bf16 v[24:27], v[238:241], v[222:225], v[4:7]
	v_mfma_f32_16x16x32_bf16 v[4:7], v[242:245], v[218:221], v[202:205]
	v_mfma_f32_16x16x32_bf16 v[20:23], v[246:249], v[222:225], v[4:7]
	v_mfma_f32_16x16x32_bf16 v[4:7], v[234:237], v[226:229], v[206:209]
	v_mfma_f32_16x16x32_bf16 v[8:11], v[242:245], v[226:229], v[210:213]
	v_mfma_f32_16x16x32_bf16 v[4:7], v[238:241], v[230:233], v[4:7]
	v_mfma_f32_16x16x32_bf16 v[8:11], v[246:249], v[230:233], v[8:11]

; template <class Epi, class Sched>
; __device__ __forceinline__ void gemm_simple(PG8_LAS unsigned char* lds, const Gemm g, const Sched& S, const Epi& E, int wave_s) {
;     ...
;             if constexpr (Epi::NST >= 16) PG8_TILE_W(0, cA + kstep, cB + kstep, "18", "20"); else PG8_TILE_W(0, cA + kstep, cB + kstep, "10", "12");
.Lacc0_skip_195:
	v_cmp_lt_i64_e32 vcc, s[10:11], v[168:169]
	s_mov_b32 s22, 0
	s_cmp_eq_u32 s9, 0
	v_add_u32_e32 v132, 0x10000, v140
	v_add_u32_e32 v133, 0x14000, v140
	v_add_u32_e32 v134, 0x18000, v140
	v_add_u32_e32 v135, 0x1c000, v140
	s_cbranch_scc1 .LBB0_194
	s_waitcnt vmcnt(18) lgkmcnt(0)
	s_barrier
	ds_read_b128 v[4:7], v132
	ds_read_b128 v[44:47], v152 offset:6144
	ds_read_b128 v[20:23], v152
	ds_read_b128 v[12:15], v132 offset:2048
	ds_read_b128 v[28:31], v152 offset:2048
	s_add_u32 s10, s18, 0x80
	s_addc_u32 s11, s19, 0
	s_mov_b32 m0, s43
	s_nop 0
	global_load_lds_dwordx4 v137, s[10:11]
	s_mov_b32 m0, s47
	s_nop 0
	global_load_lds_dwordx4 v139, s[10:11]
	s_waitcnt lgkmcnt(3)
	v_mfma_f32_16x16x32_bf16 v[92:95], v[4:7], v[44:47], v[0:3]
	ds_read_b128 v[36:39], v152 offset:4096
	s_waitcnt lgkmcnt(3)
	v_mfma_f32_16x16x32_bf16 v[68:71], v[4:7], v[20:23], v[0:3]
	s_waitcnt lgkmcnt(2)
	v_mfma_f32_16x16x32_bf16 v[72:75], v[12:15], v[20:23], v[0:3]
	ds_read_b128 v[8:11], v132 offset:1024
	ds_read_b128 v[48:51], v152 offset:7168
	s_waitcnt lgkmcnt(3)
	v_mfma_f32_16x16x32_bf16 v[76:79], v[4:7], v[28:31], v[0:3]
	v_mfma_f32_16x16x32_bf16 v[80:83], v[12:15], v[28:31], v[0:3]
	ds_read_b128 v[24:27], v152 offset:1024
	s_waitcnt lgkmcnt(3)
	v_mfma_f32_16x16x32_bf16 v[84:87], v[4:7], v[36:39], v[0:3]
	ds_read_b128 v[16:19], v132 offset:3072
	v_mfma_f32_16x16x32_bf16 v[88:91], v[12:15], v[36:39], v[0:3]
	ds_read_b128 v[32:35], v152 offset:3072
	s_waitcnt lgkmcnt(3)
	v_mfma_f32_16x16x32_bf16 v[100:103], v[8:11], v[48:51], v[92:95]
	v_mfma_f32_16x16x32_bf16 v[92:95], v[12:15], v[44:47], v[0:3]
	ds_read_b128 v[40:43], v152 offset:5120
	s_waitcnt lgkmcnt(3)
	v_mfma_f32_16x16x32_bf16 v[68:71], v[8:11], v[24:27], v[68:71]
	s_waitcnt lgkmcnt(2)
	v_mfma_f32_16x16x32_bf16 v[72:75], v[16:19], v[24:27], v[72:75]
	s_waitcnt lgkmcnt(1)
	v_mfma_f32_16x16x32_bf16 v[76:79], v[8:11], v[32:35], v[76:79]
	ds_read_b128 v[52:55], v133
	v_mfma_f32_16x16x32_bf16 v[80:83], v[16:19], v[32:35], v[80:83]
	ds_read_b128 v[60:63], v133 offset:2048
	s_waitcnt lgkmcnt(2)
	v_mfma_f32_16x16x32_bf16 v[84:87], v[8:11], v[40:43], v[84:87]
	ds_read_b128 v[56:59], v133 offset:1024
	v_mfma_f32_16x16x32_bf16 v[88:91], v[16:19], v[40:43], v[88:91]
	ds_read_b128 v[64:67], v133 offset:3072
	v_mfma_f32_16x16x32_bf16 v[104:107], v[16:19], v[48:51], v[92:95]
	s_add_u32 s10, s20, 0x80
	s_addc_u32 s11, s21, 0
	s_mov_b32 m0, s44
	s_nop 0
	global_load_lds_dwordx4 v136, s[10:11]
	s_mov_b32 m0, s48
	s_nop 0
	global_load_lds_dwordx4 v138, s[10:11]
	s_waitcnt lgkmcnt(3)
	v_mfma_f32_16x16x32_bf16 v[92:95], v[52:55], v[20:23], v[0:3]
	s_waitcnt lgkmcnt(2)
	v_mfma_f32_16x16x32_bf16 v[20:23], v[60:63], v[20:23], v[0:3]
	s_waitcnt lgkmcnt(1)
	v_mfma_f32_16x16x32_bf16 v[116:119], v[56:59], v[24:27], v[92:95]
	s_waitcnt lgkmcnt(0)
	v_mfma_f32_16x16x32_bf16 v[20:23], v[64:67], v[24:27], v[20:23]
	v_mfma_f32_16x16x32_bf16 v[24:27], v[52:55], v[28:31], v[0:3]
	v_mfma_f32_16x16x32_bf16 v[28:31], v[60:63], v[28:31], v[0:3]
	v_mfma_f32_16x16x32_bf16 v[24:27], v[56:59], v[32:35], v[24:27]
	v_mfma_f32_16x16x32_bf16 v[28:31], v[64:67], v[32:35], v[28:31]
	v_mfma_f32_16x16x32_bf16 v[32:35], v[52:55], v[36:39], v[0:3]
	v_mfma_f32_16x16x32_bf16 v[36:39], v[60:63], v[36:39], v[0:3]
	v_mfma_f32_16x16x32_bf16 v[32:35], v[56:59], v[40:43], v[32:35]
	v_mfma_f32_16x16x32_bf16 v[36:39], v[64:67], v[40:43], v[36:39]
	v_mfma_f32_16x16x32_bf16 v[40:43], v[52:55], v[44:47], v[0:3]
	v_mfma_f32_16x16x32_bf16 v[44:47], v[60:63], v[44:47], v[0:3]
	v_mfma_f32_16x16x32_bf16 v[40:43], v[56:59], v[48:51], v[40:43]
	v_mfma_f32_16x16x32_bf16 v[44:47], v[64:67], v[48:51], v[44:47]
	s_waitcnt vmcnt(20) lgkmcnt(0)
	s_barrier
	ds_read_b128 v[48:51], v152 offset:16384
	ds_read_b128 v[96:99], v152 offset:18432
	ds_read_b128 v[112:115], v152 offset:20480
	ds_read_b128 v[124:127], v152 offset:22528
	ds_read_b128 v[92:95], v152 offset:17408
	s_add_u32 s10, s18, 0x20080
	s_addc_u32 s11, s19, 0
	s_mov_b32 m0, s45
	s_nop 0
	global_load_lds_dwordx4 v137, s[10:11]
	s_mov_b32 m0, s49
	s_nop 0
	global_load_lds_dwordx4 v139, s[10:11]
	s_waitcnt lgkmcnt(4)
	v_mfma_f32_16x16x32_bf16 v[146:149], v[4:7], v[48:51], v[0:3]
	ds_read_b128 v[108:111], v152 offset:19456
	s_waitcnt lgkmcnt(4)
	v_mfma_f32_16x16x32_bf16 v[158:161], v[4:7], v[96:99], v[0:3]
	ds_read_b128 v[120:123], v152 offset:21504
	s_waitcnt lgkmcnt(4)
	v_mfma_f32_16x16x32_bf16 v[174:177], v[4:7], v[112:115], v[0:3]
	ds_read_b128 v[128:131], v152 offset:23552
	s_waitcnt lgkmcnt(4)
	v_mfma_f32_16x16x32_bf16 v[4:7], v[4:7], v[124:127], v[0:3]
	s_waitcnt lgkmcnt(3)
	v_mfma_f32_16x16x32_bf16 v[146:149], v[8:11], v[92:95], v[146:149]
	s_waitcnt lgkmcnt(2)
	v_mfma_f32_16x16x32_bf16 v[158:161], v[8:11], v[108:111], v[158:161]
	s_waitcnt lgkmcnt(1)
	v_mfma_f32_16x16x32_bf16 v[174:177], v[8:11], v[120:123], v[174:177]
	s_waitcnt lgkmcnt(0)
	v_mfma_f32_16x16x32_bf16 v[4:7], v[8:11], v[128:131], v[4:7]
	v_mfma_f32_16x16x32_bf16 v[8:11], v[12:15], v[124:127], v[0:3]
	v_mfma_f32_16x16x32_bf16 v[154:157], v[12:15], v[48:51], v[0:3]
	v_mfma_f32_16x16x32_bf16 v[170:173], v[12:15], v[96:99], v[0:3]
	v_mfma_f32_16x16x32_bf16 v[178:181], v[12:15], v[112:115], v[0:3]
	v_mfma_f32_16x16x32_bf16 v[8:11], v[16:19], v[128:131], v[8:11]
	v_mfma_f32_16x16x32_bf16 v[154:157], v[16:19], v[92:95], v[154:157]
	v_mfma_f32_16x16x32_bf16 v[170:173], v[16:19], v[108:111], v[170:173]
	v_mfma_f32_16x16x32_bf16 v[178:181], v[16:19], v[120:123], v[178:181]
	s_add_u32 s10, s20, 0x20080
	s_addc_u32 s11, s21, 0
	s_mov_b32 m0, s46
	s_nop 0
	global_load_lds_dwordx4 v136, s[10:11]
	s_mov_b32 m0, s50
	s_nop 0
	global_load_lds_dwordx4 v138, s[10:11]
	v_mfma_f32_16x16x32_bf16 v[12:15], v[52:55], v[48:51], v[0:3]
	v_mfma_f32_16x16x32_bf16 v[182:185], v[56:59], v[92:95], v[12:15]
	v_mfma_f32_16x16x32_bf16 v[12:15], v[60:63], v[48:51], v[0:3]
	v_mfma_f32_16x16x32_bf16 v[186:189], v[64:67], v[92:95], v[12:15]
	v_mfma_f32_16x16x32_bf16 v[12:15], v[52:55], v[96:99], v[0:3]
	v_mfma_f32_16x16x32_bf16 v[190:193], v[56:59], v[108:111], v[12:15]
	v_mfma_f32_16x16x32_bf16 v[12:15], v[60:63], v[96:99], v[0:3]
	v_mfma_f32_16x16x32_bf16 v[194:197], v[64:67], v[108:111], v[12:15]
	v_mfma_f32_16x16x32_bf16 v[12:15], v[52:55], v[112:115], v[0:3]
	v_mfma_f32_16x16x32_bf16 v[198:201], v[56:59], v[120:123], v[12:15]
	v_mfma_f32_16x16x32_bf16 v[12:15], v[60:63], v[112:115], v[0:3]
	v_mfma_f32_16x16x32_bf16 v[202:205], v[64:67], v[120:123], v[12:15]
	v_mfma_f32_16x16x32_bf16 v[12:15], v[52:55], v[124:127], v[0:3]
	v_mfma_f32_16x16x32_bf16 v[206:209], v[56:59], v[128:131], v[12:15]
	v_mfma_f32_16x16x32_bf16 v[12:15], v[60:63], v[124:127], v[0:3]
	v_mfma_f32_16x16x32_bf16 v[210:213], v[64:67], v[128:131], v[12:15]
	s_waitcnt vmcnt(2) lgkmcnt(0)
	s_barrier
; template <class Epi, class Sched>
; __device__ __forceinline__ void gemm_simple(PG8_LAS unsigned char* lds, const Gemm g, const Sched& S, const Epi& E, int wave_s) {
;     ...
;             PG8_TILE_W(1, cA + 2 * kstep, cB + 2 * kstep, "2", "4");
	s_nop 5
	ds_read_b128 v[12:15], v134
	ds_read_b128 v[48:51], v152 offset:32768
	ds_read_b128 v[16:19], v134 offset:1024
	ds_read_b128 v[60:63], v152 offset:33792
	ds_read_b128 v[52:55], v134 offset:2048
	ds_read_b128 v[56:59], v134 offset:3072
	ds_read_b128 v[64:67], v152 offset:34816
	s_add_u32 s10, s18, 0x100
	s_addc_u32 s11, s19, 0
	s_mov_b32 m0, s36
	s_nop 0
	global_load_lds_dwordx4 v137, s[10:11]
	s_mov_b32 m0, s37
	s_nop 0
	global_load_lds_dwordx4 v139, s[10:11]
	s_waitcnt lgkmcnt(5)
	v_mfma_f32_16x16x32_bf16 v[68:71], v[12:15], v[48:51], v[68:71]
	ds_read_b128 v[214:217], v152 offset:35840
	s_waitcnt lgkmcnt(4)
	v_mfma_f32_16x16x32_bf16 v[128:131], v[16:19], v[60:63], v[68:71]
	s_waitcnt lgkmcnt(3)
	v_mfma_f32_16x16x32_bf16 v[68:71], v[52:55], v[48:51], v[72:75]
	s_waitcnt lgkmcnt(2)
	v_mfma_f32_16x16x32_bf16 v[124:127], v[56:59], v[60:63], v[68:71]
	ds_read_b128 v[218:221], v152 offset:36864
	s_waitcnt lgkmcnt(2)
	v_mfma_f32_16x16x32_bf16 v[68:71], v[12:15], v[64:67], v[76:79]
	ds_read_b128 v[222:225], v152 offset:37888
	s_waitcnt lgkmcnt(2)
	v_mfma_f32_16x16x32_bf16 v[112:115], v[16:19], v[214:217], v[68:71]
	v_mfma_f32_16x16x32_bf16 v[68:71], v[52:55], v[64:67], v[80:83]
	v_mfma_f32_16x16x32_bf16 v[108:111], v[56:59], v[214:217], v[68:71]
	ds_read_b128 v[226:229], v152 offset:38912
	s_waitcnt lgkmcnt(2)
	v_mfma_f32_16x16x32_bf16 v[68:71], v[12:15], v[218:221], v[84:87]
	ds_read_b128 v[230:233], v152 offset:39936
	s_waitcnt lgkmcnt(2)
	v_mfma_f32_16x16x32_bf16 v[96:99], v[16:19], v[222:225], v[68:71]
	v_mfma_f32_16x16x32_bf16 v[68:71], v[52:55], v[218:221], v[88:91]
	v_mfma_f32_16x16x32_bf16 v[92:95], v[56:59], v[222:225], v[68:71]
	ds_read_b128 v[242:245], v135 offset:2048
	s_waitcnt lgkmcnt(2)
	v_mfma_f32_16x16x32_bf16 v[68:71], v[12:15], v[226:229], v[100:103]
	ds_read_b128 v[234:237], v135
	s_waitcnt lgkmcnt(2)
	v_mfma_f32_16x16x32_bf16 v[80:83], v[16:19], v[230:233], v[68:71]
	ds_read_b128 v[246:249], v135 offset:3072
	v_mfma_f32_16x16x32_bf16 v[68:71], v[52:55], v[226:229], v[104:107]
	v_mfma_f32_16x16x32_bf16 v[76:79], v[56:59], v[230:233], v[68:71]
	s_add_u32 s10, s20, 0x100
	s_addc_u32 s11, s21, 0
	s_mov_b32 m0, s17
	s_nop 0
	global_load_lds_dwordx4 v136, s[10:11]
	s_mov_b32 m0, s38
	s_nop 0
	global_load_lds_dwordx4 v138, s[10:11]
	ds_read_b128 v[238:241], v135 offset:1024
	s_waitcnt lgkmcnt(3)
	v_mfma_f32_16x16x32_bf16 v[20:23], v[242:245], v[48:51], v[20:23]
	s_waitcnt lgkmcnt(2)
	v_mfma_f32_16x16x32_bf16 v[68:71], v[234:237], v[48:51], v[116:119]
	s_waitcnt lgkmcnt(1)
	v_mfma_f32_16x16x32_bf16 v[116:119], v[246:249], v[60:63], v[20:23]
	v_mfma_f32_16x16x32_bf16 v[20:23], v[234:237], v[64:67], v[24:27]
	s_waitcnt lgkmcnt(0)
	v_mfma_f32_16x16x32_bf16 v[104:107], v[238:241], v[214:217], v[20:23]
	v_mfma_f32_16x16x32_bf16 v[20:23], v[242:245], v[64:67], v[28:31]
	v_mfma_f32_16x16x32_bf16 v[100:103], v[246:249], v[214:217], v[20:23]
	v_mfma_f32_16x16x32_bf16 v[20:23], v[234:237], v[218:221], v[32:35]
	v_mfma_f32_16x16x32_bf16 v[88:91], v[238:241], v[222:225], v[20:23]
	v_mfma_f32_16x16x32_bf16 v[20:23], v[242:245], v[218:221], v[36:39]
	v_mfma_f32_16x16x32_bf16 v[84:87], v[246:249], v[222:225], v[20:23]
	v_mfma_f32_16x16x32_bf16 v[20:23], v[234:237], v[226:229], v[40:43]
	v_mfma_f32_16x16x32_bf16 v[72:75], v[238:241], v[230:233], v[20:23]
	v_mfma_f32_16x16x32_bf16 v[20:23], v[242:245], v[226:229], v[44:47]
	v_mfma_f32_16x16x32_bf16 v[120:123], v[238:241], v[60:63], v[68:71]
	v_mfma_f32_16x16x32_bf16 v[68:71], v[246:249], v[230:233], v[20:23]
	s_waitcnt vmcnt(4) lgkmcnt(0)
	s_barrier
	s_nop 4
	ds_read_b128 v[20:23], v152 offset:49152
	ds_read_b128 v[24:27], v152 offset:50176
	ds_read_b128 v[36:39], v152 offset:51200
	s_add_u32 s10, s18, 0x20100
	s_addc_u32 s11, s19, 0
	s_mov_b32 m0, s39
	s_nop 0
	global_load_lds_dwordx4 v137, s[10:11]
	s_mov_b32 m0, s40
	s_nop 0
	global_load_lds_dwordx4 v139, s[10:11]
	s_waitcnt lgkmcnt(2)
	v_mfma_f32_16x16x32_bf16 v[28:31], v[12:15], v[20:23], v[146:149]
	ds_read_b128 v[214:217], v152 offset:52224
	s_waitcnt lgkmcnt(2)
	v_mfma_f32_16x16x32_bf16 v[64:67], v[16:19], v[24:27], v[28:31]
	v_mfma_f32_16x16x32_bf16 v[28:31], v[52:55], v[20:23], v[154:157]
	v_mfma_f32_16x16x32_bf16 v[60:63], v[56:59], v[24:27], v[28:31]
	ds_read_b128 v[218:221], v152 offset:53248
	s_waitcnt lgkmcnt(2)
	v_mfma_f32_16x16x32_bf16 v[28:31], v[12:15], v[36:39], v[158:161]
	ds_read_b128 v[226:229], v152 offset:55296
	s_waitcnt lgkmcnt(2)
	v_mfma_f32_16x16x32_bf16 v[48:51], v[16:19], v[214:217], v[28:31]
	ds_read_b128 v[222:225], v152 offset:54272
	v_mfma_f32_16x16x32_bf16 v[28:31], v[52:55], v[36:39], v[170:173]
	v_mfma_f32_16x16x32_bf16 v[44:47], v[56:59], v[214:217], v[28:31]
	ds_read_b128 v[230:233], v152 offset:56320
	s_waitcnt lgkmcnt(3)
	v_mfma_f32_16x16x32_bf16 v[28:31], v[12:15], v[218:221], v[174:177]
	s_waitcnt lgkmcnt(2)
	v_mfma_f32_16x16x32_bf16 v[4:7], v[12:15], v[226:229], v[4:7]
	s_waitcnt lgkmcnt(1)
	v_mfma_f32_16x16x32_bf16 v[32:35], v[16:19], v[222:225], v[28:31]
	v_mfma_f32_16x16x32_bf16 v[28:31], v[52:55], v[218:221], v[178:181]
	s_waitcnt lgkmcnt(0)
	v_mfma_f32_16x16x32_bf16 v[16:19], v[16:19], v[230:233], v[4:7]
	v_mfma_f32_16x16x32_bf16 v[4:7], v[52:55], v[226:229], v[8:11]
	v_mfma_f32_16x16x32_bf16 v[28:31], v[56:59], v[222:225], v[28:31]
	v_mfma_f32_16x16x32_bf16 v[12:15], v[56:59], v[230:233], v[4:7]
	s_add_u32 s10, s20, 0x20100
	s_addc_u32 s11, s21, 0
	s_mov_b32 m0, s41
	s_nop 0
	global_load_lds_dwordx4 v136, s[10:11]
	s_mov_b32 m0, s42
	s_nop 0
	global_load_lds_dwordx4 v138, s[10:11]
	v_mfma_f32_16x16x32_bf16 v[4:7], v[234:237], v[20:23], v[182:185]
	s_mov_b32 s22, 2
	v_mfma_f32_16x16x32_bf16 v[56:59], v[238:241], v[24:27], v[4:7]
	v_mfma_f32_16x16x32_bf16 v[4:7], v[242:245], v[20:23], v[186:189]
	v_mfma_f32_16x16x32_bf16 v[52:55], v[246:249], v[24:27], v[4:7]
	v_mfma_f32_16x16x32_bf16 v[4:7], v[234:237], v[36:39], v[190:193]
	v_mfma_f32_16x16x32_bf16 v[40:43], v[238:241], v[214:217], v[4:7]
	v_mfma_f32_16x16x32_bf16 v[4:7], v[242:245], v[36:39], v[194:197]
	v_mfma_f32_16x16x32_bf16 v[36:39], v[246:249], v[214:217], v[4:7]
	v_mfma_f32_16x16x32_bf16 v[4:7], v[234:237], v[218:221], v[198:201]
	v_mfma_f32_16x16x32_bf16 v[24:27], v[238:241], v[222:225], v[4:7]
	v_mfma_f32_16x16x32_bf16 v[4:7], v[242:245], v[218:221], v[202:205]
	v_mfma_f32_16x16x32_bf16 v[20:23], v[246:249], v[222:225], v[4:7]
	v_mfma_f32_16x16x32_bf16 v[4:7], v[234:237], v[226:229], v[206:209]
	v_mfma_f32_16x16x32_bf16 v[8:11], v[242:245], v[226:229], v[210:213]
	v_mfma_f32_16x16x32_bf16 v[4:7], v[238:241], v[230:233], v[4:7]
	v_mfma_f32_16x16x32_bf16 v[8:11], v[246:249], v[230:233], v[8:11]

; template <class Epi, class Sched>
; __device__ __forceinline__ void gemm_simple(PG8_LAS unsigned char* lds, const Gemm g, const Sched& S, const Epi& E, int wave_s) {
;     ...
; #pragma unroll
;         for (int a = 0; a < 2; ++a)
; #pragma unroll
;             for (int b = 0; b < 2; ++b)
; #pragma unroll
;                 for (int m = 0; m < 4; ++m)
; #pragma unroll
;                     for (int n = 0; n < 2; ++n) acc[a][b][m][n] = (f32x4){zero_o, zero_o, zero_o, zero_o};
.LBB0_218:
	s_cmp_lg_u32 s55, 0
	s_cbranch_scc1 .Lacc0_skip_221
	v_mov_b64_e32 v[10:11], v[2:3]
	v_mov_b64_e32 v[6:7], v[2:3]
	v_mov_b64_e32 v[22:23], v[2:3]
	v_mov_b64_e32 v[26:27], v[2:3]
	v_mov_b64_e32 v[38:39], v[2:3]
	v_mov_b64_e32 v[42:43], v[2:3]
	v_mov_b64_e32 v[54:55], v[2:3]
	v_mov_b64_e32 v[58:59], v[2:3]
	v_mov_b64_e32 v[14:15], v[2:3]
	v_mov_b64_e32 v[18:19], v[2:3]
	v_mov_b64_e32 v[30:31], v[2:3]
	v_mov_b64_e32 v[34:35], v[2:3]
	v_mov_b64_e32 v[46:47], v[2:3]
	v_mov_b64_e32 v[50:51], v[2:3]
	v_mov_b64_e32 v[62:63], v[2:3]
	v_mov_b64_e32 v[66:67], v[2:3]
	v_mov_b64_e32 v[70:71], v[2:3]
	v_mov_b64_e32 v[74:75], v[2:3]
	v_mov_b64_e32 v[86:87], v[2:3]
	v_mov_b64_e32 v[90:91], v[2:3]
	v_mov_b64_e32 v[102:103], v[2:3]
	v_mov_b64_e32 v[106:107], v[2:3]
	v_mov_b64_e32 v[118:119], v[2:3]
	v_mov_b64_e32 v[122:123], v[2:3]
	v_mov_b64_e32 v[78:79], v[2:3]
	v_mov_b64_e32 v[82:83], v[2:3]
	v_mov_b64_e32 v[94:95], v[2:3]
	v_mov_b64_e32 v[98:99], v[2:3]
	v_mov_b64_e32 v[110:111], v[2:3]
	v_mov_b64_e32 v[114:115], v[2:3]
	v_mov_b64_e32 v[126:127], v[2:3]
	v_mov_b64_e32 v[130:131], v[2:3]
	v_mov_b64_e32 v[8:9], v[0:1]
	v_mov_b64_e32 v[4:5], v[0:1]
	v_mov_b64_e32 v[20:21], v[0:1]
	v_mov_b64_e32 v[24:25], v[0:1]
	v_mov_b64_e32 v[36:37], v[0:1]
	v_mov_b64_e32 v[40:41], v[0:1]
	v_mov_b64_e32 v[52:53], v[0:1]
	v_mov_b64_e32 v[56:57], v[0:1]
	v_mov_b64_e32 v[12:13], v[0:1]
	v_mov_b64_e32 v[16:17], v[0:1]
	v_mov_b64_e32 v[28:29], v[0:1]
	v_mov_b64_e32 v[32:33], v[0:1]
	v_mov_b64_e32 v[44:45], v[0:1]
	v_mov_b64_e32 v[48:49], v[0:1]
	v_mov_b64_e32 v[60:61], v[0:1]
	v_mov_b64_e32 v[64:65], v[0:1]
	v_mov_b64_e32 v[68:69], v[0:1]
	v_mov_b64_e32 v[72:73], v[0:1]
	v_mov_b64_e32 v[84:85], v[0:1]
	v_mov_b64_e32 v[88:89], v[0:1]
	v_mov_b64_e32 v[100:101], v[0:1]
	v_mov_b64_e32 v[104:105], v[0:1]
	v_mov_b64_e32 v[116:117], v[0:1]
	v_mov_b64_e32 v[120:121], v[0:1]
	v_mov_b64_e32 v[76:77], v[0:1]
	v_mov_b64_e32 v[80:81], v[0:1]
	v_mov_b64_e32 v[92:93], v[0:1]
	v_mov_b64_e32 v[96:97], v[0:1]
	v_mov_b64_e32 v[108:109], v[0:1]
	v_mov_b64_e32 v[112:113], v[0:1]
	v_mov_b64_e32 v[124:125], v[0:1]
	v_mov_b64_e32 v[128:129], v[0:1]
.Lacc0_skip_221:
	s_mov_b32 s22, 0
	s_cmp_eq_u32 s55, 0
	v_add_u32_e32 v132, 0x10000, v155
	v_add_u32_e32 v133, 0x14000, v155
	v_add_u32_e32 v134, 0x18000, v155
	v_add_u32_e32 v135, 0x1c000, v155
	s_cbranch_scc1 .LBB0_220
	s_waitcnt vmcnt(18) lgkmcnt(0)
	s_barrier
	ds_read_b128 v[4:7], v132
	ds_read_b128 v[44:47], v156 offset:6144
	ds_read_b128 v[20:23], v156
	ds_read_b128 v[12:15], v132 offset:2048
	ds_read_b128 v[28:31], v156 offset:2048
	s_add_u32 s14, s10, 0x80
	s_addc_u32 s15, s11, 0
	s_mov_b32 m0, s44
	s_nop 0
	global_load_lds_dwordx4 v140, s[14:15]
	s_mov_b32 m0, s48
	s_nop 0
	global_load_lds_dwordx4 v153, s[14:15]
	s_waitcnt lgkmcnt(3)
	v_mfma_f32_16x16x32_bf16 v[92:95], v[4:7], v[44:47], v[0:3]
	ds_read_b128 v[36:39], v156 offset:4096
	s_waitcnt lgkmcnt(3)
	v_mfma_f32_16x16x32_bf16 v[68:71], v[4:7], v[20:23], v[0:3]
	s_waitcnt lgkmcnt(2)
	v_mfma_f32_16x16x32_bf16 v[72:75], v[12:15], v[20:23], v[0:3]
	ds_read_b128 v[8:11], v132 offset:1024
	ds_read_b128 v[48:51], v156 offset:7168
	s_waitcnt lgkmcnt(3)
	v_mfma_f32_16x16x32_bf16 v[76:79], v[4:7], v[28:31], v[0:3]
	v_mfma_f32_16x16x32_bf16 v[80:83], v[12:15], v[28:31], v[0:3]
	ds_read_b128 v[24:27], v156 offset:1024
	s_waitcnt lgkmcnt(3)
	v_mfma_f32_16x16x32_bf16 v[84:87], v[4:7], v[36:39], v[0:3]
	ds_read_b128 v[16:19], v132 offset:3072
	v_mfma_f32_16x16x32_bf16 v[88:91], v[12:15], v[36:39], v[0:3]
	ds_read_b128 v[32:35], v156 offset:3072
	s_waitcnt lgkmcnt(3)
	v_mfma_f32_16x16x32_bf16 v[100:103], v[8:11], v[48:51], v[92:95]
	v_mfma_f32_16x16x32_bf16 v[92:95], v[12:15], v[44:47], v[0:3]
	ds_read_b128 v[40:43], v156 offset:5120
	s_waitcnt lgkmcnt(3)
	v_mfma_f32_16x16x32_bf16 v[68:71], v[8:11], v[24:27], v[68:71]
	s_waitcnt lgkmcnt(2)
	v_mfma_f32_16x16x32_bf16 v[72:75], v[16:19], v[24:27], v[72:75]
	s_waitcnt lgkmcnt(1)
	v_mfma_f32_16x16x32_bf16 v[76:79], v[8:11], v[32:35], v[76:79]
	ds_read_b128 v[52:55], v133
	v_mfma_f32_16x16x32_bf16 v[80:83], v[16:19], v[32:35], v[80:83]
	ds_read_b128 v[60:63], v133 offset:2048
	s_waitcnt lgkmcnt(2)
	v_mfma_f32_16x16x32_bf16 v[84:87], v[8:11], v[40:43], v[84:87]
	ds_read_b128 v[56:59], v133 offset:1024
	v_mfma_f32_16x16x32_bf16 v[88:91], v[16:19], v[40:43], v[88:91]
	ds_read_b128 v[64:67], v133 offset:3072
	v_mfma_f32_16x16x32_bf16 v[104:107], v[16:19], v[48:51], v[92:95]
	s_add_u32 s14, s20, 0x80
	s_addc_u32 s15, s21, 0
	s_mov_b32 m0, s45
	s_nop 0
	global_load_lds_dwordx4 v139, s[14:15]
	s_mov_b32 m0, s49
	s_nop 0
	global_load_lds_dwordx4 v152, s[14:15]
	s_waitcnt lgkmcnt(3)
	v_mfma_f32_16x16x32_bf16 v[92:95], v[52:55], v[20:23], v[0:3]
	s_waitcnt lgkmcnt(2)
	v_mfma_f32_16x16x32_bf16 v[20:23], v[60:63], v[20:23], v[0:3]
	s_waitcnt lgkmcnt(1)
	v_mfma_f32_16x16x32_bf16 v[116:119], v[56:59], v[24:27], v[92:95]
	s_waitcnt lgkmcnt(0)
	v_mfma_f32_16x16x32_bf16 v[20:23], v[64:67], v[24:27], v[20:23]
	v_mfma_f32_16x16x32_bf16 v[24:27], v[52:55], v[28:31], v[0:3]
	v_mfma_f32_16x16x32_bf16 v[28:31], v[60:63], v[28:31], v[0:3]
	v_mfma_f32_16x16x32_bf16 v[24:27], v[56:59], v[32:35], v[24:27]
	v_mfma_f32_16x16x32_bf16 v[28:31], v[64:67], v[32:35], v[28:31]
	v_mfma_f32_16x16x32_bf16 v[32:35], v[52:55], v[36:39], v[0:3]
	v_mfma_f32_16x16x32_bf16 v[36:39], v[60:63], v[36:39], v[0:3]
	v_mfma_f32_16x16x32_bf16 v[32:35], v[56:59], v[40:43], v[32:35]
	v_mfma_f32_16x16x32_bf16 v[36:39], v[64:67], v[40:43], v[36:39]
	v_mfma_f32_16x16x32_bf16 v[40:43], v[52:55], v[44:47], v[0:3]
	v_mfma_f32_16x16x32_bf16 v[44:47], v[60:63], v[44:47], v[0:3]
	v_mfma_f32_16x16x32_bf16 v[40:43], v[56:59], v[48:51], v[40:43]
	v_mfma_f32_16x16x32_bf16 v[44:47], v[64:67], v[48:51], v[44:47]
	s_waitcnt vmcnt(20) lgkmcnt(0)
	s_barrier
; template <class Epi, class Sched>
; __device__ __forceinline__ void gemm_simple(PG8_LAS unsigned char* lds, const Gemm g, const Sched& S, const Epi& E, int wave_s) {
;     ...
;             if constexpr (Epi::NST >= 16) PG8_TILE_W(0, cA + kstep, cB + kstep, "18", "20"); else PG8_TILE_W(0, cA + kstep, cB + kstep, "10", "12");
;             PG8_TILE_W(1, cA + 2 * kstep, cB + 2 * kstep, "2", "4");
	ds_read_b128 v[48:51], v156 offset:16384
	ds_read_b128 v[96:99], v156 offset:18432
	ds_read_b128 v[112:115], v156 offset:20480
	ds_read_b128 v[124:127], v156 offset:22528
	ds_read_b128 v[92:95], v156 offset:17408
	s_add_u32 s14, s10, 0x80080
	s_addc_u32 s15, s11, 0
	s_mov_b32 m0, s46
	s_nop 0
	global_load_lds_dwordx4 v140, s[14:15]
	s_mov_b32 m0, s50
	s_nop 0
	global_load_lds_dwordx4 v153, s[14:15]
	s_waitcnt lgkmcnt(4)
	v_mfma_f32_16x16x32_bf16 v[158:161], v[4:7], v[48:51], v[0:3]
	ds_read_b128 v[108:111], v156 offset:19456
	s_waitcnt lgkmcnt(4)
	v_mfma_f32_16x16x32_bf16 v[174:177], v[4:7], v[96:99], v[0:3]
	ds_read_b128 v[120:123], v156 offset:21504
	s_waitcnt lgkmcnt(4)
	v_mfma_f32_16x16x32_bf16 v[182:185], v[4:7], v[112:115], v[0:3]
	ds_read_b128 v[128:131], v156 offset:23552
	s_waitcnt lgkmcnt(4)
	v_mfma_f32_16x16x32_bf16 v[4:7], v[4:7], v[124:127], v[0:3]
	s_waitcnt lgkmcnt(3)
	v_mfma_f32_16x16x32_bf16 v[158:161], v[8:11], v[92:95], v[158:161]
	s_waitcnt lgkmcnt(2)
	v_mfma_f32_16x16x32_bf16 v[174:177], v[8:11], v[108:111], v[174:177]
	s_waitcnt lgkmcnt(1)
	v_mfma_f32_16x16x32_bf16 v[182:185], v[8:11], v[120:123], v[182:185]
	s_waitcnt lgkmcnt(0)
	v_mfma_f32_16x16x32_bf16 v[4:7], v[8:11], v[128:131], v[4:7]
	v_mfma_f32_16x16x32_bf16 v[8:11], v[12:15], v[124:127], v[0:3]
	v_mfma_f32_16x16x32_bf16 v[170:173], v[12:15], v[48:51], v[0:3]
	v_mfma_f32_16x16x32_bf16 v[178:181], v[12:15], v[96:99], v[0:3]
	v_mfma_f32_16x16x32_bf16 v[186:189], v[12:15], v[112:115], v[0:3]
	v_mfma_f32_16x16x32_bf16 v[8:11], v[16:19], v[128:131], v[8:11]
	v_mfma_f32_16x16x32_bf16 v[170:173], v[16:19], v[92:95], v[170:173]
	v_mfma_f32_16x16x32_bf16 v[178:181], v[16:19], v[108:111], v[178:181]
	v_mfma_f32_16x16x32_bf16 v[186:189], v[16:19], v[120:123], v[186:189]
	s_add_u32 s14, s20, 0x80080
	s_addc_u32 s15, s21, 0
	s_mov_b32 m0, s47
	s_nop 0
	global_load_lds_dwordx4 v139, s[14:15]
	s_mov_b32 m0, s51
	s_nop 0
	global_load_lds_dwordx4 v152, s[14:15]
	v_mfma_f32_16x16x32_bf16 v[12:15], v[52:55], v[48:51], v[0:3]
	v_mfma_f32_16x16x32_bf16 v[190:193], v[56:59], v[92:95], v[12:15]
	v_mfma_f32_16x16x32_bf16 v[12:15], v[60:63], v[48:51], v[0:3]
	v_mfma_f32_16x16x32_bf16 v[194:197], v[64:67], v[92:95], v[12:15]
	v_mfma_f32_16x16x32_bf16 v[12:15], v[52:55], v[96:99], v[0:3]
	v_mfma_f32_16x16x32_bf16 v[198:201], v[56:59], v[108:111], v[12:15]
	v_mfma_f32_16x16x32_bf16 v[12:15], v[60:63], v[96:99], v[0:3]
	v_mfma_f32_16x16x32_bf16 v[202:205], v[64:67], v[108:111], v[12:15]
	v_mfma_f32_16x16x32_bf16 v[12:15], v[52:55], v[112:115], v[0:3]
	v_mfma_f32_16x16x32_bf16 v[206:209], v[56:59], v[120:123], v[12:15]
	v_mfma_f32_16x16x32_bf16 v[12:15], v[60:63], v[112:115], v[0:3]
	v_mfma_f32_16x16x32_bf16 v[210:213], v[64:67], v[120:123], v[12:15]
	v_mfma_f32_16x16x32_bf16 v[12:15], v[52:55], v[124:127], v[0:3]
	v_mfma_f32_16x16x32_bf16 v[214:217], v[56:59], v[128:131], v[12:15]
	v_mfma_f32_16x16x32_bf16 v[12:15], v[60:63], v[124:127], v[0:3]
	v_mfma_f32_16x16x32_bf16 v[218:221], v[64:67], v[128:131], v[12:15]
	s_waitcnt vmcnt(2) lgkmcnt(0)
	s_barrier
	s_nop 5
	ds_read_b128 v[12:15], v134
	ds_read_b128 v[48:51], v156 offset:32768
	ds_read_b128 v[16:19], v134 offset:1024
	ds_read_b128 v[60:63], v156 offset:33792
	ds_read_b128 v[52:55], v134 offset:2048
	ds_read_b128 v[56:59], v134 offset:3072
	ds_read_b128 v[64:67], v156 offset:34816
	s_add_u32 s14, s10, 0x100
	s_addc_u32 s15, s11, 0
	s_mov_b32 m0, s29
	s_nop 0
	global_load_lds_dwordx4 v140, s[14:15]
	s_mov_b32 m0, s35
	s_nop 0
	global_load_lds_dwordx4 v153, s[14:15]
	s_waitcnt lgkmcnt(5)
	v_mfma_f32_16x16x32_bf16 v[68:71], v[12:15], v[48:51], v[68:71]
	ds_read_b128 v[222:225], v156 offset:35840
	s_waitcnt lgkmcnt(4)
	v_mfma_f32_16x16x32_bf16 v[128:131], v[16:19], v[60:63], v[68:71]
	s_waitcnt lgkmcnt(3)
	v_mfma_f32_16x16x32_bf16 v[68:71], v[52:55], v[48:51], v[72:75]
	s_waitcnt lgkmcnt(2)
	v_mfma_f32_16x16x32_bf16 v[124:127], v[56:59], v[60:63], v[68:71]
	ds_read_b128 v[226:229], v156 offset:36864
	s_waitcnt lgkmcnt(2)
	v_mfma_f32_16x16x32_bf16 v[68:71], v[12:15], v[64:67], v[76:79]
	ds_read_b128 v[230:233], v156 offset:37888
	s_waitcnt lgkmcnt(2)
	v_mfma_f32_16x16x32_bf16 v[112:115], v[16:19], v[222:225], v[68:71]
	v_mfma_f32_16x16x32_bf16 v[68:71], v[52:55], v[64:67], v[80:83]
	v_mfma_f32_16x16x32_bf16 v[108:111], v[56:59], v[222:225], v[68:71]
	ds_read_b128 v[234:237], v156 offset:38912
	s_waitcnt lgkmcnt(2)
	v_mfma_f32_16x16x32_bf16 v[68:71], v[12:15], v[226:229], v[84:87]
	ds_read_b128 v[238:241], v156 offset:39936
	s_waitcnt lgkmcnt(2)
	v_mfma_f32_16x16x32_bf16 v[96:99], v[16:19], v[230:233], v[68:71]
	v_mfma_f32_16x16x32_bf16 v[68:71], v[52:55], v[226:229], v[88:91]
	v_mfma_f32_16x16x32_bf16 v[92:95], v[56:59], v[230:233], v[68:71]
	ds_read_b128 v[250:253], v135 offset:2048
	s_waitcnt lgkmcnt(2)
	v_mfma_f32_16x16x32_bf16 v[68:71], v[12:15], v[234:237], v[100:103]
	ds_read_b128 v[242:245], v135
	s_waitcnt lgkmcnt(2)
	v_mfma_f32_16x16x32_bf16 v[80:83], v[16:19], v[238:241], v[68:71]
	ds_read_b128 v[146:149], v135 offset:3072
	v_mfma_f32_16x16x32_bf16 v[68:71], v[52:55], v[234:237], v[104:107]
	v_mfma_f32_16x16x32_bf16 v[76:79], v[56:59], v[238:241], v[68:71]
	s_add_u32 s14, s20, 0x100
	s_addc_u32 s15, s21, 0
	s_mov_b32 m0, s19
	s_nop 0
	global_load_lds_dwordx4 v139, s[14:15]
	s_mov_b32 m0, s36
	s_nop 0
	global_load_lds_dwordx4 v152, s[14:15]
	ds_read_b128 v[246:249], v135 offset:1024
	s_waitcnt lgkmcnt(3)
	v_mfma_f32_16x16x32_bf16 v[20:23], v[250:253], v[48:51], v[20:23]
	s_waitcnt lgkmcnt(2)
	v_mfma_f32_16x16x32_bf16 v[68:71], v[242:245], v[48:51], v[116:119]
	s_waitcnt lgkmcnt(1)
	v_mfma_f32_16x16x32_bf16 v[116:119], v[146:149], v[60:63], v[20:23]
	v_mfma_f32_16x16x32_bf16 v[20:23], v[242:245], v[64:67], v[24:27]
	s_waitcnt lgkmcnt(0)
	v_mfma_f32_16x16x32_bf16 v[104:107], v[246:249], v[222:225], v[20:23]
	v_mfma_f32_16x16x32_bf16 v[20:23], v[250:253], v[64:67], v[28:31]
	v_mfma_f32_16x16x32_bf16 v[100:103], v[146:149], v[222:225], v[20:23]
	v_mfma_f32_16x16x32_bf16 v[20:23], v[242:245], v[226:229], v[32:35]
	v_mfma_f32_16x16x32_bf16 v[88:91], v[246:249], v[230:233], v[20:23]
	v_mfma_f32_16x16x32_bf16 v[20:23], v[250:253], v[226:229], v[36:39]
	v_mfma_f32_16x16x32_bf16 v[84:87], v[146:149], v[230:233], v[20:23]
	v_mfma_f32_16x16x32_bf16 v[20:23], v[242:245], v[234:237], v[40:43]
	v_mfma_f32_16x16x32_bf16 v[72:75], v[246:249], v[238:241], v[20:23]
	v_mfma_f32_16x16x32_bf16 v[20:23], v[250:253], v[234:237], v[44:47]
	v_mfma_f32_16x16x32_bf16 v[120:123], v[246:249], v[60:63], v[68:71]
	v_mfma_f32_16x16x32_bf16 v[68:71], v[146:149], v[238:241], v[20:23]
	s_waitcnt vmcnt(4) lgkmcnt(0)
	s_barrier
; template <class Epi, class Sched>
; __device__ __forceinline__ void gemm_simple(PG8_LAS unsigned char* lds, const Gemm g, const Sched& S, const Epi& E, int wave_s) {
;     ...
;             PG8_TILE_W(1, cA + 2 * kstep, cB + 2 * kstep, "2", "4");
;             t = 2;
	s_nop 4
	ds_read_b128 v[20:23], v156 offset:49152
	ds_read_b128 v[24:27], v156 offset:50176
	ds_read_b128 v[36:39], v156 offset:51200
	s_add_u32 s14, s10, 0x80100
	s_addc_u32 s15, s11, 0
	s_mov_b32 m0, s37
	s_nop 0
	global_load_lds_dwordx4 v140, s[14:15]
	s_mov_b32 m0, s38
	s_nop 0
	global_load_lds_dwordx4 v153, s[14:15]
	s_waitcnt lgkmcnt(2)
	v_mfma_f32_16x16x32_bf16 v[28:31], v[12:15], v[20:23], v[158:161]
	ds_read_b128 v[222:225], v156 offset:52224
	s_waitcnt lgkmcnt(2)
	v_mfma_f32_16x16x32_bf16 v[64:67], v[16:19], v[24:27], v[28:31]
	v_mfma_f32_16x16x32_bf16 v[28:31], v[52:55], v[20:23], v[170:173]
	v_mfma_f32_16x16x32_bf16 v[60:63], v[56:59], v[24:27], v[28:31]
	ds_read_b128 v[226:229], v156 offset:53248
	s_waitcnt lgkmcnt(2)
	v_mfma_f32_16x16x32_bf16 v[28:31], v[12:15], v[36:39], v[174:177]
	ds_read_b128 v[234:237], v156 offset:55296
	s_waitcnt lgkmcnt(2)
	v_mfma_f32_16x16x32_bf16 v[48:51], v[16:19], v[222:225], v[28:31]
	ds_read_b128 v[230:233], v156 offset:54272
	v_mfma_f32_16x16x32_bf16 v[28:31], v[52:55], v[36:39], v[178:181]
	v_mfma_f32_16x16x32_bf16 v[44:47], v[56:59], v[222:225], v[28:31]
	ds_read_b128 v[238:241], v156 offset:56320
	s_waitcnt lgkmcnt(3)
	v_mfma_f32_16x16x32_bf16 v[28:31], v[12:15], v[226:229], v[182:185]
	s_waitcnt lgkmcnt(2)
	v_mfma_f32_16x16x32_bf16 v[4:7], v[12:15], v[234:237], v[4:7]
	s_waitcnt lgkmcnt(1)
	v_mfma_f32_16x16x32_bf16 v[32:35], v[16:19], v[230:233], v[28:31]
	v_mfma_f32_16x16x32_bf16 v[28:31], v[52:55], v[226:229], v[186:189]
	s_waitcnt lgkmcnt(0)
	v_mfma_f32_16x16x32_bf16 v[16:19], v[16:19], v[238:241], v[4:7]
	v_mfma_f32_16x16x32_bf16 v[4:7], v[52:55], v[234:237], v[8:11]
	v_mfma_f32_16x16x32_bf16 v[28:31], v[56:59], v[230:233], v[28:31]
	v_mfma_f32_16x16x32_bf16 v[12:15], v[56:59], v[238:241], v[4:7]
	s_add_u32 s14, s20, 0x80100
	s_addc_u32 s15, s21, 0
	s_mov_b32 m0, s39
	s_nop 0
	global_load_lds_dwordx4 v139, s[14:15]
	s_mov_b32 m0, s40
	s_nop 0
	global_load_lds_dwordx4 v152, s[14:15]
	v_mfma_f32_16x16x32_bf16 v[4:7], v[242:245], v[20:23], v[190:193]
	s_mov_b32 s22, 2
	v_mfma_f32_16x16x32_bf16 v[56:59], v[246:249], v[24:27], v[4:7]
	v_mfma_f32_16x16x32_bf16 v[4:7], v[250:253], v[20:23], v[194:197]
	v_mfma_f32_16x16x32_bf16 v[52:55], v[146:149], v[24:27], v[4:7]
	v_mfma_f32_16x16x32_bf16 v[4:7], v[242:245], v[36:39], v[198:201]
	v_mfma_f32_16x16x32_bf16 v[40:43], v[246:249], v[222:225], v[4:7]
	v_mfma_f32_16x16x32_bf16 v[4:7], v[250:253], v[36:39], v[202:205]
	v_mfma_f32_16x16x32_bf16 v[36:39], v[146:149], v[222:225], v[4:7]
	v_mfma_f32_16x16x32_bf16 v[4:7], v[242:245], v[226:229], v[206:209]
	v_mfma_f32_16x16x32_bf16 v[24:27], v[246:249], v[230:233], v[4:7]
	v_mfma_f32_16x16x32_bf16 v[4:7], v[250:253], v[226:229], v[210:213]
	v_mfma_f32_16x16x32_bf16 v[20:23], v[146:149], v[230:233], v[4:7]
	v_mfma_f32_16x16x32_bf16 v[4:7], v[242:245], v[234:237], v[214:217]
	v_mfma_f32_16x16x32_bf16 v[8:11], v[250:253], v[234:237], v[218:221]
	v_mfma_f32_16x16x32_bf16 v[4:7], v[246:249], v[238:241], v[4:7]
	v_mfma_f32_16x16x32_bf16 v[8:11], v[146:149], v[238:241], v[8:11]

; template <class Epi, class Sched>
; __device__ __forceinline__ void gemm_simple(PG8_LAS unsigned char* lds, const Gemm g, const Sched& S, const Epi& E, int wave_s) {
;     ...
; #pragma unroll
;         for (int a = 0; a < 2; ++a)
; #pragma unroll
;             for (int b = 0; b < 2; ++b)
; #pragma unroll
;                 for (int m = 0; m < 4; ++m)
; #pragma unroll
;                     for (int n = 0; n < 2; ++n) acc[a][b][m][n] = (f32x4){zero_o, zero_o, zero_o, zero_o};
.LBB0_272:
	s_waitcnt lgkmcnt(0)
	s_cmp_lg_u32 s21, 0
	s_cbranch_scc1 .Lacc0_skip_275
	v_mov_b64_e32 v[6:7], v[2:3]
	v_mov_b64_e32 v[10:11], v[2:3]
	v_mov_b64_e32 v[22:23], v[2:3]
	v_mov_b64_e32 v[26:27], v[2:3]
	v_mov_b64_e32 v[38:39], v[2:3]
	v_mov_b64_e32 v[42:43], v[2:3]
	v_mov_b64_e32 v[54:55], v[2:3]
	v_mov_b64_e32 v[58:59], v[2:3]
	v_mov_b64_e32 v[14:15], v[2:3]
	v_mov_b64_e32 v[18:19], v[2:3]
	v_mov_b64_e32 v[30:31], v[2:3]
	v_mov_b64_e32 v[34:35], v[2:3]
	v_mov_b64_e32 v[46:47], v[2:3]
	v_mov_b64_e32 v[50:51], v[2:3]
	v_mov_b64_e32 v[62:63], v[2:3]
	v_mov_b64_e32 v[66:67], v[2:3]
	v_mov_b64_e32 v[70:71], v[2:3]
	v_mov_b64_e32 v[74:75], v[2:3]
	v_mov_b64_e32 v[86:87], v[2:3]
	v_mov_b64_e32 v[90:91], v[2:3]
	v_mov_b64_e32 v[102:103], v[2:3]
	v_mov_b64_e32 v[106:107], v[2:3]
	v_mov_b64_e32 v[118:119], v[2:3]
	v_mov_b64_e32 v[122:123], v[2:3]
	v_mov_b64_e32 v[78:79], v[2:3]
	v_mov_b64_e32 v[82:83], v[2:3]
	v_mov_b64_e32 v[94:95], v[2:3]
	v_mov_b64_e32 v[98:99], v[2:3]
	v_mov_b64_e32 v[110:111], v[2:3]
	v_mov_b64_e32 v[114:115], v[2:3]
	v_mov_b64_e32 v[126:127], v[2:3]
	v_mov_b64_e32 v[130:131], v[2:3]
	v_mov_b64_e32 v[4:5], v[0:1]
	v_mov_b64_e32 v[8:9], v[0:1]
	v_mov_b64_e32 v[20:21], v[0:1]
	v_mov_b64_e32 v[24:25], v[0:1]
	v_mov_b64_e32 v[36:37], v[0:1]
	v_mov_b64_e32 v[40:41], v[0:1]
	v_mov_b64_e32 v[52:53], v[0:1]
	v_mov_b64_e32 v[56:57], v[0:1]
	v_mov_b64_e32 v[12:13], v[0:1]
	v_mov_b64_e32 v[16:17], v[0:1]
	v_mov_b64_e32 v[28:29], v[0:1]
	v_mov_b64_e32 v[32:33], v[0:1]
	v_mov_b64_e32 v[44:45], v[0:1]
	v_mov_b64_e32 v[48:49], v[0:1]
	v_mov_b64_e32 v[60:61], v[0:1]
	v_mov_b64_e32 v[64:65], v[0:1]
	v_mov_b64_e32 v[68:69], v[0:1]
	v_mov_b64_e32 v[72:73], v[0:1]
	v_mov_b64_e32 v[84:85], v[0:1]
	v_mov_b64_e32 v[88:89], v[0:1]
	v_mov_b64_e32 v[100:101], v[0:1]
	v_mov_b64_e32 v[104:105], v[0:1]
	v_mov_b64_e32 v[116:117], v[0:1]
	v_mov_b64_e32 v[120:121], v[0:1]
	v_mov_b64_e32 v[76:77], v[0:1]
	v_mov_b64_e32 v[80:81], v[0:1]
	v_mov_b64_e32 v[92:93], v[0:1]
	v_mov_b64_e32 v[96:97], v[0:1]
	v_mov_b64_e32 v[108:109], v[0:1]
	v_mov_b64_e32 v[112:113], v[0:1]
	v_mov_b64_e32 v[124:125], v[0:1]
	v_mov_b64_e32 v[128:129], v[0:1]
.Lacc0_skip_275:
	s_mov_b32 s26, 0
	s_cmp_eq_u32 s21, 0
	v_add_u32_e32 v132, 0x10000, v173
	v_add_u32_e32 v133, 0x14000, v173
	v_add_u32_e32 v134, 0x18000, v173
	v_add_u32_e32 v135, 0x1c000, v173
	s_cbranch_scc1 .LBB0_274
	s_waitcnt vmcnt(18) lgkmcnt(0)
	s_barrier
	ds_read_b128 v[4:7], v132
	ds_read_b128 v[44:47], v174 offset:6144
	ds_read_b128 v[20:23], v174
	ds_read_b128 v[12:15], v132 offset:2048
	ds_read_b128 v[28:31], v174 offset:2048
	s_add_u32 s16, s10, 0x80
	s_addc_u32 s17, s11, 0
	s_mov_b32 m0, s49
	s_nop 0
	global_load_lds_dwordx4 v163, s[16:17]
	s_mov_b32 m0, s53
	s_nop 0
	global_load_lds_dwordx4 v171, s[16:17]
	s_waitcnt lgkmcnt(3)
	v_mfma_f32_16x16x32_bf16 v[92:95], v[4:7], v[44:47], v[0:3]
	ds_read_b128 v[36:39], v174 offset:4096
	s_waitcnt lgkmcnt(3)
	v_mfma_f32_16x16x32_bf16 v[68:71], v[4:7], v[20:23], v[0:3]
	s_waitcnt lgkmcnt(2)
	v_mfma_f32_16x16x32_bf16 v[72:75], v[12:15], v[20:23], v[0:3]
	ds_read_b128 v[8:11], v132 offset:1024
	ds_read_b128 v[48:51], v174 offset:7168
	s_waitcnt lgkmcnt(3)
	v_mfma_f32_16x16x32_bf16 v[76:79], v[4:7], v[28:31], v[0:3]
	v_mfma_f32_16x16x32_bf16 v[80:83], v[12:15], v[28:31], v[0:3]
	ds_read_b128 v[24:27], v174 offset:1024
	s_waitcnt lgkmcnt(3)
	v_mfma_f32_16x16x32_bf16 v[84:87], v[4:7], v[36:39], v[0:3]
	ds_read_b128 v[16:19], v132 offset:3072
	v_mfma_f32_16x16x32_bf16 v[88:91], v[12:15], v[36:39], v[0:3]
	ds_read_b128 v[32:35], v174 offset:3072
	s_waitcnt lgkmcnt(3)
	v_mfma_f32_16x16x32_bf16 v[100:103], v[8:11], v[48:51], v[92:95]
	v_mfma_f32_16x16x32_bf16 v[92:95], v[12:15], v[44:47], v[0:3]
	ds_read_b128 v[40:43], v174 offset:5120
	s_waitcnt lgkmcnt(3)
	v_mfma_f32_16x16x32_bf16 v[68:71], v[8:11], v[24:27], v[68:71]
	s_waitcnt lgkmcnt(2)
	v_mfma_f32_16x16x32_bf16 v[72:75], v[16:19], v[24:27], v[72:75]
	s_waitcnt lgkmcnt(1)
	v_mfma_f32_16x16x32_bf16 v[76:79], v[8:11], v[32:35], v[76:79]
	ds_read_b128 v[52:55], v133
	v_mfma_f32_16x16x32_bf16 v[80:83], v[16:19], v[32:35], v[80:83]
	ds_read_b128 v[60:63], v133 offset:2048
	s_waitcnt lgkmcnt(2)
	v_mfma_f32_16x16x32_bf16 v[84:87], v[8:11], v[40:43], v[84:87]
	ds_read_b128 v[56:59], v133 offset:1024
	v_mfma_f32_16x16x32_bf16 v[88:91], v[16:19], v[40:43], v[88:91]
	ds_read_b128 v[64:67], v133 offset:3072
	v_mfma_f32_16x16x32_bf16 v[104:107], v[16:19], v[48:51], v[92:95]
	s_add_u32 s16, s24, 0x80
	s_addc_u32 s17, s25, 0
	s_mov_b32 m0, s50
	s_nop 0
	global_load_lds_dwordx4 v162, s[16:17]
	s_mov_b32 m0, s54
	s_nop 0
	global_load_lds_dwordx4 v170, s[16:17]
	s_waitcnt lgkmcnt(3)
	v_mfma_f32_16x16x32_bf16 v[92:95], v[52:55], v[20:23], v[0:3]
	s_waitcnt lgkmcnt(2)
	v_mfma_f32_16x16x32_bf16 v[20:23], v[60:63], v[20:23], v[0:3]
	s_waitcnt lgkmcnt(1)
	v_mfma_f32_16x16x32_bf16 v[116:119], v[56:59], v[24:27], v[92:95]
	s_waitcnt lgkmcnt(0)
	v_mfma_f32_16x16x32_bf16 v[20:23], v[64:67], v[24:27], v[20:23]
	v_mfma_f32_16x16x32_bf16 v[24:27], v[52:55], v[28:31], v[0:3]
	v_mfma_f32_16x16x32_bf16 v[28:31], v[60:63], v[28:31], v[0:3]
	v_mfma_f32_16x16x32_bf16 v[24:27], v[56:59], v[32:35], v[24:27]
	v_mfma_f32_16x16x32_bf16 v[28:31], v[64:67], v[32:35], v[28:31]
	v_mfma_f32_16x16x32_bf16 v[32:35], v[52:55], v[36:39], v[0:3]
	v_mfma_f32_16x16x32_bf16 v[36:39], v[60:63], v[36:39], v[0:3]
	v_mfma_f32_16x16x32_bf16 v[32:35], v[56:59], v[40:43], v[32:35]
	v_mfma_f32_16x16x32_bf16 v[36:39], v[64:67], v[40:43], v[36:39]
	v_mfma_f32_16x16x32_bf16 v[40:43], v[52:55], v[44:47], v[0:3]
	v_mfma_f32_16x16x32_bf16 v[44:47], v[60:63], v[44:47], v[0:3]
	v_mfma_f32_16x16x32_bf16 v[40:43], v[56:59], v[48:51], v[40:43]
	v_mfma_f32_16x16x32_bf16 v[44:47], v[64:67], v[48:51], v[44:47]
	s_waitcnt vmcnt(20) lgkmcnt(0)
	s_barrier
; template <class Epi, class Sched>
; __device__ __forceinline__ void gemm_simple(PG8_LAS unsigned char* lds, const Gemm g, const Sched& S, const Epi& E, int wave_s) {
;     ...
;             if constexpr (Epi::NST >= 16) PG8_TILE_W(0, cA + kstep, cB + kstep, "18", "20"); else PG8_TILE_W(0, cA + kstep, cB + kstep, "10", "12");
	ds_read_b128 v[48:51], v174 offset:16384
	ds_read_b128 v[96:99], v174 offset:18432
	ds_read_b128 v[112:115], v174 offset:20480
	ds_read_b128 v[124:127], v174 offset:22528
	ds_read_b128 v[92:95], v174 offset:17408
	s_add_u32 s16, s10, 0x80080
	s_addc_u32 s17, s11, 0
	s_mov_b32 m0, s51
	s_nop 0
	global_load_lds_dwordx4 v163, s[16:17]
	s_mov_b32 m0, s55
	s_nop 0
	global_load_lds_dwordx4 v171, s[16:17]
	s_waitcnt lgkmcnt(4)
	v_mfma_f32_16x16x32_bf16 v[136:139], v[4:7], v[48:51], v[0:3]
	ds_read_b128 v[108:111], v174 offset:19456
	s_waitcnt lgkmcnt(4)
	v_mfma_f32_16x16x32_bf16 v[146:149], v[4:7], v[96:99], v[0:3]
	ds_read_b128 v[120:123], v174 offset:21504
	s_waitcnt lgkmcnt(4)
	v_mfma_f32_16x16x32_bf16 v[156:159], v[4:7], v[112:115], v[0:3]
	ds_read_b128 v[128:131], v174 offset:23552
	s_waitcnt lgkmcnt(4)
	v_mfma_f32_16x16x32_bf16 v[4:7], v[4:7], v[124:127], v[0:3]
	s_waitcnt lgkmcnt(3)
	v_mfma_f32_16x16x32_bf16 v[136:139], v[8:11], v[92:95], v[136:139]
	s_waitcnt lgkmcnt(2)
	v_mfma_f32_16x16x32_bf16 v[146:149], v[8:11], v[108:111], v[146:149]
	s_waitcnt lgkmcnt(1)
	v_mfma_f32_16x16x32_bf16 v[156:159], v[8:11], v[120:123], v[156:159]
	s_waitcnt lgkmcnt(0)
	v_mfma_f32_16x16x32_bf16 v[4:7], v[8:11], v[128:131], v[4:7]
	v_mfma_f32_16x16x32_bf16 v[8:11], v[12:15], v[124:127], v[0:3]
	v_mfma_f32_16x16x32_bf16 v[142:145], v[12:15], v[48:51], v[0:3]
	v_mfma_f32_16x16x32_bf16 v[152:155], v[12:15], v[96:99], v[0:3]
	v_mfma_f32_16x16x32_bf16 v[176:179], v[12:15], v[112:115], v[0:3]
	v_mfma_f32_16x16x32_bf16 v[8:11], v[16:19], v[128:131], v[8:11]
	v_mfma_f32_16x16x32_bf16 v[142:145], v[16:19], v[92:95], v[142:145]
	v_mfma_f32_16x16x32_bf16 v[152:155], v[16:19], v[108:111], v[152:155]
	v_mfma_f32_16x16x32_bf16 v[176:179], v[16:19], v[120:123], v[176:179]
	s_add_u32 s16, s24, 0x80080
	s_addc_u32 s17, s25, 0
	s_mov_b32 m0, s52
	s_nop 0
	global_load_lds_dwordx4 v162, s[16:17]
	s_mov_b32 m0, s56
	s_nop 0
	global_load_lds_dwordx4 v170, s[16:17]
	v_mfma_f32_16x16x32_bf16 v[12:15], v[52:55], v[48:51], v[0:3]
	v_mfma_f32_16x16x32_bf16 v[180:183], v[56:59], v[92:95], v[12:15]
	v_mfma_f32_16x16x32_bf16 v[12:15], v[60:63], v[48:51], v[0:3]
	v_mfma_f32_16x16x32_bf16 v[184:187], v[64:67], v[92:95], v[12:15]
	v_mfma_f32_16x16x32_bf16 v[12:15], v[52:55], v[96:99], v[0:3]
	v_mfma_f32_16x16x32_bf16 v[188:191], v[56:59], v[108:111], v[12:15]
	v_mfma_f32_16x16x32_bf16 v[12:15], v[60:63], v[96:99], v[0:3]
	v_mfma_f32_16x16x32_bf16 v[192:195], v[64:67], v[108:111], v[12:15]
	v_mfma_f32_16x16x32_bf16 v[12:15], v[52:55], v[112:115], v[0:3]
	v_mfma_f32_16x16x32_bf16 v[196:199], v[56:59], v[120:123], v[12:15]
	v_mfma_f32_16x16x32_bf16 v[12:15], v[60:63], v[112:115], v[0:3]
	v_mfma_f32_16x16x32_bf16 v[200:203], v[64:67], v[120:123], v[12:15]
	v_mfma_f32_16x16x32_bf16 v[12:15], v[52:55], v[124:127], v[0:3]
	v_mfma_f32_16x16x32_bf16 v[204:207], v[56:59], v[128:131], v[12:15]
	v_mfma_f32_16x16x32_bf16 v[12:15], v[60:63], v[124:127], v[0:3]
	v_mfma_f32_16x16x32_bf16 v[208:211], v[64:67], v[128:131], v[12:15]
	s_waitcnt vmcnt(2) lgkmcnt(0)
	s_barrier
; template <class Epi, class Sched>
; __device__ __forceinline__ void gemm_simple(PG8_LAS unsigned char* lds, const Gemm g, const Sched& S, const Epi& E, int wave_s) {
;     ...
;             PG8_TILE_W(1, cA + 2 * kstep, cB + 2 * kstep, "2", "4");
;             t = 2;
	s_nop 5
	ds_read_b128 v[12:15], v134
	ds_read_b128 v[48:51], v174 offset:32768
	ds_read_b128 v[16:19], v134 offset:1024
	ds_read_b128 v[60:63], v174 offset:33792
	ds_read_b128 v[52:55], v134 offset:2048
	ds_read_b128 v[56:59], v134 offset:3072
	ds_read_b128 v[64:67], v174 offset:34816
	s_add_u32 s16, s10, 0x100
	s_addc_u32 s17, s11, 0
	s_mov_b32 m0, s38
	s_nop 0
	global_load_lds_dwordx4 v163, s[16:17]
	s_mov_b32 m0, s39
	s_nop 0
	global_load_lds_dwordx4 v171, s[16:17]
	s_waitcnt lgkmcnt(5)
	v_mfma_f32_16x16x32_bf16 v[68:71], v[12:15], v[48:51], v[68:71]
	ds_read_b128 v[212:215], v174 offset:35840
	s_waitcnt lgkmcnt(4)
	v_mfma_f32_16x16x32_bf16 v[128:131], v[16:19], v[60:63], v[68:71]
	s_waitcnt lgkmcnt(3)
	v_mfma_f32_16x16x32_bf16 v[68:71], v[52:55], v[48:51], v[72:75]
	s_waitcnt lgkmcnt(2)
	v_mfma_f32_16x16x32_bf16 v[124:127], v[56:59], v[60:63], v[68:71]
	ds_read_b128 v[216:219], v174 offset:36864
	s_waitcnt lgkmcnt(2)
	v_mfma_f32_16x16x32_bf16 v[68:71], v[12:15], v[64:67], v[76:79]
	ds_read_b128 v[220:223], v174 offset:37888
	s_waitcnt lgkmcnt(2)
	v_mfma_f32_16x16x32_bf16 v[112:115], v[16:19], v[212:215], v[68:71]
	v_mfma_f32_16x16x32_bf16 v[68:71], v[52:55], v[64:67], v[80:83]
	v_mfma_f32_16x16x32_bf16 v[108:111], v[56:59], v[212:215], v[68:71]
	ds_read_b128 v[224:227], v174 offset:38912
	s_waitcnt lgkmcnt(2)
	v_mfma_f32_16x16x32_bf16 v[68:71], v[12:15], v[216:219], v[84:87]
	ds_read_b128 v[228:231], v174 offset:39936
	s_waitcnt lgkmcnt(2)
	v_mfma_f32_16x16x32_bf16 v[96:99], v[16:19], v[220:223], v[68:71]
	v_mfma_f32_16x16x32_bf16 v[68:71], v[52:55], v[216:219], v[88:91]
	v_mfma_f32_16x16x32_bf16 v[92:95], v[56:59], v[220:223], v[68:71]
	ds_read_b128 v[240:243], v135 offset:2048
	s_waitcnt lgkmcnt(2)
	v_mfma_f32_16x16x32_bf16 v[68:71], v[12:15], v[224:227], v[100:103]
	ds_read_b128 v[232:235], v135
	s_waitcnt lgkmcnt(2)
	v_mfma_f32_16x16x32_bf16 v[80:83], v[16:19], v[228:231], v[68:71]
	ds_read_b128 v[244:247], v135 offset:3072
	v_mfma_f32_16x16x32_bf16 v[68:71], v[52:55], v[224:227], v[104:107]
	v_mfma_f32_16x16x32_bf16 v[76:79], v[56:59], v[228:231], v[68:71]
	s_add_u32 s16, s24, 0x100
	s_addc_u32 s17, s25, 0
	s_mov_b32 m0, s23
	s_nop 0
	global_load_lds_dwordx4 v162, s[16:17]
	s_mov_b32 m0, s40
	s_nop 0
	global_load_lds_dwordx4 v170, s[16:17]
	ds_read_b128 v[236:239], v135 offset:1024
	s_waitcnt lgkmcnt(3)
	v_mfma_f32_16x16x32_bf16 v[20:23], v[240:243], v[48:51], v[20:23]
	s_waitcnt lgkmcnt(2)
	v_mfma_f32_16x16x32_bf16 v[68:71], v[232:235], v[48:51], v[116:119]
	s_waitcnt lgkmcnt(1)
	v_mfma_f32_16x16x32_bf16 v[116:119], v[244:247], v[60:63], v[20:23]
	v_mfma_f32_16x16x32_bf16 v[20:23], v[232:235], v[64:67], v[24:27]
	s_waitcnt lgkmcnt(0)
	v_mfma_f32_16x16x32_bf16 v[104:107], v[236:239], v[212:215], v[20:23]
	v_mfma_f32_16x16x32_bf16 v[20:23], v[240:243], v[64:67], v[28:31]
	v_mfma_f32_16x16x32_bf16 v[100:103], v[244:247], v[212:215], v[20:23]
	v_mfma_f32_16x16x32_bf16 v[20:23], v[232:235], v[216:219], v[32:35]
	v_mfma_f32_16x16x32_bf16 v[88:91], v[236:239], v[220:223], v[20:23]
	v_mfma_f32_16x16x32_bf16 v[20:23], v[240:243], v[216:219], v[36:39]
	v_mfma_f32_16x16x32_bf16 v[84:87], v[244:247], v[220:223], v[20:23]
	v_mfma_f32_16x16x32_bf16 v[20:23], v[232:235], v[224:227], v[40:43]
	v_mfma_f32_16x16x32_bf16 v[72:75], v[236:239], v[228:231], v[20:23]
	v_mfma_f32_16x16x32_bf16 v[20:23], v[240:243], v[224:227], v[44:47]
	v_mfma_f32_16x16x32_bf16 v[120:123], v[236:239], v[60:63], v[68:71]
	v_mfma_f32_16x16x32_bf16 v[68:71], v[244:247], v[228:231], v[20:23]
	s_waitcnt vmcnt(4) lgkmcnt(0)
	s_barrier
	s_nop 4
	ds_read_b128 v[20:23], v174 offset:49152
	ds_read_b128 v[24:27], v174 offset:50176
	ds_read_b128 v[36:39], v174 offset:51200
	s_add_u32 s16, s10, 0x80100
	s_addc_u32 s17, s11, 0
	s_mov_b32 m0, s41
	s_nop 0
	global_load_lds_dwordx4 v163, s[16:17]
	s_mov_b32 m0, s42
	s_nop 0
	global_load_lds_dwordx4 v171, s[16:17]
	s_waitcnt lgkmcnt(2)
	v_mfma_f32_16x16x32_bf16 v[28:31], v[12:15], v[20:23], v[136:139]
	ds_read_b128 v[212:215], v174 offset:52224
	s_waitcnt lgkmcnt(2)
	v_mfma_f32_16x16x32_bf16 v[64:67], v[16:19], v[24:27], v[28:31]
	v_mfma_f32_16x16x32_bf16 v[28:31], v[52:55], v[20:23], v[142:145]
	v_mfma_f32_16x16x32_bf16 v[60:63], v[56:59], v[24:27], v[28:31]
	ds_read_b128 v[216:219], v174 offset:53248
	s_waitcnt lgkmcnt(2)
	v_mfma_f32_16x16x32_bf16 v[28:31], v[12:15], v[36:39], v[146:149]
	ds_read_b128 v[224:227], v174 offset:55296
	s_waitcnt lgkmcnt(2)
	v_mfma_f32_16x16x32_bf16 v[48:51], v[16:19], v[212:215], v[28:31]
	ds_read_b128 v[220:223], v174 offset:54272
	v_mfma_f32_16x16x32_bf16 v[28:31], v[52:55], v[36:39], v[152:155]
	v_mfma_f32_16x16x32_bf16 v[44:47], v[56:59], v[212:215], v[28:31]
	ds_read_b128 v[228:231], v174 offset:56320
	s_waitcnt lgkmcnt(3)
	v_mfma_f32_16x16x32_bf16 v[28:31], v[12:15], v[216:219], v[156:159]
	s_waitcnt lgkmcnt(2)
	v_mfma_f32_16x16x32_bf16 v[4:7], v[12:15], v[224:227], v[4:7]
	s_waitcnt lgkmcnt(1)
	v_mfma_f32_16x16x32_bf16 v[32:35], v[16:19], v[220:223], v[28:31]
	v_mfma_f32_16x16x32_bf16 v[28:31], v[52:55], v[216:219], v[176:179]
	s_waitcnt lgkmcnt(0)
	v_mfma_f32_16x16x32_bf16 v[16:19], v[16:19], v[228:231], v[4:7]
	v_mfma_f32_16x16x32_bf16 v[4:7], v[52:55], v[224:227], v[8:11]
	v_mfma_f32_16x16x32_bf16 v[28:31], v[56:59], v[220:223], v[28:31]
	v_mfma_f32_16x16x32_bf16 v[12:15], v[56:59], v[228:231], v[4:7]
	s_add_u32 s16, s24, 0x80100
	s_addc_u32 s17, s25, 0
	s_mov_b32 m0, s43
	s_nop 0
	global_load_lds_dwordx4 v162, s[16:17]
	s_mov_b32 m0, s44
	s_nop 0
	global_load_lds_dwordx4 v170, s[16:17]
	v_mfma_f32_16x16x32_bf16 v[4:7], v[232:235], v[20:23], v[180:183]
	s_mov_b32 s26, 2
	v_mfma_f32_16x16x32_bf16 v[56:59], v[236:239], v[24:27], v[4:7]
	v_mfma_f32_16x16x32_bf16 v[4:7], v[240:243], v[20:23], v[184:187]
	v_mfma_f32_16x16x32_bf16 v[52:55], v[244:247], v[24:27], v[4:7]
	v_mfma_f32_16x16x32_bf16 v[4:7], v[232:235], v[36:39], v[188:191]
	v_mfma_f32_16x16x32_bf16 v[40:43], v[236:239], v[212:215], v[4:7]
	v_mfma_f32_16x16x32_bf16 v[4:7], v[240:243], v[36:39], v[192:195]
	v_mfma_f32_16x16x32_bf16 v[36:39], v[244:247], v[212:215], v[4:7]
	v_mfma_f32_16x16x32_bf16 v[4:7], v[232:235], v[216:219], v[196:199]
	v_mfma_f32_16x16x32_bf16 v[24:27], v[236:239], v[220:223], v[4:7]
	v_mfma_f32_16x16x32_bf16 v[4:7], v[240:243], v[216:219], v[200:203]
	v_mfma_f32_16x16x32_bf16 v[20:23], v[244:247], v[220:223], v[4:7]
	v_mfma_f32_16x16x32_bf16 v[4:7], v[232:235], v[224:227], v[204:207]
	v_mfma_f32_16x16x32_bf16 v[8:11], v[236:239], v[228:231], v[4:7]
	v_mfma_f32_16x16x32_bf16 v[4:7], v[240:243], v[224:227], v[208:211]
	v_mfma_f32_16x16x32_bf16 v[4:7], v[244:247], v[228:231], v[4:7]

; template <class Epi, class Sched>
; __device__ __forceinline__ void gemm_simple(PG8_LAS unsigned char* lds, const Gemm g, const Sched& S, const Epi& E, int wave_s) {
;     ...
; #pragma unroll
;         for (int a = 0; a < 2; ++a)
; #pragma unroll
;             for (int b = 0; b < 2; ++b)
; #pragma unroll
;                 for (int m = 0; m < 4; ++m)
; #pragma unroll
;                     for (int n = 0; n < 2; ++n) acc[a][b][m][n] = (f32x4){zero_o, zero_o, zero_o, zero_o};
.LBB0_304:
	s_cmp_lg_u32 s55, 0
	s_cbranch_scc1 .Lacc0_skip_307
	v_mov_b64_e32 v[18:19], v[2:3]
	v_mov_b64_e32 v[14:15], v[2:3]
	v_mov_b64_e32 v[30:31], v[2:3]
	v_mov_b64_e32 v[34:35], v[2:3]
	v_mov_b64_e32 v[46:47], v[2:3]
	v_mov_b64_e32 v[50:51], v[2:3]
	v_mov_b64_e32 v[62:63], v[2:3]
	v_mov_b64_e32 v[66:67], v[2:3]
	v_mov_b64_e32 v[6:7], v[2:3]
	v_mov_b64_e32 v[10:11], v[2:3]
	v_mov_b64_e32 v[22:23], v[2:3]
	v_mov_b64_e32 v[26:27], v[2:3]
	v_mov_b64_e32 v[38:39], v[2:3]
	v_mov_b64_e32 v[42:43], v[2:3]
	v_mov_b64_e32 v[54:55], v[2:3]
	v_mov_b64_e32 v[58:59], v[2:3]
	v_mov_b64_e32 v[78:79], v[2:3]
	v_mov_b64_e32 v[82:83], v[2:3]
	v_mov_b64_e32 v[94:95], v[2:3]
	v_mov_b64_e32 v[98:99], v[2:3]
	v_mov_b64_e32 v[110:111], v[2:3]
	v_mov_b64_e32 v[114:115], v[2:3]
	v_mov_b64_e32 v[126:127], v[2:3]
	v_mov_b64_e32 v[130:131], v[2:3]
	v_mov_b64_e32 v[70:71], v[2:3]
	v_mov_b64_e32 v[74:75], v[2:3]
	v_mov_b64_e32 v[86:87], v[2:3]
	v_mov_b64_e32 v[90:91], v[2:3]
	v_mov_b64_e32 v[102:103], v[2:3]
	v_mov_b64_e32 v[106:107], v[2:3]
	v_mov_b64_e32 v[118:119], v[2:3]
	v_mov_b64_e32 v[122:123], v[2:3]
	v_mov_b64_e32 v[16:17], v[0:1]
	v_mov_b64_e32 v[12:13], v[0:1]
	v_mov_b64_e32 v[28:29], v[0:1]
	v_mov_b64_e32 v[32:33], v[0:1]
	v_mov_b64_e32 v[44:45], v[0:1]
	v_mov_b64_e32 v[48:49], v[0:1]
	v_mov_b64_e32 v[60:61], v[0:1]
	v_mov_b64_e32 v[64:65], v[0:1]
	v_mov_b64_e32 v[4:5], v[0:1]
	v_mov_b64_e32 v[8:9], v[0:1]
	v_mov_b64_e32 v[20:21], v[0:1]
	v_mov_b64_e32 v[24:25], v[0:1]
	v_mov_b64_e32 v[36:37], v[0:1]
	v_mov_b64_e32 v[40:41], v[0:1]
	v_mov_b64_e32 v[52:53], v[0:1]
	v_mov_b64_e32 v[56:57], v[0:1]
	v_mov_b64_e32 v[76:77], v[0:1]
	v_mov_b64_e32 v[80:81], v[0:1]
	v_mov_b64_e32 v[92:93], v[0:1]
	v_mov_b64_e32 v[96:97], v[0:1]
	v_mov_b64_e32 v[108:109], v[0:1]
	v_mov_b64_e32 v[112:113], v[0:1]
	v_mov_b64_e32 v[124:125], v[0:1]
	v_mov_b64_e32 v[128:129], v[0:1]
	v_mov_b64_e32 v[68:69], v[0:1]
	v_mov_b64_e32 v[72:73], v[0:1]
	v_mov_b64_e32 v[84:85], v[0:1]
	v_mov_b64_e32 v[88:89], v[0:1]
	v_mov_b64_e32 v[100:101], v[0:1]
	v_mov_b64_e32 v[104:105], v[0:1]
	v_mov_b64_e32 v[116:117], v[0:1]
	v_mov_b64_e32 v[120:121], v[0:1]
.Lacc0_skip_307:
	s_mov_b32 s22, 0
	s_cmp_eq_u32 s55, 0
	v_add_u32_e32 v132, 0x10000, v176
	v_add_u32_e32 v133, 0x14000, v176
	v_add_u32_e32 v134, 0x18000, v176
	v_add_u32_e32 v135, 0x1c000, v176
	s_cbranch_scc1 .LBB0_306
	s_waitcnt vmcnt(18) lgkmcnt(0)
	s_barrier
	ds_read_b128 v[12:15], v132 offset:2048
	ds_read_b128 v[36:39], v177 offset:4096
	ds_read_b128 v[16:19], v132 offset:3072
	ds_read_b128 v[40:43], v177 offset:5120
	ds_read_b128 v[4:7], v132
	ds_read_b128 v[44:47], v177 offset:6144
	ds_read_b128 v[20:23], v177
	s_add_u32 s14, s10, 0x80
	s_addc_u32 s15, s11, 0
	s_mov_b32 m0, s43
	s_nop 0
	global_load_lds_dwordx4 v172, s[14:15]
	s_mov_b32 m0, s49
	s_nop 0
	global_load_lds_dwordx4 v174, s[14:15]
	s_waitcnt lgkmcnt(5)
	v_mfma_f32_16x16x32_bf16 v[88:91], v[12:15], v[36:39], v[0:3]
	ds_read_b128 v[28:31], v177 offset:2048
	s_waitcnt lgkmcnt(4)
	v_mfma_f32_16x16x32_bf16 v[92:95], v[16:19], v[40:43], v[88:91]
	s_waitcnt lgkmcnt(2)
	v_mfma_f32_16x16x32_bf16 v[88:91], v[4:7], v[44:47], v[0:3]
	s_waitcnt lgkmcnt(1)
	v_mfma_f32_16x16x32_bf16 v[68:71], v[4:7], v[20:23], v[0:3]
	ds_read_b128 v[8:11], v132 offset:1024
	ds_read_b128 v[48:51], v177 offset:7168
	v_mfma_f32_16x16x32_bf16 v[72:75], v[12:15], v[20:23], v[0:3]
	s_waitcnt lgkmcnt(2)
	v_mfma_f32_16x16x32_bf16 v[76:79], v[4:7], v[28:31], v[0:3]
	ds_read_b128 v[24:27], v177 offset:1024
	v_mfma_f32_16x16x32_bf16 v[80:83], v[12:15], v[28:31], v[0:3]
	v_mfma_f32_16x16x32_bf16 v[84:87], v[4:7], v[36:39], v[0:3]
	ds_read_b128 v[32:35], v177 offset:3072
	s_waitcnt lgkmcnt(2)
	v_mfma_f32_16x16x32_bf16 v[96:99], v[8:11], v[48:51], v[88:91]
	v_mfma_f32_16x16x32_bf16 v[88:91], v[12:15], v[44:47], v[0:3]
	s_waitcnt lgkmcnt(1)
	v_mfma_f32_16x16x32_bf16 v[68:71], v[8:11], v[24:27], v[68:71]
	v_mfma_f32_16x16x32_bf16 v[72:75], v[16:19], v[24:27], v[72:75]
	ds_read_b128 v[52:55], v133
	s_waitcnt lgkmcnt(1)
	v_mfma_f32_16x16x32_bf16 v[76:79], v[8:11], v[32:35], v[76:79]
	ds_read_b128 v[60:63], v133 offset:2048
	v_mfma_f32_16x16x32_bf16 v[80:83], v[16:19], v[32:35], v[80:83]
	ds_read_b128 v[56:59], v133 offset:1024
	v_mfma_f32_16x16x32_bf16 v[84:87], v[8:11], v[40:43], v[84:87]
	ds_read_b128 v[64:67], v133 offset:3072
	v_mfma_f32_16x16x32_bf16 v[108:111], v[16:19], v[48:51], v[88:91]
	s_add_u32 s14, s20, 0x80
	s_addc_u32 s15, s21, 0
	s_mov_b32 m0, s44
	s_nop 0
	global_load_lds_dwordx4 v171, s[14:15]
	s_mov_b32 m0, s50
	s_nop 0
	global_load_lds_dwordx4 v173, s[14:15]
	s_waitcnt lgkmcnt(3)
	v_mfma_f32_16x16x32_bf16 v[88:91], v[52:55], v[20:23], v[0:3]
	s_waitcnt lgkmcnt(2)
	v_mfma_f32_16x16x32_bf16 v[20:23], v[60:63], v[20:23], v[0:3]
	s_waitcnt lgkmcnt(1)
	v_mfma_f32_16x16x32_bf16 v[112:115], v[56:59], v[24:27], v[88:91]
	s_waitcnt lgkmcnt(0)
	v_mfma_f32_16x16x32_bf16 v[20:23], v[64:67], v[24:27], v[20:23]
	v_mfma_f32_16x16x32_bf16 v[24:27], v[52:55], v[28:31], v[0:3]
	v_mfma_f32_16x16x32_bf16 v[28:31], v[60:63], v[28:31], v[0:3]
	v_mfma_f32_16x16x32_bf16 v[24:27], v[56:59], v[32:35], v[24:27]
	v_mfma_f32_16x16x32_bf16 v[28:31], v[64:67], v[32:35], v[28:31]
	v_mfma_f32_16x16x32_bf16 v[32:35], v[52:55], v[36:39], v[0:3]
	v_mfma_f32_16x16x32_bf16 v[36:39], v[60:63], v[36:39], v[0:3]
	v_mfma_f32_16x16x32_bf16 v[32:35], v[56:59], v[40:43], v[32:35]
	v_mfma_f32_16x16x32_bf16 v[36:39], v[64:67], v[40:43], v[36:39]
	v_mfma_f32_16x16x32_bf16 v[40:43], v[52:55], v[44:47], v[0:3]
	v_mfma_f32_16x16x32_bf16 v[44:47], v[60:63], v[44:47], v[0:3]
	v_mfma_f32_16x16x32_bf16 v[40:43], v[56:59], v[48:51], v[40:43]
	v_mfma_f32_16x16x32_bf16 v[44:47], v[64:67], v[48:51], v[44:47]
	s_waitcnt vmcnt(20) lgkmcnt(0)
	s_barrier
; template <class Epi, class Sched>
; __device__ __forceinline__ void gemm_simple(PG8_LAS unsigned char* lds, const Gemm g, const Sched& S, const Epi& E, int wave_s) {
;     ...
;             if constexpr (Epi::NST >= 16) PG8_TILE_W(0, cA + kstep, cB + kstep, "18", "20"); else PG8_TILE_W(0, cA + kstep, cB + kstep, "10", "12");
;             PG8_TILE_W(1, cA + 2 * kstep, cB + 2 * kstep, "2", "4");
	ds_read_b128 v[48:51], v177 offset:16384
	ds_read_b128 v[100:103], v177 offset:18432
	ds_read_b128 v[116:119], v177 offset:20480
	ds_read_b128 v[124:127], v177 offset:22528
	ds_read_b128 v[88:91], v177 offset:17408
	s_add_u32 s14, s10, 0x80080
	s_addc_u32 s15, s11, 0
	s_mov_b32 m0, s45
	s_nop 0
	global_load_lds_dwordx4 v172, s[14:15]
	s_mov_b32 m0, s51
	s_nop 0
	global_load_lds_dwordx4 v174, s[14:15]
	s_waitcnt lgkmcnt(4)
	v_mfma_f32_16x16x32_bf16 v[136:139], v[4:7], v[48:51], v[0:3]
	ds_read_b128 v[104:107], v177 offset:19456
	s_waitcnt lgkmcnt(4)
	v_mfma_f32_16x16x32_bf16 v[156:159], v[4:7], v[100:103], v[0:3]
	ds_read_b128 v[120:123], v177 offset:21504
	s_waitcnt lgkmcnt(4)
	v_mfma_f32_16x16x32_bf16 v[178:181], v[4:7], v[116:119], v[0:3]
	ds_read_b128 v[128:131], v177 offset:23552
	s_waitcnt lgkmcnt(4)
	v_mfma_f32_16x16x32_bf16 v[4:7], v[4:7], v[124:127], v[0:3]
	s_waitcnt lgkmcnt(3)
	v_mfma_f32_16x16x32_bf16 v[136:139], v[8:11], v[88:91], v[136:139]
	s_waitcnt lgkmcnt(2)
	v_mfma_f32_16x16x32_bf16 v[156:159], v[8:11], v[104:107], v[156:159]
	s_waitcnt lgkmcnt(1)
	v_mfma_f32_16x16x32_bf16 v[178:181], v[8:11], v[120:123], v[178:181]
	s_waitcnt lgkmcnt(0)
	v_mfma_f32_16x16x32_bf16 v[4:7], v[8:11], v[128:131], v[4:7]
	v_mfma_f32_16x16x32_bf16 v[8:11], v[12:15], v[124:127], v[0:3]
	v_mfma_f32_16x16x32_bf16 v[152:155], v[12:15], v[48:51], v[0:3]
	v_mfma_f32_16x16x32_bf16 v[160:163], v[12:15], v[100:103], v[0:3]
	v_mfma_f32_16x16x32_bf16 v[182:185], v[12:15], v[116:119], v[0:3]
	v_mfma_f32_16x16x32_bf16 v[12:15], v[16:19], v[128:131], v[8:11]
	v_mfma_f32_16x16x32_bf16 v[152:155], v[16:19], v[88:91], v[152:155]
	v_mfma_f32_16x16x32_bf16 v[160:163], v[16:19], v[104:107], v[160:163]
	v_mfma_f32_16x16x32_bf16 v[182:185], v[16:19], v[120:123], v[182:185]
	s_add_u32 s14, s20, 0x80080
	s_addc_u32 s15, s21, 0
	s_mov_b32 m0, s46
	s_nop 0
	global_load_lds_dwordx4 v171, s[14:15]
	s_mov_b32 m0, s52
	s_nop 0
	global_load_lds_dwordx4 v173, s[14:15]
	v_mfma_f32_16x16x32_bf16 v[8:11], v[52:55], v[48:51], v[0:3]
	v_mfma_f32_16x16x32_bf16 v[16:19], v[56:59], v[88:91], v[8:11]
	v_mfma_f32_16x16x32_bf16 v[8:11], v[60:63], v[48:51], v[0:3]
	v_mfma_f32_16x16x32_bf16 v[48:51], v[64:67], v[88:91], v[8:11]
	v_mfma_f32_16x16x32_bf16 v[8:11], v[52:55], v[100:103], v[0:3]
	v_mfma_f32_16x16x32_bf16 v[186:189], v[56:59], v[104:107], v[8:11]
	v_mfma_f32_16x16x32_bf16 v[8:11], v[60:63], v[100:103], v[0:3]
	v_mfma_f32_16x16x32_bf16 v[190:193], v[64:67], v[104:107], v[8:11]
	v_mfma_f32_16x16x32_bf16 v[8:11], v[52:55], v[116:119], v[0:3]
	v_mfma_f32_16x16x32_bf16 v[194:197], v[56:59], v[120:123], v[8:11]
	v_mfma_f32_16x16x32_bf16 v[8:11], v[60:63], v[116:119], v[0:3]
	v_mfma_f32_16x16x32_bf16 v[198:201], v[64:67], v[120:123], v[8:11]
	v_mfma_f32_16x16x32_bf16 v[8:11], v[52:55], v[124:127], v[0:3]
	v_mfma_f32_16x16x32_bf16 v[202:205], v[56:59], v[128:131], v[8:11]
	v_mfma_f32_16x16x32_bf16 v[8:11], v[60:63], v[124:127], v[0:3]
	v_mfma_f32_16x16x32_bf16 v[206:209], v[64:67], v[128:131], v[8:11]
	s_waitcnt vmcnt(2) lgkmcnt(0)
	s_barrier
	s_nop 5
	ds_read_b128 v[8:11], v134
	ds_read_b128 v[52:55], v177 offset:32768
	ds_read_b128 v[60:63], v134 offset:1024
	ds_read_b128 v[56:59], v177 offset:33792
	ds_read_b128 v[64:67], v134 offset:2048
	ds_read_b128 v[210:213], v134 offset:3072
	ds_read_b128 v[214:217], v177 offset:34816
	s_add_u32 s14, s10, 0x100
	s_addc_u32 s15, s11, 0
	s_mov_b32 m0, s27
	s_nop 0
	global_load_lds_dwordx4 v172, s[14:15]
	s_mov_b32 m0, s28
	s_nop 0
	global_load_lds_dwordx4 v174, s[14:15]
	s_waitcnt lgkmcnt(5)
	v_mfma_f32_16x16x32_bf16 v[68:71], v[8:11], v[52:55], v[68:71]
	ds_read_b128 v[218:221], v177 offset:35840
	s_waitcnt lgkmcnt(4)
	v_mfma_f32_16x16x32_bf16 v[120:123], v[60:63], v[56:59], v[68:71]
	s_waitcnt lgkmcnt(3)
	v_mfma_f32_16x16x32_bf16 v[68:71], v[64:67], v[52:55], v[72:75]
	s_waitcnt lgkmcnt(2)
	v_mfma_f32_16x16x32_bf16 v[116:119], v[210:213], v[56:59], v[68:71]
	ds_read_b128 v[222:225], v177 offset:36864
	s_waitcnt lgkmcnt(2)
	v_mfma_f32_16x16x32_bf16 v[68:71], v[8:11], v[214:217], v[76:79]
	ds_read_b128 v[226:229], v177 offset:37888
	s_waitcnt lgkmcnt(2)
	v_mfma_f32_16x16x32_bf16 v[104:107], v[60:63], v[218:221], v[68:71]
	v_mfma_f32_16x16x32_bf16 v[68:71], v[64:67], v[214:217], v[80:83]
	v_mfma_f32_16x16x32_bf16 v[100:103], v[210:213], v[218:221], v[68:71]
	ds_read_b128 v[230:233], v177 offset:38912
	s_waitcnt lgkmcnt(2)
	v_mfma_f32_16x16x32_bf16 v[68:71], v[8:11], v[222:225], v[84:87]
	ds_read_b128 v[234:237], v177 offset:39936
	s_waitcnt lgkmcnt(2)
	v_mfma_f32_16x16x32_bf16 v[88:91], v[60:63], v[226:229], v[68:71]
	v_mfma_f32_16x16x32_bf16 v[68:71], v[64:67], v[222:225], v[92:95]
	v_mfma_f32_16x16x32_bf16 v[84:87], v[210:213], v[226:229], v[68:71]
	ds_read_b128 v[246:249], v135 offset:2048
	s_waitcnt lgkmcnt(2)
	v_mfma_f32_16x16x32_bf16 v[68:71], v[8:11], v[230:233], v[96:99]
	ds_read_b128 v[250:253], v135 offset:3072
	s_waitcnt lgkmcnt(2)
	v_mfma_f32_16x16x32_bf16 v[72:75], v[60:63], v[234:237], v[68:71]
	ds_read_b128 v[238:241], v135
	v_mfma_f32_16x16x32_bf16 v[68:71], v[64:67], v[230:233], v[108:111]
	v_mfma_f32_16x16x32_bf16 v[68:71], v[210:213], v[234:237], v[68:71]
	s_add_u32 s14, s20, 0x100
	s_addc_u32 s15, s21, 0
	s_mov_b32 m0, s19
	s_nop 0
	global_load_lds_dwordx4 v171, s[14:15]
	s_mov_b32 m0, s29
	s_nop 0
	global_load_lds_dwordx4 v173, s[14:15]
	ds_read_b128 v[242:245], v135 offset:1024
	s_waitcnt lgkmcnt(3)
	v_mfma_f32_16x16x32_bf16 v[20:23], v[246:249], v[52:55], v[20:23]
	s_waitcnt lgkmcnt(2)
	v_mfma_f32_16x16x32_bf16 v[124:127], v[250:253], v[56:59], v[20:23]
	s_waitcnt lgkmcnt(1)
	v_mfma_f32_16x16x32_bf16 v[20:23], v[238:241], v[214:217], v[24:27]
	v_mfma_f32_16x16x32_bf16 v[76:79], v[238:241], v[52:55], v[112:115]
	s_waitcnt lgkmcnt(0)
	v_mfma_f32_16x16x32_bf16 v[112:115], v[242:245], v[218:221], v[20:23]
	v_mfma_f32_16x16x32_bf16 v[20:23], v[246:249], v[214:217], v[28:31]
	v_mfma_f32_16x16x32_bf16 v[108:111], v[250:253], v[218:221], v[20:23]
	v_mfma_f32_16x16x32_bf16 v[20:23], v[238:241], v[222:225], v[32:35]
	v_mfma_f32_16x16x32_bf16 v[96:99], v[242:245], v[226:229], v[20:23]
	v_mfma_f32_16x16x32_bf16 v[20:23], v[246:249], v[222:225], v[36:39]
	v_mfma_f32_16x16x32_bf16 v[92:95], v[250:253], v[226:229], v[20:23]
	v_mfma_f32_16x16x32_bf16 v[20:23], v[238:241], v[230:233], v[40:43]
	v_mfma_f32_16x16x32_bf16 v[80:83], v[242:245], v[234:237], v[20:23]
	v_mfma_f32_16x16x32_bf16 v[20:23], v[246:249], v[230:233], v[44:47]
	v_mfma_f32_16x16x32_bf16 v[128:131], v[242:245], v[56:59], v[76:79]
	v_mfma_f32_16x16x32_bf16 v[76:79], v[250:253], v[234:237], v[20:23]
	s_waitcnt vmcnt(4) lgkmcnt(0)
	s_barrier
; template <class Epi, class Sched>
; __device__ __forceinline__ void gemm_simple(PG8_LAS unsigned char* lds, const Gemm g, const Sched& S, const Epi& E, int wave_s) {
;     ...
;             PG8_TILE_W(1, cA + 2 * kstep, cB + 2 * kstep, "2", "4");
;             t = 2;
	ds_read_b128 v[28:31], v177 offset:49152
	ds_read_b128 v[32:35], v177 offset:50176
	ds_read_b128 v[44:47], v177 offset:51200
	s_add_u32 s14, s10, 0x80100
	s_addc_u32 s15, s11, 0
	s_mov_b32 m0, s36
	s_nop 0
	global_load_lds_dwordx4 v172, s[14:15]
	s_mov_b32 m0, s37
	s_nop 0
	global_load_lds_dwordx4 v174, s[14:15]
	s_waitcnt lgkmcnt(2)
	v_mfma_f32_16x16x32_bf16 v[20:23], v[8:11], v[28:31], v[136:139]
	ds_read_b128 v[214:217], v177 offset:52224
	s_waitcnt lgkmcnt(2)
	v_mfma_f32_16x16x32_bf16 v[56:59], v[60:63], v[32:35], v[20:23]
	v_mfma_f32_16x16x32_bf16 v[20:23], v[64:67], v[28:31], v[152:155]
	v_mfma_f32_16x16x32_bf16 v[52:55], v[210:213], v[32:35], v[20:23]
	ds_read_b128 v[218:221], v177 offset:53248
	s_waitcnt lgkmcnt(2)
	v_mfma_f32_16x16x32_bf16 v[20:23], v[8:11], v[44:47], v[156:159]
	ds_read_b128 v[226:229], v177 offset:55296
	s_waitcnt lgkmcnt(2)
	v_mfma_f32_16x16x32_bf16 v[40:43], v[60:63], v[214:217], v[20:23]
	ds_read_b128 v[222:225], v177 offset:54272
	v_mfma_f32_16x16x32_bf16 v[20:23], v[64:67], v[44:47], v[160:163]
	v_mfma_f32_16x16x32_bf16 v[36:39], v[210:213], v[214:217], v[20:23]
	ds_read_b128 v[230:233], v177 offset:56320
	s_waitcnt lgkmcnt(3)
	v_mfma_f32_16x16x32_bf16 v[20:23], v[8:11], v[218:221], v[178:181]
	s_waitcnt lgkmcnt(2)
	v_mfma_f32_16x16x32_bf16 v[4:7], v[8:11], v[226:229], v[4:7]
	s_waitcnt lgkmcnt(1)
	v_mfma_f32_16x16x32_bf16 v[24:27], v[60:63], v[222:225], v[20:23]
	v_mfma_f32_16x16x32_bf16 v[20:23], v[64:67], v[218:221], v[182:185]
	s_waitcnt lgkmcnt(0)
	v_mfma_f32_16x16x32_bf16 v[8:11], v[60:63], v[230:233], v[4:7]
	v_mfma_f32_16x16x32_bf16 v[4:7], v[64:67], v[226:229], v[12:15]
	v_mfma_f32_16x16x32_bf16 v[20:23], v[210:213], v[222:225], v[20:23]
	v_mfma_f32_16x16x32_bf16 v[4:7], v[210:213], v[230:233], v[4:7]
	s_add_u32 s14, s20, 0x80100
	s_addc_u32 s15, s21, 0
	s_mov_b32 m0, s38
	s_nop 0
	global_load_lds_dwordx4 v171, s[14:15]
	s_mov_b32 m0, s39
	s_nop 0
	global_load_lds_dwordx4 v173, s[14:15]
	v_mfma_f32_16x16x32_bf16 v[12:15], v[238:241], v[28:31], v[16:19]
	s_mov_b32 s22, 2
	v_mfma_f32_16x16x32_bf16 v[64:67], v[242:245], v[32:35], v[12:15]
	v_mfma_f32_16x16x32_bf16 v[12:15], v[246:249], v[28:31], v[48:51]
	v_mfma_f32_16x16x32_bf16 v[60:63], v[250:253], v[32:35], v[12:15]
	v_mfma_f32_16x16x32_bf16 v[12:15], v[238:241], v[44:47], v[186:189]
	v_mfma_f32_16x16x32_bf16 v[48:51], v[242:245], v[214:217], v[12:15]
	v_mfma_f32_16x16x32_bf16 v[12:15], v[246:249], v[44:47], v[190:193]
	v_mfma_f32_16x16x32_bf16 v[44:47], v[250:253], v[214:217], v[12:15]
	v_mfma_f32_16x16x32_bf16 v[12:15], v[238:241], v[218:221], v[194:197]
	v_mfma_f32_16x16x32_bf16 v[32:35], v[242:245], v[222:225], v[12:15]
	v_mfma_f32_16x16x32_bf16 v[12:15], v[246:249], v[218:221], v[198:201]
	v_mfma_f32_16x16x32_bf16 v[28:31], v[250:253], v[222:225], v[12:15]
	v_mfma_f32_16x16x32_bf16 v[12:15], v[238:241], v[226:229], v[202:205]
	v_mfma_f32_16x16x32_bf16 v[16:19], v[246:249], v[226:229], v[206:209]
	v_mfma_f32_16x16x32_bf16 v[12:15], v[242:245], v[230:233], v[12:15]
	v_mfma_f32_16x16x32_bf16 v[16:19], v[250:253], v[230:233], v[16:19]
